# v14 plus PEER score loops: the 8 sub-key fragments of the next iteration loaded right after the MFMA chain into own registers
# speedup vs baseline: 1.0461x; 1.0114x over previous
.LBB0_474:
	v_mov_b32_e32 v144, v152
	s_barrier
	s_lshl_b32 s18, s29, 8
	v_and_b32_e32 v163, 31, v144
	v_ashrrev_i32_e32 v164, 1, v144
	v_and_or_b32 v147, v164, s22, v163
	v_add_u32_e32 v150, s18, v147
	v_ashrrev_i32_e32 v151, 31, v150
	v_or_b32_e32 v136, 32, v150
	v_lshlrev_b64 v[128:129], 5, v[150:151]
	v_ashrrev_i32_e32 v137, 31, v136
	v_lshl_add_u64 v[128:129], s[2:3], 0, v[128:129]
	v_lshlrev_b64 v[136:137], 5, v[136:137]
	global_load_dwordx4 v[132:135], v[128:129], off
	s_nop 0
	global_load_dwordx4 v[128:131], v[128:129], off offset:16
	v_lshl_add_u64 v[136:137], s[2:3], 0, v[136:137]
	global_load_dwordx4 v[140:143], v[136:137], off
	s_nop 0
	global_load_dwordx4 v[136:139], v[136:137], off offset:16
	v_or_b32_e32 v166, 64, v150
	v_or_b32_e32 v168, 0x60, v150
	v_ashrrev_i32_e32 v167, 31, v166
	v_ashrrev_i32_e32 v169, 31, v168
	v_lshlrev_b64 v[166:167], 5, v[166:167]
	v_lshlrev_b64 v[168:169], 5, v[168:169]
	v_lshl_add_u64 v[170:171], s[2:3], 0, v[166:167]
	v_lshl_add_u64 v[180:181], s[2:3], 0, v[168:169]
	global_load_dwordx4 v[166:169], v[170:171], off offset:16
	s_nop 0
	global_load_dwordx4 v[170:173], v[170:171], off
	s_nop 0
	global_load_dwordx4 v[174:177], v[180:181], off offset:16
	global_load_dwordx4 v[186:189], v[180:181], off
	v_mov_b64_e32 v[148:149], s[14:15]
	v_bfe_u32 v151, v144, 5, 1
	v_and_b32_e32 v146, 0xc0, v144
	v_lshlrev_b32_e32 v165, 3, v151
	v_lshl_or_b32 v146, v146, 1, v165
	v_mad_u64_u32 v[146:147], s[0:1], v147, s23, v[146:147]
	s_waitcnt vmcnt(7)
	v_mov_b32_e32 v180, v132
	s_waitcnt vmcnt(6)
	v_mov_b32_e32 v181, v128
	v_mov_b32_e32 v128, v133
	v_mov_b32_e32 v132, v134
	v_mov_b32_e32 v133, v130
	v_mov_b32_e32 v130, v135
	v_pk_add_f32 v[128:129], v[180:181], v[128:129]
	v_pk_add_f32 v[130:131], v[132:133], v[130:131]
	s_waitcnt vmcnt(5)
	v_mov_b32_e32 v132, v140
	s_waitcnt vmcnt(4)
	v_mov_b32_e32 v133, v136
	v_mov_b32_e32 v136, v141
	v_mov_b32_e32 v134, v142
	v_mov_b32_e32 v135, v138
	v_mov_b32_e32 v138, v143
	v_pk_add_f32 v[128:129], v[128:129], v[130:131]
	v_pk_add_f32 v[130:131], v[132:133], v[136:137]
	v_pk_add_f32 v[132:133], v[134:135], v[138:139]
	s_nop 0
	v_pk_add_f32 v[130:131], v[130:131], v[132:133]
	v_mov_b32_e32 v133, v128
	v_mov_b32_e32 v132, v130
	v_mov_b32_e32 v128, v131
	v_pk_add_f32 v[128:129], v[132:133], v[128:129]
	s_nop 0
	v_pk_fma_f32 v[128:129], v[128:129], s[12:13], v[148:149] op_sel_hi:[1,0,0]
	s_nop 0
	v_mul_f32_e32 v130, 0x4b800000, v129
	v_cmp_gt_f32_e32 vcc, s24, v129
	v_mul_f32_e32 v131, 0x4b800000, v128
	v_cmp_gt_f32_e64 s[0:1], s24, v128
	v_cndmask_b32_e32 v129, v129, v130, vcc
	v_rsq_f32_e32 v129, v129
	v_cndmask_b32_e64 v128, v128, v131, s[0:1]
	v_rsq_f32_e32 v130, v128
	v_mul_f32_e32 v128, 0x45800000, v129
	v_cndmask_b32_e32 v128, v129, v128, vcc
	v_pk_mul_f32 v[112:113], v[112:113], v[128:129] op_sel_hi:[1,0]
	v_pk_mul_f32 v[114:115], v[114:115], v[128:129] op_sel_hi:[1,0]
	v_pk_mul_f32 v[116:117], v[116:117], v[128:129] op_sel_hi:[1,0]
	v_pk_mul_f32 v[118:119], v[118:119], v[128:129] op_sel_hi:[1,0]
	v_pk_mul_f32 v[96:97], v[96:97], v[128:129] op_sel_hi:[1,0]
	v_pk_mul_f32 v[98:99], v[98:99], v[128:129] op_sel_hi:[1,0]
	v_pk_mul_f32 v[120:121], v[120:121], v[128:129] op_sel_hi:[1,0]
	v_pk_mul_f32 v[122:123], v[122:123], v[128:129] op_sel_hi:[1,0]
	v_pk_mul_f32 v[124:125], v[124:125], v[128:129] op_sel_hi:[1,0]
	v_pk_mul_f32 v[126:127], v[126:127], v[128:129] op_sel_hi:[1,0]
	v_pk_mul_f32 v[100:101], v[100:101], v[128:129] op_sel_hi:[1,0]
	v_pk_mul_f32 v[102:103], v[102:103], v[128:129] op_sel_hi:[1,0]
	v_cvt_pk_bf16_f32 v112, v112, v113
	v_cvt_pk_bf16_f32 v113, v114, v115
	v_cvt_pk_bf16_f32 v114, v116, v117
	v_cvt_pk_bf16_f32 v115, v118, v119
	v_cvt_pk_bf16_f32 v96, v96, v97
	v_cvt_pk_bf16_f32 v97, v98, v99
	v_cvt_pk_bf16_f32 v116, v120, v121
	v_cvt_pk_bf16_f32 v117, v122, v123
	v_cvt_pk_bf16_f32 v118, v124, v125
	v_cvt_pk_bf16_f32 v119, v126, v127
	v_cvt_pk_bf16_f32 v98, v100, v101
	v_cvt_pk_bf16_f32 v99, v102, v103
	ds_write2_b64 v146, v[112:113], v[114:115] offset1:2
	ds_write2_b64 v146, v[116:117], v[118:119] offset0:4 offset1:6
	ds_write2_b64 v146, v[96:97], v[98:99] offset0:8 offset1:10
	v_pk_mul_f32 v[96:97], v[110:111], v[128:129] op_sel_hi:[1,0]
	v_pk_mul_f32 v[104:105], v[104:105], v[128:129] op_sel_hi:[1,0]
	v_cvt_pk_bf16_f32 v103, v96, v97
	v_mul_f32_e32 v96, 0x45800000, v130
	v_cndmask_b32_e64 v96, v130, v96, s[0:1]
	v_pk_mul_f32 v[64:65], v[64:65], v[96:97] op_sel_hi:[1,0]
	v_pk_mul_f32 v[66:67], v[66:67], v[96:97] op_sel_hi:[1,0]
	v_cvt_pk_bf16_f32 v64, v64, v65
	v_cvt_pk_bf16_f32 v65, v66, v67
	v_pk_mul_f32 v[66:67], v[68:69], v[96:97] op_sel_hi:[1,0]
	v_pk_mul_f32 v[68:69], v[70:71], v[96:97] op_sel_hi:[1,0]
	v_pk_mul_f32 v[80:81], v[80:81], v[96:97] op_sel_hi:[1,0]
	v_pk_mul_f32 v[82:83], v[82:83], v[96:97] op_sel_hi:[1,0]
	v_cvt_pk_bf16_f32 v66, v66, v67
	v_cvt_pk_bf16_f32 v67, v68, v69
	s_waitcnt vmcnt(2)
	v_mov_b32_e32 v68, v170
	v_mov_b32_e32 v69, v166
	v_mov_b32_e32 v166, v171
	v_mov_b32_e32 v70, v172
	v_mov_b32_e32 v71, v168
	v_mov_b32_e32 v168, v173
	v_cvt_pk_bf16_f32 v80, v80, v81
	v_cvt_pk_bf16_f32 v81, v82, v83
	v_pk_mul_f32 v[82:83], v[84:85], v[96:97] op_sel_hi:[1,0]
	v_pk_mul_f32 v[84:85], v[86:87], v[96:97] op_sel_hi:[1,0]
	v_add_u32_e32 v86, 0x4000, v146
	v_pk_add_f32 v[68:69], v[68:69], v[166:167]
	v_pk_add_f32 v[70:71], v[70:71], v[168:169]
	ds_write2_b64 v86, v[64:65], v[66:67] offset0:72 offset1:74
	v_pk_mul_f32 v[64:65], v[72:73], v[96:97] op_sel_hi:[1,0]
	v_pk_add_f32 v[68:69], v[68:69], v[70:71]
	s_waitcnt vmcnt(0)
	v_mov_b32_e32 v70, v186
	v_mov_b32_e32 v71, v174
	v_mov_b32_e32 v174, v187
	v_mov_b32_e32 v72, v188
	v_mov_b32_e32 v73, v176
	v_mov_b32_e32 v176, v189
	v_pk_add_f32 v[70:71], v[70:71], v[174:175]
	v_pk_add_f32 v[72:73], v[72:73], v[176:177]
	v_pk_mul_f32 v[66:67], v[74:75], v[96:97] op_sel_hi:[1,0]
	v_pk_add_f32 v[70:71], v[70:71], v[72:73]
	v_mov_b32_e32 v73, v68
	v_mov_b32_e32 v72, v70
	v_mov_b32_e32 v68, v71
	v_pk_add_f32 v[68:69], v[72:73], v[68:69]
	v_cvt_pk_bf16_f32 v64, v64, v65
	v_cvt_pk_bf16_f32 v65, v66, v67
	v_pk_mul_f32 v[66:67], v[76:77], v[96:97] op_sel_hi:[1,0]
	v_pk_fma_f32 v[68:69], v[68:69], s[12:13], v[148:149] op_sel_hi:[1,0,0]
	v_cvt_pk_bf16_f32 v66, v66, v67
	v_mul_f32_e32 v67, 0x4b800000, v69
	v_cmp_gt_f32_e32 vcc, s24, v69
	v_pk_mul_f32 v[70:71], v[78:79], v[96:97] op_sel_hi:[1,0]
	v_cvt_pk_bf16_f32 v82, v82, v83
	v_cndmask_b32_e32 v67, v69, v67, vcc
	v_rsq_f32_e32 v69, v67
	v_cvt_pk_bf16_f32 v67, v70, v71
	ds_write2_b64 v86, v[64:65], v[66:67] offset0:76 offset1:78
	v_cvt_pk_bf16_f32 v83, v84, v85
	v_mul_f32_e32 v64, 0x45800000, v69
	v_cndmask_b32_e32 v64, v69, v64, vcc
	v_pk_mul_f32 v[32:33], v[32:33], v[64:65] op_sel_hi:[1,0]
	v_pk_mul_f32 v[34:35], v[34:35], v[64:65] op_sel_hi:[1,0]
	v_pk_mul_f32 v[48:49], v[48:49], v[64:65] op_sel_hi:[1,0]
	v_pk_mul_f32 v[50:51], v[50:51], v[64:65] op_sel_hi:[1,0]
	v_cvt_pk_bf16_f32 v32, v32, v33
	v_cvt_pk_bf16_f32 v33, v34, v35
	v_pk_mul_f32 v[34:35], v[36:37], v[64:65] op_sel_hi:[1,0]
	v_pk_mul_f32 v[36:37], v[38:39], v[64:65] op_sel_hi:[1,0]
	v_cvt_pk_bf16_f32 v48, v48, v49
	v_cvt_pk_bf16_f32 v49, v50, v51
	v_pk_mul_f32 v[50:51], v[52:53], v[64:65] op_sel_hi:[1,0]
	v_pk_mul_f32 v[52:53], v[54:55], v[64:65] op_sel_hi:[1,0]
	v_add_u32_e32 v54, 0x8000, v146
	v_cvt_pk_bf16_f32 v34, v34, v35
	v_cvt_pk_bf16_f32 v35, v36, v37
	ds_write2_b64 v54, v[32:33], v[34:35] offset0:136 offset1:138
	v_pk_mul_f32 v[32:33], v[40:41], v[64:65] op_sel_hi:[1,0]
	v_pk_mul_f32 v[34:35], v[42:43], v[64:65] op_sel_hi:[1,0]
	v_cvt_pk_bf16_f32 v32, v32, v33
	v_cvt_pk_bf16_f32 v33, v34, v35
	v_pk_mul_f32 v[34:35], v[44:45], v[64:65] op_sel_hi:[1,0]
	v_cmp_gt_f32_e32 vcc, s24, v68
	v_cvt_pk_bf16_f32 v34, v34, v35
	v_mul_f32_e32 v35, 0x4b800000, v68
	v_cndmask_b32_e32 v35, v68, v35, vcc
	v_rsq_f32_e32 v38, v35
	v_pk_mul_f32 v[36:37], v[46:47], v[64:65] op_sel_hi:[1,0]
	v_cvt_pk_bf16_f32 v50, v50, v51
	v_cvt_pk_bf16_f32 v35, v36, v37
	ds_write2_b64 v54, v[32:33], v[34:35] offset0:140 offset1:142
	v_mul_f32_e32 v32, 0x45800000, v38
	v_cndmask_b32_e32 v32, v38, v32, vcc
	v_pk_mul_f32 v[0:1], v[0:1], v[32:33] op_sel_hi:[1,0]
	v_pk_mul_f32 v[2:3], v[2:3], v[32:33] op_sel_hi:[1,0]
	v_pk_mul_f32 v[16:17], v[16:17], v[32:33] op_sel_hi:[1,0]
	v_pk_mul_f32 v[18:19], v[18:19], v[32:33] op_sel_hi:[1,0]
	v_cvt_pk_bf16_f32 v0, v0, v1
	v_cvt_pk_bf16_f32 v1, v2, v3
	v_pk_mul_f32 v[2:3], v[4:5], v[32:33] op_sel_hi:[1,0]
	v_pk_mul_f32 v[4:5], v[6:7], v[32:33] op_sel_hi:[1,0]
	v_cvt_pk_bf16_f32 v16, v16, v17
	v_cvt_pk_bf16_f32 v17, v18, v19
	v_pk_mul_f32 v[18:19], v[20:21], v[32:33] op_sel_hi:[1,0]
	v_pk_mul_f32 v[20:21], v[22:23], v[32:33] op_sel_hi:[1,0]
	v_add_u32_e32 v22, 0xc000, v146
	v_cvt_pk_bf16_f32 v2, v2, v3
	v_cvt_pk_bf16_f32 v3, v4, v5
	ds_write2_b64 v22, v[0:1], v[2:3] offset0:200 offset1:202
	v_pk_mul_f32 v[0:1], v[8:9], v[32:33] op_sel_hi:[1,0]
	v_pk_mul_f32 v[2:3], v[10:11], v[32:33] op_sel_hi:[1,0]
	v_cvt_pk_bf16_f32 v51, v52, v53
	v_cvt_pk_bf16_f32 v18, v18, v19
	v_cvt_pk_bf16_f32 v19, v20, v21
	v_cvt_pk_bf16_f32 v0, v0, v1
	v_cvt_pk_bf16_f32 v1, v2, v3
	v_pk_mul_f32 v[2:3], v[12:13], v[32:33] op_sel_hi:[1,0]
	v_pk_mul_f32 v[4:5], v[14:15], v[32:33] op_sel_hi:[1,0]
	ds_write2_b64 v86, v[80:81], v[82:83] offset0:64 offset1:66
	v_pk_mul_f32 v[80:81], v[88:89], v[96:97] op_sel_hi:[1,0]
	v_pk_mul_f32 v[82:83], v[90:91], v[96:97] op_sel_hi:[1,0]
	ds_write2_b64 v54, v[48:49], v[50:51] offset0:128 offset1:130
	v_pk_mul_f32 v[48:49], v[56:57], v[64:65] op_sel_hi:[1,0]
	v_pk_mul_f32 v[50:51], v[58:59], v[64:65] op_sel_hi:[1,0]
	ds_write2_b64 v22, v[16:17], v[18:19] offset0:192 offset1:194
	v_pk_mul_f32 v[16:17], v[24:25], v[32:33] op_sel_hi:[1,0]
	v_pk_mul_f32 v[18:19], v[26:27], v[32:33] op_sel_hi:[1,0]
	v_cvt_pk_bf16_f32 v2, v2, v3
	v_cvt_pk_bf16_f32 v3, v4, v5
	v_pk_mul_f32 v[106:107], v[106:107], v[128:129] op_sel_hi:[1,0]
	v_pk_mul_f32 v[108:109], v[108:109], v[128:129] op_sel_hi:[1,0]
	v_cvt_pk_bf16_f32 v80, v80, v81
	v_cvt_pk_bf16_f32 v81, v82, v83
	v_pk_mul_f32 v[82:83], v[92:93], v[96:97] op_sel_hi:[1,0]
	v_pk_mul_f32 v[84:85], v[94:95], v[96:97] op_sel_hi:[1,0]
	v_cvt_pk_bf16_f32 v48, v48, v49
	v_cvt_pk_bf16_f32 v49, v50, v51
	v_pk_mul_f32 v[50:51], v[60:61], v[64:65] op_sel_hi:[1,0]
	v_pk_mul_f32 v[52:53], v[62:63], v[64:65] op_sel_hi:[1,0]
	v_cvt_pk_bf16_f32 v16, v16, v17
	v_cvt_pk_bf16_f32 v17, v18, v19
	v_pk_mul_f32 v[18:19], v[28:29], v[32:33] op_sel_hi:[1,0]
	v_pk_mul_f32 v[20:21], v[30:31], v[32:33] op_sel_hi:[1,0]
	ds_write2_b64 v22, v[0:1], v[2:3] offset0:204 offset1:206
	v_bfi_b32 v57, s25, v164, v144
	v_lshlrev_b32_e32 v0, 4, v151
	v_cvt_pk_bf16_f32 v100, v104, v105
	v_cvt_pk_bf16_f32 v101, v106, v107
	v_cvt_pk_bf16_f32 v102, v108, v109
	v_cvt_pk_bf16_f32 v82, v82, v83
	v_cvt_pk_bf16_f32 v83, v84, v85
	v_cvt_pk_bf16_f32 v50, v50, v51
	v_cvt_pk_bf16_f32 v51, v52, v53
	v_cvt_pk_bf16_f32 v18, v18, v19
	v_cvt_pk_bf16_f32 v19, v20, v21
	v_mad_u64_u32 v[52:53], s[0:1], v57, s23, v[0:1]
	ds_write2_b64 v146, v[100:101], v[102:103] offset0:12 offset1:14
	ds_write2_b64 v86, v[80:81], v[82:83] offset0:68 offset1:70
	ds_write2_b64 v54, v[48:49], v[50:51] offset0:132 offset1:134
	ds_write2_b64 v22, v[16:17], v[18:19] offset0:196 offset1:198
	s_waitcnt lgkmcnt(0)
	s_barrier
	ds_read_b128 v[16:19], v52
	ds_read_b128 v[20:23], v52 offset:32
	ds_read_b128 v[24:27], v52 offset:64
	ds_read_b128 v[28:31], v52 offset:96
	ds_read_b128 v[32:35], v52 offset:128
	ds_read_b128 v[36:39], v52 offset:160
	ds_read_b128 v[40:43], v52 offset:192
	ds_read_b128 v[44:47], v52 offset:224
	v_lshl_or_b32 v144, v163, 8, v0
	v_and_b32_e32 v56, 0xffffffe0, v164
	v_lshlrev_b32_e32 v75, 2, v151
	v_lshl_add_u64 v[54:55], s[8:9], 0, v[144:145]
	v_mov_b32_e32 v58, 0xff800000
	s_mov_b32 s0, 0
	v_mov_b32_e32 v59, 0xff800000
	v_mov_b32_e32 v74, 0xff800000
	v_mov_b32_e32 v76, 0xff800000
	v_mov_b32_e32 v77, 0xff800000
	v_mov_b32_e32 v78, 0xff800000
	v_mov_b32_e32 v79, 0xff800000
	v_mov_b32_e32 v80, 0xff800000
	v_mov_b32_e32 v81, 0xff800000
	v_mov_b32_e32 v82, 0xff800000
	v_mov_b32_e32 v83, 0xff800000
	v_mov_b32_e32 v84, 0xff800000
	v_mov_b32_e32 v85, 0xff800000
	v_mov_b32_e32 v86, 0xff800000
	v_mov_b32_e32 v87, 0xff800000
	v_mov_b32_e32 v88, 0xff800000
	global_load_dwordx4 v[196:199], v[54:55], off offset:-128
	global_load_dwordx4 v[200:203], v[54:55], off offset:-96
	global_load_dwordx4 v[204:207], v[54:55], off offset:-64
	global_load_dwordx4 v[208:211], v[54:55], off offset:-32
	global_load_dwordx4 v[212:215], v[54:55], off
	global_load_dwordx4 v[216:219], v[54:55], off offset:32
	global_load_dwordx4 v[220:223], v[54:55], off offset:64
	global_load_dwordx4 v[224:227], v[54:55], off offset:96
	v_lshl_add_u64 v[54:55], v[54:55], 0, s[16:17]
.LBB0_475:
	v_add_u32_e32 v53, s0, v75
	s_add_i32 s0, s0, 32
	s_cmpk_lg_i32 s0, 0x80
	v_max_f32_e32 v60, v88, v88
	s_waitcnt vmcnt(0) lgkmcnt(0)
	v_mfma_f32_32x32x16_bf16 v[0:15], v[196:199], v[16:19], 0
	v_mfma_f32_32x32x16_bf16 v[0:15], v[200:203], v[20:23], v[0:15]
	v_mfma_f32_32x32x16_bf16 v[0:15], v[204:207], v[24:27], v[0:15]
	v_mfma_f32_32x32x16_bf16 v[0:15], v[208:211], v[28:31], v[0:15]
	v_mfma_f32_32x32x16_bf16 v[0:15], v[212:215], v[32:35], v[0:15]
	v_mfma_f32_32x32x16_bf16 v[0:15], v[216:219], v[36:39], v[0:15]
	v_mfma_f32_32x32x16_bf16 v[0:15], v[220:223], v[40:43], v[0:15]
	v_mfma_f32_32x32x16_bf16 v[0:15], v[224:227], v[44:47], v[0:15]
	s_cbranch_scc0 .Lnl_q0a
	global_load_dwordx4 v[196:199], v[54:55], off offset:-128
	global_load_dwordx4 v[200:203], v[54:55], off offset:-96
	global_load_dwordx4 v[204:207], v[54:55], off offset:-64
	global_load_dwordx4 v[208:211], v[54:55], off offset:-32
	global_load_dwordx4 v[212:215], v[54:55], off
	global_load_dwordx4 v[216:219], v[54:55], off offset:32
	global_load_dwordx4 v[220:223], v[54:55], off offset:64
	global_load_dwordx4 v[224:227], v[54:55], off offset:96
	v_lshl_add_u64 v[54:55], v[54:55], 0, s[16:17]
.Lnl_q0a:
	s_nop 11
	v_and_b32_e32 v0, 0xffffff80, v0
	v_and_b32_e32 v1, 0xffffff80, v1
	v_and_b32_e32 v2, 0xffffff80, v2
	v_and_b32_e32 v3, 0xffffff80, v3
	v_and_b32_e32 v4, 0xffffff80, v4
	v_and_b32_e32 v5, 0xffffff80, v5
	v_and_b32_e32 v6, 0xffffff80, v6
	v_and_b32_e32 v7, 0xffffff80, v7
	v_and_b32_e32 v8, 0xffffff80, v8
	v_and_b32_e32 v9, 0xffffff80, v9
	v_and_b32_e32 v10, 0xffffff80, v10
	v_and_b32_e32 v11, 0xffffff80, v11
	v_and_b32_e32 v12, 0xffffff80, v12
	v_and_b32_e32 v13, 0xffffff80, v13
	v_and_b32_e32 v14, 0xffffff80, v14
	v_and_b32_e32 v15, 0xffffff80, v15
	v_add_u32_e32 v0, v53, v0
	v_add3_u32 v1, v53, v1, 1
	v_add3_u32 v2, v53, v2, 2
	v_add3_u32 v3, v53, v3, 3
	v_add3_u32 v4, v53, v4, 8
	v_add3_u32 v5, v53, v5, 9
	v_add3_u32 v6, v53, v6, 10
	v_add3_u32 v7, v53, v7, 11
	v_add3_u32 v8, v53, v8, 16
	v_add3_u32 v9, v53, v9, 17
	v_add3_u32 v10, v53, v10, 18
	v_add3_u32 v11, v53, v11, 19
	v_add3_u32 v12, v53, v12, 24
	v_add3_u32 v13, v53, v13, 25
	v_add3_u32 v14, v53, v14, 26
	v_add3_u32 v15, v53, v15, 27
	v_med3_f32 v48, v58, v59, v0
	v_med3_f32 v49, v74, v58, v0
	v_med3_f32 v50, v76, v74, v0
	v_med3_f32 v51, v77, v76, v0
	v_med3_f32 v53, v78, v77, v0
	v_med3_f32 v58, v79, v78, v0
	v_med3_f32 v59, v80, v79, v0
	v_med3_f32 v61, v81, v80, v0
	v_med3_f32 v62, v82, v81, v0
	v_med3_f32 v63, v83, v82, v0
	v_med3_f32 v64, v84, v83, v0
	v_med3_f32 v65, v85, v84, v0
	v_med3_f32 v66, v86, v85, v0
	v_med3_f32 v67, v87, v86, v0
	v_med3_f32 v68, v88, v87, v0
	v_max_f32_e32 v0, v0, v0
	v_max_f32_e32 v69, v1, v1
	v_max_f32_e32 v0, v60, v0
	v_max_f32_e32 v70, v2, v2
	v_med3_f32 v48, v49, v48, v1
	v_med3_f32 v49, v50, v49, v1
	v_med3_f32 v50, v51, v50, v1
	v_med3_f32 v51, v53, v51, v1
	v_med3_f32 v53, v58, v53, v1
	v_med3_f32 v58, v59, v58, v1
	v_med3_f32 v59, v61, v59, v1
	v_med3_f32 v60, v62, v61, v1
	v_med3_f32 v61, v63, v62, v1
	v_med3_f32 v62, v64, v63, v1
	v_med3_f32 v63, v65, v64, v1
	v_med3_f32 v64, v66, v65, v1
	v_med3_f32 v65, v67, v66, v1
	v_med3_f32 v66, v68, v67, v1
	v_med3_f32 v1, v0, v68, v1
	v_max_f32_e32 v0, v0, v69
	v_max_f32_e32 v71, v3, v3
	v_med3_f32 v48, v49, v48, v2
	v_med3_f32 v49, v50, v49, v2
	v_med3_f32 v50, v51, v50, v2
	v_med3_f32 v51, v53, v51, v2
	v_med3_f32 v53, v58, v53, v2
	v_med3_f32 v58, v59, v58, v2
	v_med3_f32 v59, v60, v59, v2
	v_med3_f32 v60, v61, v60, v2
	v_med3_f32 v61, v62, v61, v2
	v_med3_f32 v62, v63, v62, v2
	v_med3_f32 v63, v64, v63, v2
	v_med3_f32 v64, v65, v64, v2
	v_med3_f32 v65, v66, v65, v2
	v_med3_f32 v66, v1, v66, v2
	v_med3_f32 v1, v0, v1, v2
	v_max_f32_e32 v0, v0, v70
	v_max_f32_e32 v72, v4, v4
	v_med3_f32 v2, v49, v48, v3
	v_med3_f32 v48, v50, v49, v3
	v_med3_f32 v49, v51, v50, v3
	v_med3_f32 v50, v53, v51, v3
	v_med3_f32 v51, v58, v53, v3
	v_med3_f32 v53, v59, v58, v3
	v_med3_f32 v58, v60, v59, v3
	v_med3_f32 v59, v61, v60, v3
	v_med3_f32 v60, v62, v61, v3
	v_med3_f32 v61, v63, v62, v3
	v_med3_f32 v62, v64, v63, v3
	v_med3_f32 v63, v65, v64, v3
	v_med3_f32 v64, v66, v65, v3
	v_med3_f32 v65, v1, v66, v3
	v_med3_f32 v1, v0, v1, v3
	v_max_f32_e32 v0, v0, v71
	v_max_f32_e32 v73, v5, v5
	v_med3_f32 v2, v48, v2, v4
	v_med3_f32 v3, v49, v48, v4
	v_med3_f32 v48, v50, v49, v4
	v_med3_f32 v49, v51, v50, v4
	v_med3_f32 v50, v53, v51, v4
	v_med3_f32 v51, v58, v53, v4
	v_med3_f32 v53, v59, v58, v4
	v_med3_f32 v58, v60, v59, v4
	v_med3_f32 v59, v61, v60, v4
	v_med3_f32 v60, v62, v61, v4
	v_med3_f32 v61, v63, v62, v4
	v_med3_f32 v62, v64, v63, v4
	v_med3_f32 v63, v65, v64, v4
	v_med3_f32 v64, v1, v65, v4
	v_med3_f32 v1, v0, v1, v4
	v_max_f32_e32 v0, v0, v72
	v_max_f32_e32 v74, v6, v6
	v_med3_f32 v2, v3, v2, v5
	v_med3_f32 v3, v48, v3, v5
	v_med3_f32 v4, v49, v48, v5
	v_med3_f32 v48, v50, v49, v5
	v_med3_f32 v49, v51, v50, v5
	v_med3_f32 v50, v53, v51, v5
	v_med3_f32 v51, v58, v53, v5
	v_med3_f32 v53, v59, v58, v5
	v_med3_f32 v58, v60, v59, v5
	v_med3_f32 v59, v61, v60, v5
	v_med3_f32 v60, v62, v61, v5
	v_med3_f32 v61, v63, v62, v5
	v_med3_f32 v62, v64, v63, v5
	v_med3_f32 v63, v1, v64, v5
	v_med3_f32 v1, v0, v1, v5
	v_max_f32_e32 v0, v0, v73
	v_max_f32_e32 v76, v7, v7
	v_med3_f32 v2, v3, v2, v6
	v_med3_f32 v3, v4, v3, v6
	v_med3_f32 v4, v48, v4, v6
	v_med3_f32 v5, v49, v48, v6
	v_med3_f32 v48, v50, v49, v6
	v_med3_f32 v49, v51, v50, v6
	v_med3_f32 v50, v53, v51, v6
	v_med3_f32 v51, v58, v53, v6
	v_med3_f32 v53, v59, v58, v6
	v_med3_f32 v58, v60, v59, v6
	v_med3_f32 v59, v61, v60, v6
	v_med3_f32 v60, v62, v61, v6
	v_med3_f32 v61, v63, v62, v6
	v_med3_f32 v62, v1, v63, v6
	v_med3_f32 v1, v0, v1, v6
	v_max_f32_e32 v0, v0, v74
	v_max_f32_e32 v77, v8, v8
	v_med3_f32 v2, v3, v2, v7
	v_med3_f32 v3, v4, v3, v7
	v_med3_f32 v4, v5, v4, v7
	v_med3_f32 v5, v48, v5, v7
	v_med3_f32 v6, v49, v48, v7
	v_med3_f32 v48, v50, v49, v7
	v_med3_f32 v49, v51, v50, v7
	v_med3_f32 v50, v53, v51, v7
	v_med3_f32 v51, v58, v53, v7
	v_med3_f32 v53, v59, v58, v7
	v_med3_f32 v58, v60, v59, v7
	v_med3_f32 v59, v61, v60, v7
	v_med3_f32 v60, v62, v61, v7
	v_med3_f32 v61, v1, v62, v7
	v_med3_f32 v1, v0, v1, v7
	v_max_f32_e32 v0, v0, v76
	v_max_f32_e32 v78, v9, v9
	v_med3_f32 v2, v3, v2, v8
	v_med3_f32 v3, v4, v3, v8
	v_med3_f32 v4, v5, v4, v8
	v_med3_f32 v5, v6, v5, v8
	v_med3_f32 v6, v48, v6, v8
	v_med3_f32 v7, v49, v48, v8
	v_med3_f32 v48, v50, v49, v8
	v_med3_f32 v49, v51, v50, v8
	v_med3_f32 v50, v53, v51, v8
	v_med3_f32 v51, v58, v53, v8
	v_med3_f32 v53, v59, v58, v8
	v_med3_f32 v58, v60, v59, v8
	v_med3_f32 v59, v61, v60, v8
	v_med3_f32 v60, v1, v61, v8
	v_med3_f32 v1, v0, v1, v8
	v_max_f32_e32 v0, v0, v77
	v_max_f32_e32 v79, v10, v10
	v_med3_f32 v2, v3, v2, v9
	v_med3_f32 v3, v4, v3, v9
	v_med3_f32 v4, v5, v4, v9
	v_med3_f32 v5, v6, v5, v9
	v_med3_f32 v6, v7, v6, v9
	v_med3_f32 v7, v48, v7, v9
	v_med3_f32 v8, v49, v48, v9
	v_med3_f32 v48, v50, v49, v9
	v_med3_f32 v49, v51, v50, v9
	v_med3_f32 v50, v53, v51, v9
	v_med3_f32 v51, v58, v53, v9
	v_med3_f32 v53, v59, v58, v9
	v_med3_f32 v58, v60, v59, v9
	v_med3_f32 v59, v1, v60, v9
	v_med3_f32 v1, v0, v1, v9
	v_max_f32_e32 v0, v0, v78
	v_max_f32_e32 v80, v11, v11
	v_med3_f32 v2, v3, v2, v10
	v_med3_f32 v3, v4, v3, v10
	v_med3_f32 v4, v5, v4, v10
	v_med3_f32 v5, v6, v5, v10
	v_med3_f32 v6, v7, v6, v10
	v_med3_f32 v7, v8, v7, v10
	v_med3_f32 v8, v48, v8, v10
	v_med3_f32 v9, v49, v48, v10
	v_med3_f32 v48, v50, v49, v10
	v_med3_f32 v49, v51, v50, v10
	v_med3_f32 v50, v53, v51, v10
	v_med3_f32 v51, v58, v53, v10
	v_med3_f32 v53, v59, v58, v10
	v_med3_f32 v58, v1, v59, v10
	v_med3_f32 v1, v0, v1, v10
	v_max_f32_e32 v0, v0, v79
	v_max_f32_e32 v81, v12, v12
	v_med3_f32 v2, v3, v2, v11
	v_med3_f32 v3, v4, v3, v11
	v_med3_f32 v4, v5, v4, v11
	v_med3_f32 v5, v6, v5, v11
	v_med3_f32 v6, v7, v6, v11
	v_med3_f32 v7, v8, v7, v11
	v_med3_f32 v8, v9, v8, v11
	v_med3_f32 v9, v48, v9, v11
	v_med3_f32 v10, v49, v48, v11
	v_med3_f32 v48, v50, v49, v11
	v_med3_f32 v49, v51, v50, v11
	v_med3_f32 v50, v53, v51, v11
	v_med3_f32 v51, v58, v53, v11
	v_med3_f32 v53, v1, v58, v11
	v_med3_f32 v1, v0, v1, v11
	v_max_f32_e32 v0, v0, v80
	v_max_f32_e32 v82, v13, v13
	v_med3_f32 v2, v3, v2, v12
	v_med3_f32 v3, v4, v3, v12
	v_med3_f32 v4, v5, v4, v12
	v_med3_f32 v5, v6, v5, v12
	v_med3_f32 v6, v7, v6, v12
	v_med3_f32 v7, v8, v7, v12
	v_med3_f32 v8, v9, v8, v12
	v_med3_f32 v9, v10, v9, v12
	v_med3_f32 v10, v48, v10, v12
	v_med3_f32 v11, v49, v48, v12
	v_med3_f32 v48, v50, v49, v12
	v_med3_f32 v49, v51, v50, v12
	v_med3_f32 v50, v53, v51, v12
	v_med3_f32 v51, v1, v53, v12
	v_med3_f32 v1, v0, v1, v12
	v_max_f32_e32 v0, v0, v81
	v_max_f32_e32 v83, v14, v14
	v_med3_f32 v2, v3, v2, v13
	v_med3_f32 v3, v4, v3, v13
	v_med3_f32 v4, v5, v4, v13
	v_med3_f32 v5, v6, v5, v13
	v_med3_f32 v6, v7, v6, v13
	v_med3_f32 v7, v8, v7, v13
	v_med3_f32 v8, v9, v8, v13
	v_med3_f32 v9, v10, v9, v13
	v_med3_f32 v10, v11, v10, v13
	v_med3_f32 v11, v48, v11, v13
	v_med3_f32 v12, v49, v48, v13
	v_med3_f32 v48, v50, v49, v13
	v_med3_f32 v49, v51, v50, v13
	v_med3_f32 v50, v1, v51, v13
	v_med3_f32 v1, v0, v1, v13
	v_max_f32_e32 v0, v0, v82
	v_max_f32_e32 v88, v15, v15
	v_med3_f32 v2, v3, v2, v14
	v_med3_f32 v3, v4, v3, v14
	v_med3_f32 v4, v5, v4, v14
	v_med3_f32 v5, v6, v5, v14
	v_med3_f32 v6, v7, v6, v14
	v_med3_f32 v7, v8, v7, v14
	v_med3_f32 v8, v9, v8, v14
	v_med3_f32 v9, v10, v9, v14
	v_med3_f32 v10, v11, v10, v14
	v_med3_f32 v11, v12, v11, v14
	v_med3_f32 v12, v48, v12, v14
	v_med3_f32 v13, v49, v48, v14
	v_med3_f32 v48, v50, v49, v14
	v_med3_f32 v49, v1, v50, v14
	v_med3_f32 v1, v0, v1, v14
	v_max_f32_e32 v0, v0, v83
	v_med3_f32 v59, v3, v2, v15
	v_med3_f32 v58, v4, v3, v15
	v_med3_f32 v74, v5, v4, v15
	v_med3_f32 v76, v6, v5, v15
	v_med3_f32 v77, v7, v6, v15
	v_med3_f32 v78, v8, v7, v15
	v_med3_f32 v79, v9, v8, v15
	v_med3_f32 v80, v10, v9, v15
	v_med3_f32 v81, v11, v10, v15
	v_med3_f32 v82, v12, v11, v15
	v_med3_f32 v83, v13, v12, v15
	v_med3_f32 v84, v48, v13, v15
	v_med3_f32 v85, v49, v48, v15
	v_med3_f32 v86, v1, v49, v15
	v_med3_f32 v87, v0, v1, v15
	v_max_f32_e32 v88, v0, v88
	s_cbranch_scc1 .LBB0_475
	ds_read_b128 v[16:19], v52 offset:256
	ds_read_b128 v[20:23], v52 offset:288
	ds_read_b128 v[24:27], v52 offset:320
	ds_read_b128 v[28:31], v52 offset:352
	ds_read_b128 v[32:35], v52 offset:384
	ds_read_b128 v[36:39], v52 offset:416
	ds_read_b128 v[40:43], v52 offset:448
	ds_read_b128 v[44:47], v52 offset:480
	ds_bpermute_b32 v54, v161, v88
	ds_bpermute_b32 v55, v161, v87
	ds_bpermute_b32 v60, v161, v86
	ds_bpermute_b32 v61, v161, v85
	ds_bpermute_b32 v62, v161, v84
	ds_bpermute_b32 v63, v161, v83
	ds_bpermute_b32 v64, v161, v82
	ds_bpermute_b32 v65, v161, v81
	ds_bpermute_b32 v66, v161, v80
	ds_bpermute_b32 v67, v161, v79
	ds_bpermute_b32 v68, v161, v78
	ds_bpermute_b32 v69, v161, v77
	ds_bpermute_b32 v70, v161, v76
	ds_bpermute_b32 v71, v161, v74
	ds_bpermute_b32 v72, v161, v58
	ds_bpermute_b32 v73, v161, v59
	v_lshl_add_u64 v[52:53], s[10:11], 0, v[144:145]
	v_mov_b32_e32 v89, 0xff800000
	s_mov_b32 s0, 0
	v_mov_b32_e32 v90, 0xff800000
	v_mov_b32_e32 v91, 0xff800000
	v_mov_b32_e32 v92, 0xff800000
	v_mov_b32_e32 v93, 0xff800000
	v_mov_b32_e32 v94, 0xff800000
	v_mov_b32_e32 v95, 0xff800000
	v_mov_b32_e32 v96, 0xff800000
	v_mov_b32_e32 v97, 0xff800000
	v_mov_b32_e32 v98, 0xff800000
	v_mov_b32_e32 v99, 0xff800000
	v_mov_b32_e32 v100, 0xff800000
	v_mov_b32_e32 v101, 0xff800000
	v_mov_b32_e32 v102, 0xff800000
	v_mov_b32_e32 v103, 0xff800000
	v_mov_b32_e32 v104, 0xff800000
	global_load_dwordx4 v[196:199], v[52:53], off offset:-128
	global_load_dwordx4 v[200:203], v[52:53], off offset:-96
	global_load_dwordx4 v[204:207], v[52:53], off offset:-64
	global_load_dwordx4 v[208:211], v[52:53], off offset:-32
	global_load_dwordx4 v[212:215], v[52:53], off
	global_load_dwordx4 v[216:219], v[52:53], off offset:32
	global_load_dwordx4 v[220:223], v[52:53], off offset:64
	global_load_dwordx4 v[224:227], v[52:53], off offset:96
	v_lshl_add_u64 v[52:53], v[52:53], 0, s[16:17]
.LBB0_477:
	v_add_u32_e32 v105, s0, v75
	s_add_i32 s0, s0, 32
	s_cmpk_lg_i32 s0, 0x80
	v_max_f32_e32 v106, v104, v104
	s_waitcnt vmcnt(0) lgkmcnt(14)
	v_mfma_f32_32x32x16_bf16 v[0:15], v[196:199], v[16:19], 0
	v_mfma_f32_32x32x16_bf16 v[0:15], v[200:203], v[20:23], v[0:15]
	v_mfma_f32_32x32x16_bf16 v[0:15], v[204:207], v[24:27], v[0:15]
	v_mfma_f32_32x32x16_bf16 v[0:15], v[208:211], v[28:31], v[0:15]
	v_mfma_f32_32x32x16_bf16 v[0:15], v[212:215], v[32:35], v[0:15]
	v_mfma_f32_32x32x16_bf16 v[0:15], v[216:219], v[36:39], v[0:15]
	v_mfma_f32_32x32x16_bf16 v[0:15], v[220:223], v[40:43], v[0:15]
	v_mfma_f32_32x32x16_bf16 v[0:15], v[224:227], v[44:47], v[0:15]
	s_cbranch_scc0 .Lnl_q0b
	global_load_dwordx4 v[196:199], v[52:53], off offset:-128
	global_load_dwordx4 v[200:203], v[52:53], off offset:-96
	global_load_dwordx4 v[204:207], v[52:53], off offset:-64
	global_load_dwordx4 v[208:211], v[52:53], off offset:-32
	global_load_dwordx4 v[212:215], v[52:53], off
	global_load_dwordx4 v[216:219], v[52:53], off offset:32
	global_load_dwordx4 v[220:223], v[52:53], off offset:64
	global_load_dwordx4 v[224:227], v[52:53], off offset:96
	v_lshl_add_u64 v[52:53], v[52:53], 0, s[16:17]
.Lnl_q0b:
	s_nop 11
	v_and_b32_e32 v0, 0xffffff80, v0
	v_and_b32_e32 v1, 0xffffff80, v1
	v_add_u32_e32 v0, v105, v0
	v_and_b32_e32 v2, 0xffffff80, v2
	v_add3_u32 v1, v105, v1, 1
	v_med3_f32 v48, v89, v90, v0
	v_med3_f32 v49, v91, v89, v0
	v_med3_f32 v50, v92, v91, v0
	v_med3_f32 v51, v93, v92, v0
	v_med3_f32 v89, v94, v93, v0
	v_med3_f32 v90, v95, v94, v0
	v_med3_f32 v91, v96, v95, v0
	v_med3_f32 v92, v97, v96, v0
	v_med3_f32 v93, v98, v97, v0
	v_med3_f32 v94, v99, v98, v0
	v_med3_f32 v95, v100, v99, v0
	v_med3_f32 v96, v101, v100, v0
	v_med3_f32 v97, v102, v101, v0
	v_med3_f32 v98, v103, v102, v0
	v_med3_f32 v99, v104, v103, v0
	v_max_f32_e32 v0, v0, v0
	v_and_b32_e32 v3, 0xffffff80, v3
	v_add3_u32 v2, v105, v2, 2
	v_max_f32_e32 v100, v1, v1
	v_max_f32_e32 v0, v106, v0
	v_and_b32_e32 v4, 0xffffff80, v4
	v_add3_u32 v3, v105, v3, 3
	v_max_f32_e32 v101, v2, v2
	v_med3_f32 v48, v49, v48, v1
	v_med3_f32 v49, v50, v49, v1
	v_med3_f32 v50, v51, v50, v1
	v_med3_f32 v51, v89, v51, v1
	v_med3_f32 v89, v90, v89, v1
	v_med3_f32 v90, v91, v90, v1
	v_med3_f32 v91, v92, v91, v1
	v_med3_f32 v92, v93, v92, v1
	v_med3_f32 v93, v94, v93, v1
	v_med3_f32 v94, v95, v94, v1
	v_med3_f32 v95, v96, v95, v1
	v_med3_f32 v96, v97, v96, v1
	v_med3_f32 v97, v98, v97, v1
	v_med3_f32 v98, v99, v98, v1
	v_med3_f32 v1, v0, v99, v1
	v_max_f32_e32 v0, v0, v100
	v_and_b32_e32 v5, 0xffffff80, v5
	v_add3_u32 v4, v105, v4, 8
	v_max_f32_e32 v102, v3, v3
	v_med3_f32 v48, v49, v48, v2
	v_med3_f32 v49, v50, v49, v2
	v_med3_f32 v50, v51, v50, v2
	v_med3_f32 v51, v89, v51, v2
	v_med3_f32 v89, v90, v89, v2
	v_med3_f32 v90, v91, v90, v2
	v_med3_f32 v91, v92, v91, v2
	v_med3_f32 v92, v93, v92, v2
	v_med3_f32 v93, v94, v93, v2
	v_med3_f32 v94, v95, v94, v2
	v_med3_f32 v95, v96, v95, v2
	v_med3_f32 v96, v97, v96, v2
	v_med3_f32 v97, v98, v97, v2
	v_med3_f32 v98, v1, v98, v2
	v_med3_f32 v1, v0, v1, v2
	v_max_f32_e32 v0, v0, v101
	v_and_b32_e32 v6, 0xffffff80, v6
	v_add3_u32 v5, v105, v5, 9
	v_max_f32_e32 v103, v4, v4
	v_med3_f32 v2, v49, v48, v3
	v_med3_f32 v48, v50, v49, v3
	v_med3_f32 v49, v51, v50, v3
	v_med3_f32 v50, v89, v51, v3
	v_med3_f32 v51, v90, v89, v3
	v_med3_f32 v89, v91, v90, v3
	v_med3_f32 v90, v92, v91, v3
	v_med3_f32 v91, v93, v92, v3
	v_med3_f32 v92, v94, v93, v3
	v_med3_f32 v93, v95, v94, v3
	v_med3_f32 v94, v96, v95, v3
	v_med3_f32 v95, v97, v96, v3
	v_med3_f32 v96, v98, v97, v3
	v_med3_f32 v97, v1, v98, v3
	v_med3_f32 v1, v0, v1, v3
	v_max_f32_e32 v0, v0, v102
	v_and_b32_e32 v7, 0xffffff80, v7
	v_and_b32_e32 v8, 0xffffff80, v8
	v_and_b32_e32 v9, 0xffffff80, v9
	v_and_b32_e32 v10, 0xffffff80, v10
	v_and_b32_e32 v11, 0xffffff80, v11
	v_and_b32_e32 v12, 0xffffff80, v12
	v_and_b32_e32 v13, 0xffffff80, v13
	v_and_b32_e32 v14, 0xffffff80, v14
	v_and_b32_e32 v15, 0xffffff80, v15
	v_add3_u32 v6, v105, v6, 10
	v_max_f32_e32 v104, v5, v5
	v_med3_f32 v2, v48, v2, v4
	v_med3_f32 v3, v49, v48, v4
	v_med3_f32 v48, v50, v49, v4
	v_med3_f32 v49, v51, v50, v4
	v_med3_f32 v50, v89, v51, v4
	v_med3_f32 v51, v90, v89, v4
	v_med3_f32 v89, v91, v90, v4
	v_med3_f32 v90, v92, v91, v4
	v_med3_f32 v91, v93, v92, v4
	v_med3_f32 v92, v94, v93, v4
	v_med3_f32 v93, v95, v94, v4
	v_med3_f32 v94, v96, v95, v4
	v_med3_f32 v95, v97, v96, v4
	v_med3_f32 v96, v1, v97, v4
	v_med3_f32 v1, v0, v1, v4
	v_max_f32_e32 v0, v0, v103
	v_add3_u32 v7, v105, v7, 11
	v_add3_u32 v8, v105, v8, 16
	v_add3_u32 v9, v105, v9, 17
	v_add3_u32 v10, v105, v10, 18
	v_add3_u32 v11, v105, v11, 19
	v_add3_u32 v12, v105, v12, 24
	v_add3_u32 v13, v105, v13, 25
	v_add3_u32 v14, v105, v14, 26
	v_add3_u32 v15, v105, v15, 27
	v_max_f32_e32 v105, v6, v6
	v_med3_f32 v2, v3, v2, v5
	v_med3_f32 v3, v48, v3, v5
	v_med3_f32 v4, v49, v48, v5
	v_med3_f32 v48, v50, v49, v5
	v_med3_f32 v49, v51, v50, v5
	v_med3_f32 v50, v89, v51, v5
	v_med3_f32 v51, v90, v89, v5
	v_med3_f32 v89, v91, v90, v5
	v_med3_f32 v90, v92, v91, v5
	v_med3_f32 v91, v93, v92, v5
	v_med3_f32 v92, v94, v93, v5
	v_med3_f32 v93, v95, v94, v5
	v_med3_f32 v94, v96, v95, v5
	v_med3_f32 v95, v1, v96, v5
	v_med3_f32 v1, v0, v1, v5
	v_max_f32_e32 v0, v0, v104
	v_max_f32_e32 v107, v7, v7
	v_med3_f32 v2, v3, v2, v6
	v_med3_f32 v3, v4, v3, v6
	v_med3_f32 v4, v48, v4, v6
	v_med3_f32 v5, v49, v48, v6
	v_med3_f32 v48, v50, v49, v6
	v_med3_f32 v49, v51, v50, v6
	v_med3_f32 v50, v89, v51, v6
	v_med3_f32 v51, v90, v89, v6
	v_med3_f32 v89, v91, v90, v6
	v_med3_f32 v90, v92, v91, v6
	v_med3_f32 v91, v93, v92, v6
	v_med3_f32 v92, v94, v93, v6
	v_med3_f32 v93, v95, v94, v6
	v_med3_f32 v94, v1, v95, v6
	v_med3_f32 v1, v0, v1, v6
	v_max_f32_e32 v0, v0, v105
	v_max_f32_e32 v108, v8, v8
	v_med3_f32 v2, v3, v2, v7
	v_med3_f32 v3, v4, v3, v7
	v_med3_f32 v4, v5, v4, v7
	v_med3_f32 v5, v48, v5, v7
	v_med3_f32 v6, v49, v48, v7
	v_med3_f32 v48, v50, v49, v7
	v_med3_f32 v49, v51, v50, v7
	v_med3_f32 v50, v89, v51, v7
	v_med3_f32 v51, v90, v89, v7
	v_med3_f32 v89, v91, v90, v7
	v_med3_f32 v90, v92, v91, v7
	v_med3_f32 v91, v93, v92, v7
	v_med3_f32 v92, v94, v93, v7
	v_med3_f32 v93, v1, v94, v7
	v_med3_f32 v1, v0, v1, v7
	v_max_f32_e32 v0, v0, v107
	v_max_f32_e32 v109, v9, v9
	v_med3_f32 v2, v3, v2, v8
	v_med3_f32 v3, v4, v3, v8
	v_med3_f32 v4, v5, v4, v8
	v_med3_f32 v5, v6, v5, v8
	v_med3_f32 v6, v48, v6, v8
	v_med3_f32 v7, v49, v48, v8
	v_med3_f32 v48, v50, v49, v8
	v_med3_f32 v49, v51, v50, v8
	v_med3_f32 v50, v89, v51, v8
	v_med3_f32 v51, v90, v89, v8
	v_med3_f32 v89, v91, v90, v8
	v_med3_f32 v90, v92, v91, v8
	v_med3_f32 v91, v93, v92, v8
	v_med3_f32 v92, v1, v93, v8
	v_med3_f32 v1, v0, v1, v8
	v_max_f32_e32 v0, v0, v108
	v_max_f32_e32 v110, v10, v10
	v_med3_f32 v2, v3, v2, v9
	v_med3_f32 v3, v4, v3, v9
	v_med3_f32 v4, v5, v4, v9
	v_med3_f32 v5, v6, v5, v9
	v_med3_f32 v6, v7, v6, v9
	v_med3_f32 v7, v48, v7, v9
	v_med3_f32 v8, v49, v48, v9
	v_med3_f32 v48, v50, v49, v9
	v_med3_f32 v49, v51, v50, v9
	v_med3_f32 v50, v89, v51, v9
	v_med3_f32 v51, v90, v89, v9
	v_med3_f32 v89, v91, v90, v9
	v_med3_f32 v90, v92, v91, v9
	v_med3_f32 v91, v1, v92, v9
	v_med3_f32 v1, v0, v1, v9
	v_max_f32_e32 v0, v0, v109
	v_max_f32_e32 v111, v11, v11
	v_med3_f32 v2, v3, v2, v10
	v_med3_f32 v3, v4, v3, v10
	v_med3_f32 v4, v5, v4, v10
	v_med3_f32 v5, v6, v5, v10
	v_med3_f32 v6, v7, v6, v10
	v_med3_f32 v7, v8, v7, v10
	v_med3_f32 v8, v48, v8, v10
	v_med3_f32 v9, v49, v48, v10
	v_med3_f32 v48, v50, v49, v10
	v_med3_f32 v49, v51, v50, v10
	v_med3_f32 v50, v89, v51, v10
	v_med3_f32 v51, v90, v89, v10
	v_med3_f32 v89, v91, v90, v10
	v_med3_f32 v90, v1, v91, v10
	v_med3_f32 v1, v0, v1, v10
	v_max_f32_e32 v0, v0, v110
	v_max_f32_e32 v112, v12, v12
	v_med3_f32 v2, v3, v2, v11
	v_med3_f32 v3, v4, v3, v11
	v_med3_f32 v4, v5, v4, v11
	v_med3_f32 v5, v6, v5, v11
	v_med3_f32 v6, v7, v6, v11
	v_med3_f32 v7, v8, v7, v11
	v_med3_f32 v8, v9, v8, v11
	v_med3_f32 v9, v48, v9, v11
	v_med3_f32 v10, v49, v48, v11
	v_med3_f32 v48, v50, v49, v11
	v_med3_f32 v49, v51, v50, v11
	v_med3_f32 v50, v89, v51, v11
	v_med3_f32 v51, v90, v89, v11
	v_med3_f32 v89, v1, v90, v11
	v_med3_f32 v1, v0, v1, v11
	v_max_f32_e32 v0, v0, v111
	v_max_f32_e32 v113, v13, v13
	v_med3_f32 v2, v3, v2, v12
	v_med3_f32 v3, v4, v3, v12
	v_med3_f32 v4, v5, v4, v12
	v_med3_f32 v5, v6, v5, v12
	v_med3_f32 v6, v7, v6, v12
	v_med3_f32 v7, v8, v7, v12
	v_med3_f32 v8, v9, v8, v12
	v_med3_f32 v9, v10, v9, v12
	v_med3_f32 v10, v48, v10, v12
	v_med3_f32 v11, v49, v48, v12
	v_med3_f32 v48, v50, v49, v12
	v_med3_f32 v49, v51, v50, v12
	v_med3_f32 v50, v89, v51, v12
	v_med3_f32 v51, v1, v89, v12
	v_med3_f32 v1, v0, v1, v12
	v_max_f32_e32 v0, v0, v112
	v_max_f32_e32 v114, v14, v14
	v_med3_f32 v2, v3, v2, v13
	v_med3_f32 v3, v4, v3, v13
	v_med3_f32 v4, v5, v4, v13
	v_med3_f32 v5, v6, v5, v13
	v_med3_f32 v6, v7, v6, v13
	v_med3_f32 v7, v8, v7, v13
	v_med3_f32 v8, v9, v8, v13
	v_med3_f32 v9, v10, v9, v13
	v_med3_f32 v10, v11, v10, v13
	v_med3_f32 v11, v48, v11, v13
	v_med3_f32 v12, v49, v48, v13
	v_med3_f32 v48, v50, v49, v13
	v_med3_f32 v49, v51, v50, v13
	v_med3_f32 v50, v1, v51, v13
	v_med3_f32 v1, v0, v1, v13
	v_max_f32_e32 v0, v0, v113
	v_max_f32_e32 v115, v15, v15
	v_med3_f32 v2, v3, v2, v14
	v_med3_f32 v3, v4, v3, v14
	v_med3_f32 v4, v5, v4, v14
	v_med3_f32 v5, v6, v5, v14
	v_med3_f32 v6, v7, v6, v14
	v_med3_f32 v7, v8, v7, v14
	v_med3_f32 v8, v9, v8, v14
	v_med3_f32 v9, v10, v9, v14
	v_med3_f32 v10, v11, v10, v14
	v_med3_f32 v11, v12, v11, v14
	v_med3_f32 v12, v48, v12, v14
	v_med3_f32 v13, v49, v48, v14
	v_med3_f32 v48, v50, v49, v14
	v_med3_f32 v49, v1, v50, v14
	v_med3_f32 v1, v0, v1, v14
	v_max_f32_e32 v0, v0, v114
	v_med3_f32 v90, v3, v2, v15
	v_med3_f32 v89, v4, v3, v15
	v_med3_f32 v91, v5, v4, v15
	v_med3_f32 v92, v6, v5, v15
	v_med3_f32 v93, v7, v6, v15
	v_med3_f32 v94, v8, v7, v15
	v_med3_f32 v95, v9, v8, v15
	v_med3_f32 v96, v10, v9, v15
	v_med3_f32 v97, v11, v10, v15
	v_med3_f32 v98, v12, v11, v15
	v_med3_f32 v99, v13, v12, v15
	v_med3_f32 v100, v48, v13, v15
	v_med3_f32 v101, v49, v48, v15
	v_med3_f32 v102, v1, v49, v15
	v_med3_f32 v103, v0, v1, v15
	v_max_f32_e32 v104, v0, v115
	s_cbranch_scc1 .LBB0_477
	ds_bpermute_b32 v0, v161, v104
	ds_bpermute_b32 v1, v161, v103
	ds_bpermute_b32 v2, v161, v102
	ds_bpermute_b32 v3, v161, v101
	ds_bpermute_b32 v4, v161, v100
	ds_bpermute_b32 v5, v161, v99
	ds_bpermute_b32 v7, v161, v98
	ds_bpermute_b32 v8, v161, v97
	ds_bpermute_b32 v9, v161, v96
	ds_bpermute_b32 v10, v161, v95
	ds_bpermute_b32 v11, v161, v94
	ds_bpermute_b32 v12, v161, v93
	ds_bpermute_b32 v14, v161, v92
	ds_bpermute_b32 v15, v161, v91
	ds_bpermute_b32 v16, v161, v89
	ds_bpermute_b32 v47, v161, v90
	v_cmp_eq_u32_e32 vcc, 0, v151
	s_and_saveexec_b64 s[0:1], vcc
	s_cbranch_execz .LBB0_467
	v_max_f32_e32 v28, v54, v54
	v_max_f32_e32 v29, v88, v88
	v_med3_f32 v6, v76, v74, v54
	v_med3_f32 v13, v77, v76, v54
	v_med3_f32 v17, v78, v77, v54
	v_med3_f32 v18, v79, v78, v54
	v_med3_f32 v19, v80, v79, v54
	v_med3_f32 v20, v81, v80, v54
	v_med3_f32 v21, v82, v81, v54
	v_med3_f32 v22, v83, v82, v54
	v_med3_f32 v23, v84, v83, v54
	v_med3_f32 v24, v85, v84, v54
	v_med3_f32 v25, v86, v85, v54
	v_med3_f32 v26, v87, v86, v54
	v_med3_f32 v27, v88, v87, v54
	v_max_f32_e32 v28, v29, v28
	v_max_f32_e32 v29, v55, v55
	v_med3_f32 v32, v13, v6, v55
	v_med3_f32 v13, v17, v13, v55
	v_med3_f32 v17, v18, v17, v55
	v_med3_f32 v18, v19, v18, v55
	v_med3_f32 v19, v20, v19, v55
	v_med3_f32 v20, v21, v20, v55
	v_med3_f32 v21, v22, v21, v55
	v_med3_f32 v22, v23, v22, v55
	v_med3_f32 v23, v24, v23, v55
	v_med3_f32 v24, v25, v24, v55
	v_med3_f32 v25, v26, v25, v55
	v_med3_f32 v26, v27, v26, v55
	v_med3_f32 v27, v28, v27, v55
	v_max_f32_e32 v28, v28, v29
	s_waitcnt lgkmcnt(14)
	v_max_f32_e32 v29, v60, v60
	v_med3_f32 v33, v13, v32, v60
	v_med3_f32 v13, v17, v13, v60
	v_med3_f32 v17, v18, v17, v60
	v_med3_f32 v18, v19, v18, v60
	v_med3_f32 v19, v20, v19, v60
	v_med3_f32 v20, v21, v20, v60
	v_med3_f32 v21, v22, v21, v60
	v_med3_f32 v22, v23, v22, v60
	v_med3_f32 v23, v24, v23, v60
	v_med3_f32 v24, v25, v24, v60
	v_med3_f32 v25, v26, v25, v60
	v_med3_f32 v26, v27, v26, v60
	v_med3_f32 v27, v28, v27, v60
	v_max_f32_e32 v28, v28, v29
	v_max_f32_e32 v29, v61, v61
	v_med3_f32 v34, v13, v33, v61
	v_med3_f32 v13, v17, v13, v61
	v_med3_f32 v17, v18, v17, v61
	v_med3_f32 v18, v19, v18, v61
	v_med3_f32 v19, v20, v19, v61
	v_med3_f32 v20, v21, v20, v61
	v_med3_f32 v21, v22, v21, v61
	v_med3_f32 v22, v23, v22, v61
	v_med3_f32 v23, v24, v23, v61
	v_med3_f32 v24, v25, v24, v61
	v_med3_f32 v25, v26, v25, v61
	v_med3_f32 v26, v27, v26, v61
	v_med3_f32 v27, v28, v27, v61
	v_max_f32_e32 v28, v28, v29
	v_max_f32_e32 v29, v62, v62
	v_med3_f32 v35, v13, v34, v62
	v_med3_f32 v13, v17, v13, v62
	v_med3_f32 v17, v18, v17, v62
	v_med3_f32 v18, v19, v18, v62
	v_med3_f32 v19, v20, v19, v62
	v_med3_f32 v20, v21, v20, v62
	v_med3_f32 v21, v22, v21, v62
	v_med3_f32 v22, v23, v22, v62
	v_med3_f32 v23, v24, v23, v62
	v_med3_f32 v24, v25, v24, v62
	v_med3_f32 v25, v26, v25, v62
	v_med3_f32 v26, v27, v26, v62
	v_med3_f32 v27, v28, v27, v62
	v_max_f32_e32 v28, v28, v29
	v_max_f32_e32 v29, v63, v63
	v_med3_f32 v36, v13, v35, v63
	v_med3_f32 v13, v17, v13, v63
	v_med3_f32 v17, v18, v17, v63
	v_med3_f32 v18, v19, v18, v63
	v_med3_f32 v19, v20, v19, v63
	v_med3_f32 v20, v21, v20, v63
	v_med3_f32 v21, v22, v21, v63
	v_med3_f32 v22, v23, v22, v63
	v_med3_f32 v23, v24, v23, v63
	v_med3_f32 v24, v25, v24, v63
	v_med3_f32 v25, v26, v25, v63
	v_med3_f32 v26, v27, v26, v63
	v_med3_f32 v27, v28, v27, v63
	v_max_f32_e32 v28, v28, v29
	v_max_f32_e32 v29, v64, v64
	v_med3_f32 v37, v13, v36, v64
	v_med3_f32 v13, v17, v13, v64
	v_med3_f32 v17, v18, v17, v64
	v_med3_f32 v18, v19, v18, v64
	v_med3_f32 v19, v20, v19, v64
	v_med3_f32 v20, v21, v20, v64
	v_med3_f32 v21, v22, v21, v64
	v_med3_f32 v22, v23, v22, v64
	v_med3_f32 v23, v24, v23, v64
	v_med3_f32 v24, v25, v24, v64
	v_med3_f32 v25, v26, v25, v64
	v_med3_f32 v26, v27, v26, v64
	v_med3_f32 v27, v28, v27, v64
	v_max_f32_e32 v28, v28, v29
	v_max_f32_e32 v29, v65, v65
	v_med3_f32 v38, v13, v37, v65
	v_med3_f32 v13, v17, v13, v65
	v_med3_f32 v17, v18, v17, v65
	v_med3_f32 v18, v19, v18, v65
	v_med3_f32 v19, v20, v19, v65
	v_med3_f32 v20, v21, v20, v65
	v_med3_f32 v21, v22, v21, v65
	v_med3_f32 v22, v23, v22, v65
	v_med3_f32 v23, v24, v23, v65
	v_med3_f32 v24, v25, v24, v65
	v_med3_f32 v25, v26, v25, v65
	v_med3_f32 v26, v27, v26, v65
	v_med3_f32 v27, v28, v27, v65
	v_max_f32_e32 v28, v28, v29
	v_max_f32_e32 v29, v66, v66
	v_med3_f32 v39, v13, v38, v66
	v_med3_f32 v13, v17, v13, v66
	v_med3_f32 v17, v18, v17, v66
	v_med3_f32 v18, v19, v18, v66
	v_med3_f32 v19, v20, v19, v66
	v_med3_f32 v20, v21, v20, v66
	v_med3_f32 v21, v22, v21, v66
	v_med3_f32 v22, v23, v22, v66
	v_med3_f32 v23, v24, v23, v66
	v_med3_f32 v24, v25, v24, v66
	v_med3_f32 v25, v26, v25, v66
	v_med3_f32 v26, v27, v26, v66
	v_med3_f32 v27, v28, v27, v66
	v_max_f32_e32 v28, v28, v29
	v_max_f32_e32 v29, v67, v67
	v_med3_f32 v40, v13, v39, v67
	v_med3_f32 v13, v17, v13, v67
	v_med3_f32 v17, v18, v17, v67
	v_med3_f32 v18, v19, v18, v67
	v_med3_f32 v19, v20, v19, v67
	v_med3_f32 v20, v21, v20, v67
	v_med3_f32 v21, v22, v21, v67
	v_med3_f32 v22, v23, v22, v67
	v_med3_f32 v23, v24, v23, v67
	v_med3_f32 v24, v25, v24, v67
	v_med3_f32 v25, v26, v25, v67
	v_med3_f32 v26, v27, v26, v67
	v_med3_f32 v27, v28, v27, v67
	v_max_f32_e32 v28, v28, v29
	v_max_f32_e32 v29, v68, v68
	v_med3_f32 v41, v13, v40, v68
	v_med3_f32 v13, v17, v13, v68
	v_med3_f32 v17, v18, v17, v68
	v_med3_f32 v18, v19, v18, v68
	v_med3_f32 v19, v20, v19, v68
	v_med3_f32 v20, v21, v20, v68
	v_med3_f32 v21, v22, v21, v68
	v_med3_f32 v22, v23, v22, v68
	v_med3_f32 v23, v24, v23, v68
	v_med3_f32 v24, v25, v24, v68
	v_med3_f32 v25, v26, v25, v68
	v_med3_f32 v26, v27, v26, v68
	v_med3_f32 v27, v28, v27, v68
	v_max_f32_e32 v28, v28, v29
	v_max_f32_e32 v29, v69, v69
	v_med3_f32 v42, v13, v41, v69
	v_med3_f32 v13, v17, v13, v69
	v_med3_f32 v17, v18, v17, v69
	v_med3_f32 v18, v19, v18, v69
	v_med3_f32 v19, v20, v19, v69
	v_med3_f32 v20, v21, v20, v69
	v_med3_f32 v21, v22, v21, v69
	v_med3_f32 v22, v23, v22, v69
	v_med3_f32 v23, v24, v23, v69
	v_med3_f32 v24, v25, v24, v69
	v_med3_f32 v25, v26, v25, v69
	v_med3_f32 v26, v27, v26, v69
	v_med3_f32 v27, v28, v27, v69
	v_max_f32_e32 v28, v28, v29
	v_max_f32_e32 v29, v70, v70
	v_med3_f32 v43, v13, v42, v70
	v_med3_f32 v13, v17, v13, v70
	v_med3_f32 v17, v18, v17, v70
	v_med3_f32 v18, v19, v18, v70
	v_med3_f32 v19, v20, v19, v70
	v_med3_f32 v20, v21, v20, v70
	v_med3_f32 v21, v22, v21, v70
	v_med3_f32 v22, v23, v22, v70
	v_med3_f32 v23, v24, v23, v70
	v_med3_f32 v24, v25, v24, v70
	v_med3_f32 v25, v26, v25, v70
	v_med3_f32 v26, v27, v26, v70
	v_med3_f32 v27, v28, v27, v70
	v_max_f32_e32 v28, v28, v29
	v_med3_f32 v44, v13, v43, v71
	v_med3_f32 v13, v17, v13, v71
	v_med3_f32 v29, v18, v17, v71
	v_med3_f32 v17, v19, v18, v71
	v_med3_f32 v18, v20, v19, v71
	v_med3_f32 v30, v21, v20, v71
	v_med3_f32 v21, v22, v21, v71
	v_med3_f32 v19, v23, v22, v71
	v_med3_f32 v20, v24, v23, v71
	v_med3_f32 v22, v25, v24, v71
	v_med3_f32 v23, v26, v25, v71
	v_med3_f32 v24, v27, v26, v71
	v_med3_f32 v25, v28, v27, v71
	v_max_f32_e32 v26, v71, v71
	v_max_f32_e32 v26, v28, v26
	v_med3_f32 v45, v17, v29, v72
	v_med3_f32 v46, v18, v17, v72
	v_med3_f32 v48, v30, v18, v72
	v_med3_f32 v51, v22, v20, v72
	v_med3_f32 v31, v24, v23, v72
	v_med3_f32 v24, v25, v24, v72
	v_max_f32_e32 v17, v72, v72
	v_med3_f32 v22, v23, v22, v72
	v_med3_f32 v23, v21, v30, v72
	v_med3_f32 v28, v13, v44, v72
	v_med3_f32 v49, v19, v21, v72
	v_med3_f32 v50, v20, v19, v72
	v_max_f32_e32 v27, v26, v17
	v_med3_f32 v20, v24, v31, v73
	v_med3_f32 v52, v26, v25, v72
	v_med3_f32 v26, v22, v51, v73
	v_med3_f32 v18, v23, v48, v73
	v_med3_f32 v13, v29, v13, v72
	v_max_f32_e32 v29, v73, v73
	v_med3_f32 v31, v31, v22, v73
	v_med3_f32 v22, v48, v46, v73
	v_med3_f32 v48, v74, v58, v54
	v_med3_f32 v19, v50, v49, v73
	v_med3_f32 v25, v27, v52, v73
	v_med3_f32 v21, v13, v28, v73
	v_max_f32_e32 v30, v27, v29
	v_med3_f32 v27, v52, v24, v73
	v_med3_f32 v23, v49, v23, v73
	v_med3_f32 v24, v45, v13, v73
	v_med3_f32 v49, v6, v48, v55
	v_max_f32_e32 v6, v0, v0
	v_max_f32_e32 v13, v104, v104
	v_max_f32_e32 v6, v13, v6
	v_max_f32_e32 v13, v1, v1
	v_med3_f32 v29, v51, v50, v73
	v_med3_f32 v50, v32, v49, v60
	v_max_f32_e32 v13, v6, v13
	s_waitcnt lgkmcnt(13)
	v_max_f32_e32 v32, v2, v2
	v_med3_f32 v51, v33, v50, v61
	v_max_f32_e32 v33, v13, v32
	s_waitcnt lgkmcnt(12)
	v_max_f32_e32 v32, v3, v3
	v_med3_f32 v111, v34, v51, v62
	v_max_f32_e32 v34, v33, v32
	s_waitcnt lgkmcnt(11)
	v_max_f32_e32 v32, v4, v4
	v_med3_f32 v112, v35, v111, v63
	v_max_f32_e32 v35, v34, v32
	s_waitcnt lgkmcnt(10)
	v_max_f32_e32 v32, v5, v5
	v_med3_f32 v113, v36, v112, v64
	v_max_f32_e32 v36, v35, v32
	s_waitcnt lgkmcnt(9)
	v_max_f32_e32 v32, v7, v7
	v_med3_f32 v114, v37, v113, v65
	v_max_f32_e32 v37, v36, v32
	s_waitcnt lgkmcnt(8)
	v_max_f32_e32 v32, v8, v8
	v_med3_f32 v115, v38, v114, v66
	v_max_f32_e32 v38, v37, v32
	s_waitcnt lgkmcnt(7)
	v_max_f32_e32 v32, v9, v9
	v_med3_f32 v116, v39, v115, v67
	v_max_f32_e32 v39, v38, v32
	s_waitcnt lgkmcnt(6)
	v_max_f32_e32 v32, v10, v10
	v_med3_f32 v117, v40, v116, v68
	v_max_f32_e32 v40, v39, v32
	s_waitcnt lgkmcnt(5)
	v_max_f32_e32 v32, v11, v11
	v_med3_f32 v118, v41, v117, v69
	v_max_f32_e32 v41, v40, v32
	s_waitcnt lgkmcnt(4)
	v_max_f32_e32 v32, v12, v12
	v_med3_f32 v119, v42, v118, v70
	v_max_f32_e32 v42, v41, v32
	s_waitcnt lgkmcnt(3)
	v_max_f32_e32 v32, v14, v14
	v_med3_f32 v120, v43, v119, v71
	v_max_f32_e32 v43, v42, v32
	s_waitcnt lgkmcnt(2)
	v_max_f32_e32 v32, v15, v15
	v_med3_f32 v121, v44, v120, v72
	v_max_f32_e32 v44, v43, v32
	s_waitcnt lgkmcnt(1)
	v_max_f32_e32 v32, v16, v16
	v_med3_f32 v17, v46, v45, v73
	v_max_f32_e32 v45, v44, v32
	s_waitcnt lgkmcnt(0)
	v_max_f32_e32 v32, v47, v47
	v_max_f32_e32 v32, v45, v32
	v_add_f32_e32 v46, v30, v32
	v_and_b32_e32 v46, 0xffffff00, v46
	v_max_f32_e32 v46, v46, v46
	v_max_f32_e32 v122, 0xff800000, v46
	v_med3_f32 v46, v104, v103, v0
	v_med3_f32 v6, v6, v46, v1
	v_med3_f32 v13, v13, v6, v2
	v_med3_f32 v52, v33, v13, v3
	v_med3_f32 v34, v34, v52, v4
	v_med3_f32 v35, v35, v34, v5
	v_med3_f32 v36, v36, v35, v7
	v_med3_f32 v37, v37, v36, v8
	v_med3_f32 v38, v38, v37, v9
	v_med3_f32 v39, v39, v38, v10
	v_med3_f32 v40, v40, v39, v11
	v_med3_f32 v41, v41, v40, v12
	v_med3_f32 v42, v42, v41, v14
	v_med3_f32 v43, v43, v42, v15
	v_med3_f32 v44, v44, v43, v16
	v_med3_f32 v33, v45, v44, v47
	v_add_f32_e32 v45, v30, v33
	v_and_or_b32 v45, v45, s26, 1
	v_max_f32_e32 v123, v45, v45
	v_med3_f32 v45, v103, v102, v0
	v_med3_f32 v46, v46, v45, v1
	v_med3_f32 v6, v6, v46, v2
	v_med3_f32 v13, v13, v6, v3
	v_med3_f32 v52, v52, v13, v4
	v_med3_f32 v53, v34, v52, v5
	v_med3_f32 v35, v35, v53, v7
	v_med3_f32 v36, v36, v35, v8
	v_med3_f32 v37, v37, v36, v9
	v_med3_f32 v38, v38, v37, v10
	v_med3_f32 v39, v39, v38, v11
	v_med3_f32 v40, v40, v39, v12
	v_med3_f32 v41, v41, v40, v14
	v_med3_f32 v42, v42, v41, v15
	v_med3_f32 v43, v43, v42, v16
	v_med3_f32 v34, v44, v43, v47
	v_add_f32_e32 v44, v30, v34
	v_and_or_b32 v125, v44, s26, 2
	v_med3_f32 v44, v102, v101, v0
	v_med3_f32 v45, v45, v44, v1
	v_med3_f32 v46, v46, v45, v2
	v_med3_f32 v6, v6, v46, v3
	v_med3_f32 v13, v13, v6, v4
	v_med3_f32 v52, v52, v13, v5
	v_med3_f32 v53, v53, v52, v7
	v_med3_f32 v74, v35, v53, v8
	v_med3_f32 v36, v36, v74, v9
	v_med3_f32 v37, v37, v36, v10
	v_med3_f32 v38, v38, v37, v11
	v_med3_f32 v39, v39, v38, v12
	v_med3_f32 v40, v40, v39, v14
	v_med3_f32 v41, v41, v40, v15
	v_med3_f32 v42, v42, v41, v16
	v_med3_f32 v35, v43, v42, v47
	v_add_f32_e32 v43, v30, v35
	v_and_or_b32 v128, v43, s26, 3
	v_med3_f32 v43, v101, v100, v0
	v_med3_f32 v44, v44, v43, v1
	v_med3_f32 v45, v45, v44, v2
	v_med3_f32 v46, v46, v45, v3
	v_med3_f32 v6, v6, v46, v4
	v_med3_f32 v13, v13, v6, v5
	v_med3_f32 v52, v52, v13, v7
	v_med3_f32 v53, v53, v52, v8
	v_med3_f32 v74, v74, v53, v9
	v_med3_f32 v75, v36, v74, v10
	v_med3_f32 v37, v37, v75, v11
	v_med3_f32 v38, v38, v37, v12
	v_med3_f32 v39, v39, v38, v14
	v_med3_f32 v40, v40, v39, v15
	v_med3_f32 v41, v41, v40, v16
	v_med3_f32 v36, v42, v41, v47
	v_add_f32_e32 v42, v30, v36
	v_and_or_b32 v131, v42, s26, 4
	v_med3_f32 v42, v100, v99, v0
	v_med3_f32 v43, v43, v42, v1
	v_med3_f32 v44, v44, v43, v2
	v_med3_f32 v45, v45, v44, v3
	v_med3_f32 v46, v46, v45, v4
	v_med3_f32 v6, v6, v46, v5
	v_med3_f32 v13, v13, v6, v7
	v_med3_f32 v52, v52, v13, v8
	v_med3_f32 v53, v53, v52, v9
	v_med3_f32 v74, v74, v53, v10
	v_med3_f32 v75, v75, v74, v11
	v_med3_f32 v76, v37, v75, v12
	v_med3_f32 v38, v38, v76, v14
	v_med3_f32 v39, v39, v38, v15
	v_med3_f32 v40, v40, v39, v16
	v_med3_f32 v37, v41, v40, v47
	v_add_f32_e32 v41, v30, v37
	v_and_or_b32 v110, v41, s26, 5
	v_med3_f32 v41, v99, v98, v0
	v_med3_f32 v42, v42, v41, v1
	v_med3_f32 v43, v43, v42, v2
	v_med3_f32 v44, v44, v43, v3
	v_med3_f32 v45, v45, v44, v4
	v_med3_f32 v46, v46, v45, v5
	v_med3_f32 v6, v6, v46, v7
	v_med3_f32 v13, v13, v6, v8
	v_med3_f32 v52, v52, v13, v9
	v_med3_f32 v53, v53, v52, v10
	v_med3_f32 v74, v74, v53, v11
	v_med3_f32 v75, v75, v74, v12
	v_med3_f32 v76, v76, v75, v14
	v_med3_f32 v77, v38, v76, v15
	v_med3_f32 v39, v39, v77, v16
	v_med3_f32 v38, v40, v39, v47
	v_add_f32_e32 v40, v30, v38
	v_and_or_b32 v108, v40, s26, 6
	v_med3_f32 v40, v98, v97, v0
	v_med3_f32 v41, v41, v40, v1
	v_med3_f32 v42, v42, v41, v2
	v_med3_f32 v43, v43, v42, v3
	v_med3_f32 v44, v44, v43, v4
	v_med3_f32 v45, v45, v44, v5
	v_med3_f32 v46, v46, v45, v7
	v_med3_f32 v6, v6, v46, v8
	v_med3_f32 v13, v13, v6, v9
	v_med3_f32 v52, v52, v13, v10
	v_med3_f32 v53, v53, v52, v11
	v_med3_f32 v74, v74, v53, v12
	v_med3_f32 v75, v75, v74, v14
	v_med3_f32 v76, v76, v75, v15
	v_med3_f32 v77, v77, v76, v16
	v_med3_f32 v39, v39, v77, v47
	v_add_f32_e32 v78, v30, v39
	v_and_or_b32 v106, v78, s26, 7
	v_med3_f32 v78, v97, v96, v0
	v_med3_f32 v79, v40, v78, v1
	v_med3_f32 v41, v41, v79, v2
	v_med3_f32 v42, v42, v41, v3
	v_med3_f32 v43, v43, v42, v4
	v_med3_f32 v44, v44, v43, v5
	v_med3_f32 v45, v45, v44, v7
	v_med3_f32 v46, v46, v45, v8
	v_med3_f32 v6, v6, v46, v9
	v_med3_f32 v13, v13, v6, v10
	v_med3_f32 v52, v52, v13, v11
	v_med3_f32 v53, v53, v52, v12
	v_med3_f32 v74, v74, v53, v14
	v_med3_f32 v75, v75, v74, v15
	v_med3_f32 v76, v76, v75, v16
	v_med3_f32 v40, v77, v76, v47
	v_add_f32_e32 v77, v30, v40
	v_and_or_b32 v104, v77, s26, 8
	v_med3_f32 v77, v96, v95, v0
	v_med3_f32 v78, v78, v77, v1
	v_med3_f32 v79, v79, v78, v2
	v_med3_f32 v80, v41, v79, v3
	v_med3_f32 v42, v42, v80, v4
	v_med3_f32 v43, v43, v42, v5
	v_med3_f32 v44, v44, v43, v7
	v_med3_f32 v45, v45, v44, v8
	v_med3_f32 v46, v46, v45, v9
	v_med3_f32 v6, v6, v46, v10
	v_med3_f32 v13, v13, v6, v11
	v_med3_f32 v52, v52, v13, v12
	v_med3_f32 v53, v53, v52, v14
	v_med3_f32 v74, v74, v53, v15
	v_med3_f32 v75, v75, v74, v16
	v_med3_f32 v41, v76, v75, v47
	v_add_f32_e32 v76, v30, v41
	v_and_or_b32 v102, v76, s26, 9
	v_med3_f32 v76, v95, v94, v0
	v_med3_f32 v77, v77, v76, v1
	v_med3_f32 v78, v78, v77, v2
	v_med3_f32 v79, v79, v78, v3
	v_med3_f32 v80, v80, v79, v4
	v_med3_f32 v81, v42, v80, v5
	v_med3_f32 v43, v43, v81, v7
	v_med3_f32 v44, v44, v43, v8
	v_med3_f32 v45, v45, v44, v9
	v_med3_f32 v46, v46, v45, v10
	v_med3_f32 v6, v6, v46, v11
	v_med3_f32 v13, v13, v6, v12
	v_med3_f32 v52, v52, v13, v14
	v_med3_f32 v53, v53, v52, v15
	v_med3_f32 v74, v74, v53, v16
	v_med3_f32 v42, v75, v74, v47
	v_add_f32_e32 v75, v30, v42
	v_and_or_b32 v100, v75, s26, 10
	v_med3_f32 v75, v94, v93, v0
	v_med3_f32 v76, v76, v75, v1
	v_med3_f32 v77, v77, v76, v2
	v_med3_f32 v78, v78, v77, v3
	v_med3_f32 v79, v79, v78, v4
	v_med3_f32 v80, v80, v79, v5
	v_med3_f32 v81, v81, v80, v7
	v_med3_f32 v82, v43, v81, v8
	v_med3_f32 v44, v44, v82, v9
	v_med3_f32 v45, v45, v44, v10
	v_med3_f32 v46, v46, v45, v11
	v_med3_f32 v6, v6, v46, v12
	v_med3_f32 v13, v13, v6, v14
	v_med3_f32 v52, v52, v13, v15
	v_med3_f32 v53, v53, v52, v16
	v_med3_f32 v43, v74, v53, v47
	v_add_f32_e32 v74, v30, v43
	v_and_or_b32 v96, v74, s26, 11
	v_med3_f32 v74, v93, v92, v0
	v_med3_f32 v75, v75, v74, v1
	v_med3_f32 v83, v76, v75, v2
	v_med3_f32 v77, v77, v83, v3
	v_med3_f32 v78, v78, v77, v4
	v_med3_f32 v79, v79, v78, v5
	v_med3_f32 v80, v80, v79, v7
	v_med3_f32 v81, v81, v80, v8
	v_med3_f32 v82, v82, v81, v9
	v_med3_f32 v85, v44, v82, v10
	v_med3_f32 v45, v45, v85, v11
	v_med3_f32 v46, v46, v45, v12
	v_med3_f32 v6, v6, v46, v14
	v_med3_f32 v13, v13, v6, v15
	v_med3_f32 v52, v52, v13, v16
	v_med3_f32 v44, v53, v52, v47
	v_add_f32_e32 v53, v30, v44
	v_and_or_b32 v93, v53, s26, 12
	v_med3_f32 v53, v92, v91, v0
	v_med3_f32 v74, v74, v53, v1
	v_med3_f32 v75, v75, v74, v2
	v_med3_f32 v83, v83, v75, v3
	v_med3_f32 v77, v77, v83, v4
	v_med3_f32 v78, v78, v77, v5
	v_med3_f32 v79, v79, v78, v7
	v_med3_f32 v80, v80, v79, v8
	v_med3_f32 v81, v81, v80, v9
	v_med3_f32 v86, v82, v81, v10
	v_med3_f32 v85, v85, v86, v11
	v_med3_f32 v87, v45, v85, v12
	v_med3_f32 v46, v46, v87, v14
	v_med3_f32 v6, v6, v46, v15
	v_med3_f32 v88, v13, v6, v16
	v_med3_f32 v45, v52, v88, v47
	v_med3_f32 v52, v91, v89, v0
	v_med3_f32 v53, v53, v52, v1
	v_med3_f32 v0, v89, v90, v0
	v_med3_f32 v74, v74, v53, v2
	v_med3_f32 v0, v52, v0, v1
	v_med3_f32 v75, v75, v74, v3
	v_med3_f32 v0, v53, v0, v2
	v_med3_f32 v83, v83, v75, v4
	v_med3_f32 v0, v74, v0, v3
	v_med3_f32 v91, v77, v83, v5
	v_med3_f32 v0, v75, v0, v4
	v_max_f32_e32 v124, v122, v123
	v_max_f32_e32 v126, v125, v125
	v_med3_f32 v78, v78, v91, v7
	v_med3_f32 v0, v83, v0, v5
	v_max_f32_e32 v127, v124, v126
	v_max_f32_e32 v129, v128, v128
	v_med3_f32 v79, v79, v78, v8
	v_med3_f32 v0, v91, v0, v7
	v_max_f32_e32 v130, v127, v129
	v_max_f32_e32 v109, v131, v131
	v_med3_f32 v80, v80, v79, v9
	v_med3_f32 v0, v78, v0, v8
	v_max_f32_e32 v132, v130, v109
	v_max_f32_e32 v107, v110, v110
	v_med3_f32 v81, v81, v80, v10
	v_med3_f32 v0, v79, v0, v9
	v_max_f32_e32 v133, v132, v107
	v_max_f32_e32 v105, v108, v108
	v_med3_f32 v86, v86, v81, v11
	v_med3_f32 v0, v80, v0, v10
	v_max_f32_e32 v134, v133, v105
	v_max_f32_e32 v103, v106, v106
	v_med3_f32 v85, v85, v86, v12
	v_med3_f32 v0, v81, v0, v11
	v_max_f32_e32 v135, v134, v103
	v_max_f32_e32 v101, v104, v104
	v_med3_f32 v87, v87, v85, v14
	v_med3_f32 v0, v86, v0, v12
	v_max_f32_e32 v136, v135, v101
	v_max_f32_e32 v98, v102, v102
	v_med3_f32 v92, v46, v87, v15
	v_med3_f32 v0, v85, v0, v14
	v_max_f32_e32 v137, v136, v98
	v_max_f32_e32 v95, v100, v100
	v_med3_f32 v94, v6, v92, v16
	v_med3_f32 v0, v87, v0, v15
	v_max_f32_e32 v138, v137, v95
	v_max_f32_e32 v84, v96, v96
	v_add_f32_e32 v13, v30, v45
	v_med3_f32 v46, v88, v94, v47
	v_med3_f32 v0, v92, v0, v16
	v_max_f32_e32 v139, v138, v84
	v_max_f32_e32 v76, v93, v93
	v_and_or_b32 v82, v13, s26, 13
	v_add_f32_e32 v6, v30, v46
	v_med3_f32 v47, v94, v0, v47
	v_max_f32_e32 v140, v139, v76
	v_max_f32_e32 v13, v82, v82
	v_and_or_b32 v77, v6, s26, 14
	v_add_f32_e32 v0, v30, v47
	v_max_f32_e32 v141, v140, v13
	v_max_f32_e32 v6, v77, v77
	v_and_or_b32 v14, v0, s26, 15
	v_add_f32_e32 v1, v25, v32
	v_max_f32_e32 v142, v141, v6
	v_max_f32_e32 v0, v14, v14
	v_and_or_b32 v1, v1, s26, 16
	v_max_f32_e32 v143, v142, v0
	v_max_f32_e32 v2, v1, v1
	v_max_f32_e32 v144, v143, v2
	v_add_f32_e32 v2, v25, v33
	v_and_or_b32 v2, v2, s26, 17
	v_max_f32_e32 v3, v2, v2
	v_max_f32_e32 v146, v144, v3
	v_add_f32_e32 v3, v25, v34
	v_and_or_b32 v3, v3, s26, 18
	v_max_f32_e32 v4, v3, v3
	v_max_f32_e32 v147, v146, v4
	v_add_f32_e32 v4, v25, v35
	v_and_or_b32 v4, v4, s26, 19
	v_max_f32_e32 v5, v4, v4
	v_max_f32_e32 v148, v147, v5
	v_add_f32_e32 v5, v25, v36
	v_and_or_b32 v5, v5, s26, 20
	v_max_f32_e32 v7, v5, v5
	v_max_f32_e32 v149, v148, v7
	v_add_f32_e32 v7, v25, v37
	v_and_or_b32 v7, v7, s26, 21
	v_max_f32_e32 v8, v7, v7
	v_max_f32_e32 v150, v149, v8
	v_add_f32_e32 v8, v25, v38
	v_and_or_b32 v8, v8, s26, 22
	v_max_f32_e32 v9, v8, v8
	v_max_f32_e32 v151, v150, v9
	v_add_f32_e32 v9, v25, v39
	v_and_or_b32 v9, v9, s26, 23
	v_max_f32_e32 v10, v9, v9
	v_max_f32_e32 v164, v151, v10
	v_add_f32_e32 v10, v27, v32
	v_and_or_b32 v10, v10, s26, 32
	v_max_f32_e32 v11, v10, v10
	v_max_f32_e32 v165, v164, v11
	v_add_f32_e32 v11, v27, v33
	v_and_or_b32 v11, v11, s26, 33
	v_max_f32_e32 v12, v11, v11
	v_max_f32_e32 v166, v165, v12
	v_add_f32_e32 v12, v27, v34
	v_and_or_b32 v12, v12, s26, 34
	v_max_f32_e32 v15, v12, v12
	v_max_f32_e32 v167, v166, v15
	v_add_f32_e32 v15, v27, v35
	v_and_or_b32 v15, v15, s26, 35
	v_max_f32_e32 v16, v15, v15
	v_max_f32_e32 v168, v167, v16
	v_add_f32_e32 v16, v27, v36
	v_and_or_b32 v16, v16, s26, 36
	v_max_f32_e32 v52, v16, v16
	v_max_f32_e32 v169, v168, v52
	v_add_f32_e32 v52, v20, v32
	v_and_or_b32 v52, v52, s26, 48
	v_max_f32_e32 v53, v52, v52
	v_max_f32_e32 v170, v169, v53
	v_add_f32_e32 v53, v20, v33
	v_and_or_b32 v53, v53, s26, 49
	v_max_f32_e32 v74, v53, v53
	v_max_f32_e32 v171, v170, v74
	v_add_f32_e32 v74, v20, v34
	v_and_or_b32 v74, v74, s26, 50
	v_max_f32_e32 v75, v74, v74
	v_max_f32_e32 v172, v171, v75
	v_add_f32_e32 v75, v20, v35
	v_and_or_b32 v75, v75, s26, 51
	v_max_f32_e32 v78, v75, v75
	v_max_f32_e32 v173, v172, v78
	v_add_f32_e32 v78, v31, v32
	v_and_or_b32 v78, v78, s26, 64
	v_max_f32_e32 v79, v78, v78
	v_max_f32_e32 v174, v173, v79
	v_add_f32_e32 v79, v31, v33
	v_and_b32_e32 v79, 0xffffff00, v79
	v_or_b32_e32 v79, 0x41, v79
	v_max_f32_e32 v80, v79, v79
	v_max_f32_e32 v175, v174, v80
	v_add_f32_e32 v80, v31, v34
	v_and_b32_e32 v80, 0xffffff00, v80
	v_or_b32_e32 v80, 0x42, v80
	v_max_f32_e32 v81, v80, v80
	v_max_f32_e32 v176, v175, v81
	v_add_f32_e32 v81, v26, v32
	v_and_b32_e32 v81, 0xffffff00, v81
	v_or_b32_e32 v81, 0x50, v81
	v_med3_f32 v54, v58, v59, v54
	v_max_f32_e32 v83, v81, v81
	v_med3_f32 v48, v48, v54, v55
	v_max_f32_e32 v177, v176, v83
	v_add_f32_e32 v83, v26, v33
	v_med3_f32 v48, v49, v48, v60
	v_and_b32_e32 v83, 0xffffff00, v83
	v_med3_f32 v48, v50, v48, v61
	v_or_b32_e32 v83, 0x51, v83
	v_med3_f32 v48, v51, v48, v62
	v_min_f32_e32 v51, v122, v123
	v_max_f32_e32 v85, v83, v83
	v_med3_f32 v54, v124, v51, v125
	v_min_f32_e32 v126, v51, v126
	v_max_f32_e32 v180, v177, v85
	v_add_f32_e32 v85, v29, v32
	v_med3_f32 v55, v127, v54, v128
	v_med3_f32 v54, v54, v126, v128
	v_min_f32_e32 v126, v126, v129
	v_and_b32_e32 v85, 0xffffff00, v85
	v_med3_f32 v59, v130, v55, v131
	v_med3_f32 v55, v55, v54, v131
	v_med3_f32 v129, v54, v126, v131
	v_min_f32_e32 v109, v126, v109
	v_or_b32_e32 v85, 0x60, v85
	v_med3_f32 v60, v132, v59, v110
	v_med3_f32 v59, v59, v55, v110
	v_med3_f32 v55, v55, v129, v110
	v_med3_f32 v110, v129, v109, v110
	v_min_f32_e32 v107, v109, v107
	v_max_f32_e32 v86, v85, v85
	v_med3_f32 v61, v133, v60, v108
	v_med3_f32 v60, v60, v59, v108
	v_med3_f32 v59, v59, v55, v108
	v_med3_f32 v126, v55, v110, v108
	v_med3_f32 v108, v110, v107, v108
	v_min_f32_e32 v105, v107, v105
	v_max_f32_e32 v181, v180, v86
	v_add_f32_e32 v86, v29, v33
	v_med3_f32 v62, v134, v61, v106
	v_med3_f32 v61, v61, v60, v106
	v_med3_f32 v60, v60, v59, v106
	v_med3_f32 v59, v59, v126, v106
	v_med3_f32 v109, v126, v108, v106
	v_med3_f32 v106, v108, v105, v106
	v_min_f32_e32 v103, v105, v103
	v_and_b32_e32 v86, 0xffffff00, v86
	v_med3_f32 v48, v111, v48, v63
	v_med3_f32 v63, v135, v62, v104
	v_med3_f32 v62, v62, v61, v104
	v_med3_f32 v61, v61, v60, v104
	v_med3_f32 v60, v60, v59, v104
	v_med3_f32 v110, v59, v109, v104
	v_med3_f32 v107, v109, v106, v104
	v_med3_f32 v104, v106, v103, v104
	v_min_f32_e32 v101, v103, v101
	v_or_b32_e32 v86, 0x61, v86
	v_med3_f32 v48, v112, v48, v64
	v_med3_f32 v64, v136, v63, v102
	v_med3_f32 v63, v63, v62, v102
	v_med3_f32 v62, v62, v61, v102
	v_med3_f32 v61, v61, v60, v102
	v_med3_f32 v60, v60, v110, v102
	v_med3_f32 v108, v110, v107, v102
	v_med3_f32 v105, v107, v104, v102
	v_med3_f32 v102, v104, v101, v102
	v_min_f32_e32 v98, v101, v98
	v_max_f32_e32 v87, v86, v86
	v_med3_f32 v48, v113, v48, v65
	v_med3_f32 v65, v137, v64, v100
	v_med3_f32 v64, v64, v63, v100
	v_med3_f32 v63, v63, v62, v100
	v_med3_f32 v62, v62, v61, v100
	v_med3_f32 v61, v61, v60, v100
	v_med3_f32 v109, v60, v108, v100
	v_med3_f32 v106, v108, v105, v100
	v_med3_f32 v103, v105, v102, v100
	v_med3_f32 v100, v102, v98, v100
	v_min_f32_e32 v95, v98, v95
	v_max_f32_e32 v185, v181, v87
	v_add_f32_e32 v87, v19, v32
	v_med3_f32 v48, v114, v48, v66
	v_med3_f32 v66, v138, v65, v96
	v_med3_f32 v65, v65, v64, v96
	v_med3_f32 v64, v64, v63, v96
	v_med3_f32 v63, v63, v62, v96
	v_med3_f32 v62, v62, v61, v96
	v_med3_f32 v61, v61, v109, v96
	v_med3_f32 v107, v109, v106, v96
	v_med3_f32 v104, v106, v103, v96
	v_med3_f32 v101, v103, v100, v96
	v_med3_f32 v96, v100, v95, v96
	v_min_f32_e32 v84, v95, v84
	v_and_b32_e32 v87, 0xffffff00, v87
	v_med3_f32 v48, v115, v48, v67
	v_med3_f32 v67, v139, v66, v93
	v_med3_f32 v66, v66, v65, v93
	v_med3_f32 v65, v65, v64, v93
	v_med3_f32 v64, v64, v63, v93
	v_med3_f32 v63, v63, v62, v93
	v_med3_f32 v62, v62, v61, v93
	v_med3_f32 v108, v61, v107, v93
	v_med3_f32 v105, v107, v104, v93
	v_med3_f32 v102, v104, v101, v93
	v_med3_f32 v98, v101, v96, v93
	v_med3_f32 v93, v96, v84, v93
	v_min_f32_e32 v76, v84, v76
	v_or_b32_e32 v87, 0x70, v87
	v_med3_f32 v48, v116, v48, v68
	v_med3_f32 v68, v140, v67, v82
	v_med3_f32 v67, v67, v66, v82
	v_med3_f32 v66, v66, v65, v82
	v_med3_f32 v65, v65, v64, v82
	v_med3_f32 v64, v64, v63, v82
	v_med3_f32 v63, v63, v62, v82
	v_med3_f32 v62, v62, v108, v82
	v_med3_f32 v106, v108, v105, v82
	v_med3_f32 v103, v105, v102, v82
	v_med3_f32 v100, v102, v98, v82
	v_med3_f32 v95, v98, v93, v82
	v_med3_f32 v82, v93, v76, v82
	v_min_f32_e32 v13, v76, v13
	v_max_f32_e32 v88, v87, v87
	v_med3_f32 v48, v117, v48, v69
	v_med3_f32 v69, v141, v68, v77
	v_med3_f32 v68, v68, v67, v77
	v_med3_f32 v67, v67, v66, v77
	v_med3_f32 v66, v66, v65, v77
	v_med3_f32 v65, v65, v64, v77
	v_med3_f32 v64, v64, v63, v77
	v_med3_f32 v63, v63, v62, v77
	v_med3_f32 v107, v62, v106, v77
	v_med3_f32 v104, v106, v103, v77
	v_med3_f32 v101, v103, v100, v77
	v_med3_f32 v96, v100, v95, v77
	v_med3_f32 v84, v95, v82, v77
	v_med3_f32 v76, v82, v13, v77
	v_min_f32_e32 v6, v13, v6
	v_max_f32_e32 v186, v185, v88
	v_add_f32_e32 v88, v19, v33
	v_med3_f32 v48, v118, v48, v70
	v_med3_f32 v70, v142, v69, v14
	v_med3_f32 v69, v69, v68, v14
	v_med3_f32 v68, v68, v67, v14
	v_med3_f32 v67, v67, v66, v14
	v_med3_f32 v66, v66, v65, v14
	v_med3_f32 v65, v65, v64, v14
	v_med3_f32 v64, v64, v63, v14
	v_med3_f32 v63, v63, v107, v14
	v_med3_f32 v105, v107, v104, v14
	v_med3_f32 v102, v104, v101, v14
	v_med3_f32 v98, v101, v96, v14
	v_med3_f32 v93, v96, v84, v14
	v_med3_f32 v77, v84, v76, v14
	v_med3_f32 v13, v76, v6, v14
	v_min_f32_e32 v0, v6, v0
	v_and_b32_e32 v88, 0xffffff00, v88
	v_med3_f32 v48, v119, v48, v71
	v_med3_f32 v71, v143, v70, v1
	v_med3_f32 v70, v70, v69, v1
	v_med3_f32 v69, v69, v68, v1
	v_med3_f32 v68, v68, v67, v1
	v_med3_f32 v67, v67, v66, v1
	v_med3_f32 v66, v66, v65, v1
	v_med3_f32 v65, v65, v64, v1
	v_med3_f32 v64, v64, v63, v1
	v_med3_f32 v63, v63, v105, v1
	v_med3_f32 v103, v105, v102, v1
	v_med3_f32 v100, v102, v98, v1
	v_med3_f32 v95, v98, v93, v1
	v_med3_f32 v82, v93, v77, v1
	v_med3_f32 v14, v77, v13, v1
	v_med3_f32 v0, v13, v0, v1
	v_or_b32_e32 v88, 0x71, v88
	v_med3_f32 v48, v120, v48, v72
	v_med3_f32 v72, v144, v71, v2
	v_med3_f32 v71, v71, v70, v2
	v_med3_f32 v70, v70, v69, v2
	v_med3_f32 v69, v69, v68, v2
	v_med3_f32 v68, v68, v67, v2
	v_med3_f32 v67, v67, v66, v2
	v_med3_f32 v66, v66, v65, v2
	v_med3_f32 v65, v65, v64, v2
	v_med3_f32 v64, v64, v63, v2
	v_med3_f32 v63, v63, v103, v2
	v_med3_f32 v101, v103, v100, v2
	v_med3_f32 v96, v100, v95, v2
	v_med3_f32 v84, v95, v82, v2
	v_med3_f32 v76, v82, v14, v2
	v_med3_f32 v0, v14, v0, v2
	v_med3_f32 v28, v28, v121, v73
	v_max_f32_e32 v89, v88, v88
	v_med3_f32 v50, v121, v48, v73
	v_med3_f32 v73, v146, v72, v3
	v_med3_f32 v72, v72, v71, v3
	v_med3_f32 v71, v71, v70, v3
	v_med3_f32 v70, v70, v69, v3
	v_med3_f32 v69, v69, v68, v3
	v_med3_f32 v68, v68, v67, v3
	v_med3_f32 v67, v67, v66, v3
	v_med3_f32 v66, v66, v65, v3
	v_med3_f32 v65, v65, v64, v3
	v_med3_f32 v64, v64, v63, v3
	v_med3_f32 v63, v63, v101, v3
	v_med3_f32 v98, v101, v96, v3
	v_med3_f32 v93, v96, v84, v3
	v_med3_f32 v77, v84, v76, v3
	v_med3_f32 v0, v76, v0, v3
	v_max_f32_e32 v187, v186, v89
	v_add_f32_e32 v89, v23, v32
	v_med3_f32 v111, v147, v73, v4
	v_med3_f32 v73, v73, v72, v4
	v_med3_f32 v72, v72, v71, v4
	v_med3_f32 v71, v71, v70, v4
	v_med3_f32 v70, v70, v69, v4
	v_med3_f32 v69, v69, v68, v4
	v_med3_f32 v68, v68, v67, v4
	v_med3_f32 v67, v67, v66, v4
	v_med3_f32 v66, v66, v65, v4
	v_med3_f32 v65, v65, v64, v4
	v_med3_f32 v64, v64, v63, v4
	v_med3_f32 v63, v63, v98, v4
	v_med3_f32 v95, v98, v93, v4
	v_med3_f32 v82, v93, v77, v4
	v_med3_f32 v0, v77, v0, v4
	v_and_b32_e32 v89, 0xffffff00, v89
	v_med3_f32 v112, v148, v111, v5
	v_med3_f32 v111, v111, v73, v5
	v_med3_f32 v73, v73, v72, v5
	v_med3_f32 v72, v72, v71, v5
	v_med3_f32 v71, v71, v70, v5
	v_med3_f32 v70, v70, v69, v5
	v_med3_f32 v69, v69, v68, v5
	v_med3_f32 v68, v68, v67, v5
	v_med3_f32 v67, v67, v66, v5
	v_med3_f32 v66, v66, v65, v5
	v_med3_f32 v65, v65, v64, v5
	v_med3_f32 v64, v64, v63, v5
	v_med3_f32 v63, v63, v95, v5
	v_med3_f32 v84, v95, v82, v5
	v_med3_f32 v0, v82, v0, v5
	v_or_b32_e32 v89, 0x80, v89
	v_med3_f32 v113, v149, v112, v7
	v_med3_f32 v112, v112, v111, v7
	v_med3_f32 v111, v111, v73, v7
	v_med3_f32 v73, v73, v72, v7
	v_med3_f32 v72, v72, v71, v7
	v_med3_f32 v71, v71, v70, v7
	v_med3_f32 v70, v70, v69, v7
	v_med3_f32 v69, v69, v68, v7
	v_med3_f32 v68, v68, v67, v7
	v_med3_f32 v67, v67, v66, v7
	v_med3_f32 v66, v66, v65, v7
	v_med3_f32 v65, v65, v64, v7
	v_med3_f32 v64, v64, v63, v7
	v_med3_f32 v63, v63, v84, v7
	v_med3_f32 v0, v84, v0, v7
	v_max_f32_e32 v90, v89, v89
	v_med3_f32 v114, v150, v113, v8
	v_med3_f32 v113, v113, v112, v8
	v_med3_f32 v112, v112, v111, v8
	v_med3_f32 v111, v111, v73, v8
	v_med3_f32 v73, v73, v72, v8
	v_med3_f32 v72, v72, v71, v8
	v_med3_f32 v71, v71, v70, v8
	v_med3_f32 v70, v70, v69, v8
	v_med3_f32 v69, v69, v68, v8
	v_med3_f32 v68, v68, v67, v8
	v_med3_f32 v67, v67, v66, v8
	v_med3_f32 v66, v66, v65, v8
	v_med3_f32 v65, v65, v64, v8
	v_med3_f32 v64, v64, v63, v8
	v_med3_f32 v0, v63, v0, v8
	v_max_f32_e32 v188, v187, v90
	v_add_f32_e32 v90, v18, v32
	v_med3_f32 v115, v151, v114, v9
	v_med3_f32 v114, v114, v113, v9
	v_med3_f32 v113, v113, v112, v9
	v_med3_f32 v112, v112, v111, v9
	v_med3_f32 v111, v111, v73, v9
	v_med3_f32 v73, v73, v72, v9
	v_med3_f32 v72, v72, v71, v9
	v_med3_f32 v71, v71, v70, v9
	v_med3_f32 v70, v70, v69, v9
	v_med3_f32 v69, v69, v68, v9
	v_med3_f32 v68, v68, v67, v9
	v_med3_f32 v67, v67, v66, v9
	v_med3_f32 v66, v66, v65, v9
	v_med3_f32 v65, v65, v64, v9
	v_med3_f32 v0, v64, v0, v9
	v_and_b32_e32 v90, 0xffffff00, v90
	v_med3_f32 v116, v164, v115, v10
	v_med3_f32 v115, v115, v114, v10
	v_med3_f32 v114, v114, v113, v10
	v_med3_f32 v113, v113, v112, v10
	v_med3_f32 v112, v112, v111, v10
	v_med3_f32 v110, v111, v73, v10
	v_med3_f32 v73, v73, v72, v10
	v_med3_f32 v72, v72, v71, v10
	v_med3_f32 v71, v71, v70, v10
	v_med3_f32 v70, v70, v69, v10
	v_med3_f32 v69, v69, v68, v10
	v_med3_f32 v68, v68, v67, v10
	v_med3_f32 v67, v67, v66, v10
	v_med3_f32 v66, v66, v65, v10
	v_med3_f32 v0, v65, v0, v10
	v_or_b32_e32 v90, 0x90, v90
	v_med3_f32 v117, v165, v116, v11
	v_med3_f32 v116, v116, v115, v11
	v_med3_f32 v115, v115, v114, v11
	v_med3_f32 v114, v114, v113, v11
	v_med3_f32 v113, v113, v112, v11
	v_med3_f32 v111, v112, v110, v11
	v_med3_f32 v109, v110, v73, v11
	v_med3_f32 v73, v73, v72, v11
	v_med3_f32 v72, v72, v71, v11
	v_med3_f32 v71, v71, v70, v11
	v_med3_f32 v70, v70, v69, v11
	v_med3_f32 v69, v69, v68, v11
	v_med3_f32 v68, v68, v67, v11
	v_med3_f32 v67, v67, v66, v11
	v_med3_f32 v0, v66, v0, v11
	v_max_f32_e32 v91, v90, v90
	v_med3_f32 v118, v166, v117, v12
	v_med3_f32 v117, v117, v116, v12
	v_med3_f32 v116, v116, v115, v12
	v_med3_f32 v115, v115, v114, v12
	v_med3_f32 v114, v114, v113, v12
	v_med3_f32 v112, v113, v111, v12
	v_med3_f32 v110, v111, v109, v12
	v_med3_f32 v108, v109, v73, v12
	v_med3_f32 v73, v73, v72, v12
	v_med3_f32 v72, v72, v71, v12
	v_med3_f32 v71, v71, v70, v12
	v_med3_f32 v70, v70, v69, v12
	v_med3_f32 v69, v69, v68, v12
	v_med3_f32 v68, v68, v67, v12
	v_med3_f32 v0, v67, v0, v12
	v_max_f32_e32 v189, v188, v91
	v_add_f32_e32 v91, v22, v32
	v_med3_f32 v119, v167, v118, v15
	v_med3_f32 v118, v118, v117, v15
	v_med3_f32 v117, v117, v116, v15
	v_med3_f32 v116, v116, v115, v15
	v_med3_f32 v115, v115, v114, v15
	v_med3_f32 v113, v114, v112, v15
	v_med3_f32 v111, v112, v110, v15
	v_med3_f32 v109, v110, v108, v15
	v_med3_f32 v106, v108, v73, v15
	v_med3_f32 v73, v73, v72, v15
	v_med3_f32 v72, v72, v71, v15
	v_med3_f32 v71, v71, v70, v15
	v_med3_f32 v70, v70, v69, v15
	v_med3_f32 v69, v69, v68, v15
	v_med3_f32 v0, v68, v0, v15
	v_and_b32_e32 v91, 0xffffff00, v91
	v_med3_f32 v120, v168, v119, v16
	v_med3_f32 v119, v119, v118, v16
	v_med3_f32 v118, v118, v117, v16
	v_med3_f32 v117, v117, v116, v16
	v_med3_f32 v116, v116, v115, v16
	v_med3_f32 v114, v115, v113, v16
	v_med3_f32 v112, v113, v111, v16
	v_med3_f32 v110, v111, v109, v16
	v_med3_f32 v107, v109, v106, v16
	v_med3_f32 v104, v106, v73, v16
	v_med3_f32 v73, v73, v72, v16
	v_med3_f32 v72, v72, v71, v16
	v_med3_f32 v71, v71, v70, v16
	v_med3_f32 v70, v70, v69, v16
	v_med3_f32 v0, v69, v0, v16
	v_or_b32_e32 v91, 0xa0, v91
	v_med3_f32 v121, v169, v120, v52
	v_med3_f32 v120, v120, v119, v52
	v_med3_f32 v119, v119, v118, v52
	v_med3_f32 v118, v118, v117, v52
	v_med3_f32 v117, v117, v116, v52
	v_med3_f32 v115, v116, v114, v52
	v_med3_f32 v113, v114, v112, v52
	v_med3_f32 v111, v112, v110, v52
	v_med3_f32 v108, v110, v107, v52
	v_med3_f32 v105, v107, v104, v52
	v_med3_f32 v102, v104, v73, v52
	v_med3_f32 v73, v73, v72, v52
	v_med3_f32 v72, v72, v71, v52
	v_med3_f32 v71, v71, v70, v52
	v_med3_f32 v0, v70, v0, v52
	v_max_f32_e32 v92, v91, v91
	v_med3_f32 v122, v170, v121, v53
	v_med3_f32 v121, v121, v120, v53
	v_med3_f32 v120, v120, v119, v53
	v_med3_f32 v119, v119, v118, v53
	v_med3_f32 v118, v118, v117, v53
	v_med3_f32 v116, v117, v115, v53
	v_med3_f32 v114, v115, v113, v53
	v_med3_f32 v112, v113, v111, v53
	v_med3_f32 v109, v111, v108, v53
	v_med3_f32 v106, v108, v105, v53
	v_med3_f32 v103, v105, v102, v53
	v_med3_f32 v100, v102, v73, v53
	v_med3_f32 v73, v73, v72, v53
	v_med3_f32 v72, v72, v71, v53
	v_med3_f32 v0, v71, v0, v53
	v_max_f32_e32 v190, v189, v92
	v_add_f32_e32 v92, v17, v32
	v_med3_f32 v123, v171, v122, v74
	v_med3_f32 v122, v122, v121, v74
	v_med3_f32 v121, v121, v120, v74
	v_med3_f32 v120, v120, v119, v74
	v_med3_f32 v119, v119, v118, v74
	v_med3_f32 v117, v118, v116, v74
	v_med3_f32 v115, v116, v114, v74
	v_med3_f32 v113, v114, v112, v74
	v_med3_f32 v110, v112, v109, v74
	v_med3_f32 v107, v109, v106, v74
	v_med3_f32 v104, v106, v103, v74
	v_med3_f32 v101, v103, v100, v74
	v_med3_f32 v96, v100, v73, v74
	v_med3_f32 v73, v73, v72, v74
	v_med3_f32 v0, v72, v0, v74
	v_and_b32_e32 v92, 0xffffff00, v92
	v_med3_f32 v124, v172, v123, v75
	v_med3_f32 v123, v123, v122, v75
	v_med3_f32 v122, v122, v121, v75
	v_med3_f32 v121, v121, v120, v75
	v_med3_f32 v120, v120, v119, v75
	v_med3_f32 v118, v119, v117, v75
	v_med3_f32 v116, v117, v115, v75
	v_med3_f32 v114, v115, v113, v75
	v_med3_f32 v111, v113, v110, v75
	v_med3_f32 v108, v110, v107, v75
	v_med3_f32 v105, v107, v104, v75
	v_med3_f32 v102, v104, v101, v75
	v_med3_f32 v98, v101, v96, v75
	v_med3_f32 v93, v96, v73, v75
	v_med3_f32 v0, v73, v0, v75
	v_or_b32_e32 v92, 0xb0, v92
	v_med3_f32 v125, v173, v124, v78
	v_med3_f32 v124, v124, v123, v78
	v_med3_f32 v123, v123, v122, v78
	v_med3_f32 v122, v122, v121, v78
	v_med3_f32 v121, v121, v120, v78
	v_med3_f32 v119, v120, v118, v78
	v_med3_f32 v117, v118, v116, v78
	v_med3_f32 v115, v116, v114, v78
	v_med3_f32 v112, v114, v111, v78
	v_med3_f32 v109, v111, v108, v78
	v_med3_f32 v106, v108, v105, v78
	v_med3_f32 v103, v105, v102, v78
	v_med3_f32 v100, v102, v98, v78
	v_med3_f32 v95, v98, v93, v78
	v_med3_f32 v0, v93, v0, v78
	v_max_f32_e32 v94, v92, v92
	v_med3_f32 v127, v174, v125, v79
	v_med3_f32 v125, v125, v124, v79
	v_med3_f32 v124, v124, v123, v79
	v_med3_f32 v123, v123, v122, v79
	v_med3_f32 v122, v122, v121, v79
	v_med3_f32 v120, v121, v119, v79
	v_med3_f32 v118, v119, v117, v79
	v_med3_f32 v116, v117, v115, v79
	v_med3_f32 v113, v115, v112, v79
	v_med3_f32 v110, v112, v109, v79
	v_med3_f32 v107, v109, v106, v79
	v_med3_f32 v104, v106, v103, v79
	v_med3_f32 v101, v103, v100, v79
	v_med3_f32 v96, v100, v95, v79
	v_med3_f32 v0, v95, v0, v79
	v_max_f32_e32 v191, v190, v94
	v_add_f32_e32 v94, v24, v32
	v_med3_f32 v130, v175, v127, v80
	v_med3_f32 v127, v127, v125, v80
	v_med3_f32 v125, v125, v124, v80
	v_med3_f32 v124, v124, v123, v80
	v_med3_f32 v123, v123, v122, v80
	v_med3_f32 v121, v122, v120, v80
	v_med3_f32 v119, v120, v118, v80
	v_med3_f32 v117, v118, v116, v80
	v_med3_f32 v114, v116, v113, v80
	v_med3_f32 v111, v113, v110, v80
	v_med3_f32 v108, v110, v107, v80
	v_med3_f32 v105, v107, v104, v80
	v_med3_f32 v102, v104, v101, v80
	v_med3_f32 v98, v101, v96, v80
	v_med3_f32 v0, v96, v0, v80
	v_and_b32_e32 v94, 0xffffff00, v94
	v_med3_f32 v132, v176, v130, v81
	v_med3_f32 v128, v130, v127, v81
	v_med3_f32 v127, v127, v125, v81
	v_med3_f32 v125, v125, v124, v81
	v_med3_f32 v124, v124, v123, v81
	v_med3_f32 v122, v123, v121, v81
	v_med3_f32 v120, v121, v119, v81
	v_med3_f32 v118, v119, v117, v81
	v_med3_f32 v115, v117, v114, v81
	v_med3_f32 v112, v114, v111, v81
	v_med3_f32 v109, v111, v108, v81
	v_med3_f32 v106, v108, v105, v81
	v_med3_f32 v103, v105, v102, v81
	v_med3_f32 v100, v102, v98, v81
	v_med3_f32 v0, v98, v0, v81
	v_or_b32_e32 v94, 0xc0, v94
	v_med3_f32 v133, v177, v132, v83
	v_med3_f32 v130, v132, v128, v83
	v_med3_f32 v128, v128, v127, v83
	v_med3_f32 v127, v127, v125, v83
	v_med3_f32 v125, v125, v124, v83
	v_med3_f32 v123, v124, v122, v83
	v_med3_f32 v121, v122, v120, v83
	v_med3_f32 v119, v120, v118, v83
	v_med3_f32 v116, v118, v115, v83
	v_med3_f32 v113, v115, v112, v83
	v_med3_f32 v110, v112, v109, v83
	v_med3_f32 v107, v109, v106, v83
	v_med3_f32 v104, v106, v103, v83
	v_med3_f32 v101, v103, v100, v83
	v_med3_f32 v0, v100, v0, v83
	v_max_f32_e32 v97, v94, v94
	v_med3_f32 v134, v180, v133, v85
	v_med3_f32 v132, v133, v130, v85
	v_med3_f32 v130, v130, v128, v85
	v_med3_f32 v128, v128, v127, v85
	v_med3_f32 v126, v127, v125, v85
	v_med3_f32 v124, v125, v123, v85
	v_med3_f32 v122, v123, v121, v85
	v_med3_f32 v120, v121, v119, v85
	v_med3_f32 v117, v119, v116, v85
	v_med3_f32 v114, v116, v113, v85
	v_med3_f32 v111, v113, v110, v85
	v_med3_f32 v108, v110, v107, v85
	v_med3_f32 v105, v107, v104, v85
	v_med3_f32 v102, v104, v101, v85
	v_med3_f32 v0, v101, v0, v85
	v_max_f32_e32 v192, v191, v97
	v_add_f32_e32 v97, v21, v32
	v_med3_f32 v135, v181, v134, v86
	v_med3_f32 v133, v134, v132, v86
	v_med3_f32 v127, v128, v126, v86
	v_med3_f32 v125, v126, v124, v86
	v_med3_f32 v123, v124, v122, v86
	v_med3_f32 v121, v122, v120, v86
	v_med3_f32 v118, v120, v117, v86
	v_med3_f32 v115, v117, v114, v86
	v_med3_f32 v112, v114, v111, v86
	v_med3_f32 v109, v111, v108, v86
	v_med3_f32 v106, v108, v105, v86
	v_med3_f32 v103, v105, v102, v86
	v_med3_f32 v0, v102, v0, v86
	v_and_b32_e32 v97, 0xffffff00, v97
	v_med3_f32 v136, v185, v135, v87
	v_med3_f32 v134, v135, v133, v87
	v_med3_f32 v126, v127, v125, v87
	v_med3_f32 v124, v125, v123, v87
	v_med3_f32 v122, v123, v121, v87
	v_med3_f32 v119, v121, v118, v87
	v_med3_f32 v116, v118, v115, v87
	v_med3_f32 v113, v115, v112, v87
	v_med3_f32 v110, v112, v109, v87
	v_med3_f32 v107, v109, v106, v87
	v_med3_f32 v104, v106, v103, v87
	v_med3_f32 v0, v103, v0, v87
	v_or_b32_e32 v97, 0xd0, v97
	v_med3_f32 v137, v186, v136, v88
	v_med3_f32 v135, v136, v134, v88
	v_med3_f32 v131, v132, v130, v86
	v_med3_f32 v125, v126, v124, v88
	v_med3_f32 v123, v124, v122, v88
	v_med3_f32 v120, v122, v119, v88
	v_med3_f32 v117, v119, v116, v88
	v_med3_f32 v114, v116, v113, v88
	v_med3_f32 v111, v113, v110, v88
	v_med3_f32 v108, v110, v107, v88
	v_med3_f32 v105, v107, v104, v88
	v_med3_f32 v0, v104, v0, v88
	v_max_f32_e32 v99, v97, v97
	v_med3_f32 v138, v187, v137, v89
	v_med3_f32 v136, v137, v135, v89
	v_med3_f32 v132, v133, v131, v87
	v_med3_f32 v124, v125, v123, v89
	v_med3_f32 v121, v123, v120, v89
	v_med3_f32 v118, v120, v117, v89
	v_med3_f32 v115, v117, v114, v89
	v_med3_f32 v112, v114, v111, v89
	v_med3_f32 v109, v111, v108, v89
	v_med3_f32 v106, v108, v105, v89
	v_med3_f32 v0, v105, v0, v89
	v_max_f32_e32 v193, v192, v99
	v_add_f32_e32 v99, v28, v32
	v_med3_f32 v139, v188, v138, v90
	v_med3_f32 v137, v138, v136, v90
	v_med3_f32 v133, v134, v132, v88
	v_med3_f32 v122, v124, v121, v90
	v_med3_f32 v119, v121, v118, v90
	v_med3_f32 v116, v118, v115, v90
	v_med3_f32 v113, v115, v112, v90
	v_med3_f32 v110, v112, v109, v90
	v_med3_f32 v107, v109, v106, v90
	v_med3_f32 v0, v106, v0, v90
	v_and_b32_e32 v99, 0xffffff00, v99
	v_add_f32_e32 v48, v50, v32
	v_med3_f32 v140, v189, v139, v91
	v_med3_f32 v138, v139, v137, v91
	v_med3_f32 v134, v135, v133, v89
	v_med3_f32 v120, v122, v119, v91
	v_med3_f32 v117, v119, v116, v91
	v_med3_f32 v114, v116, v113, v91
	v_med3_f32 v111, v113, v110, v91
	v_med3_f32 v108, v110, v107, v91
	v_med3_f32 v0, v107, v0, v91
	v_or_b32_e32 v99, 0xe0, v99
	v_and_b32_e32 v48, 0xffffff00, v48
	v_med3_f32 v141, v190, v140, v92
	v_med3_f32 v139, v140, v138, v92
	v_med3_f32 v135, v136, v134, v90
	v_med3_f32 v118, v120, v117, v92
	v_med3_f32 v115, v117, v114, v92
	v_med3_f32 v112, v114, v111, v92
	v_med3_f32 v109, v111, v108, v92
	v_med3_f32 v0, v108, v0, v92
	v_max_f32_e32 v194, v99, v99
	v_or_b32_e32 v58, 0xf0, v48
	v_med3_f32 v142, v191, v141, v94
	v_med3_f32 v140, v141, v139, v94
	v_med3_f32 v136, v137, v135, v91
	v_med3_f32 v116, v118, v115, v94
	v_med3_f32 v113, v115, v112, v94
	v_med3_f32 v110, v112, v109, v94
	v_med3_f32 v0, v109, v0, v94
	v_max_f32_e32 v194, v193, v194
	v_max_f32_e32 v48, v58, v58
	v_med3_f32 v143, v192, v142, v97
	v_med3_f32 v141, v142, v140, v97
	v_med3_f32 v137, v138, v136, v92
	v_med3_f32 v129, v130, v128, v86
	v_med3_f32 v114, v116, v113, v97
	v_med3_f32 v111, v113, v110, v97
	v_med3_f32 v0, v110, v0, v97
	v_max_f32_e32 v48, v194, v48
	v_med3_f32 v144, v193, v143, v99
	v_med3_f32 v142, v143, v141, v99
	v_med3_f32 v138, v139, v137, v94
	v_med3_f32 v130, v131, v129, v87
	v_med3_f32 v112, v114, v111, v99
	v_med3_f32 v0, v111, v0, v99
	v_med3_f32 v49, v194, v144, v58
	v_med3_f32 v51, v144, v142, v58
	v_med3_f32 v139, v140, v138, v97
	v_med3_f32 v131, v132, v130, v88
	v_med3_f32 v128, v129, v127, v87
	v_med3_f32 v53, v112, v0, v58
	v_sub_f32_e32 v0, v48, v48
	v_med3_f32 v140, v141, v139, v99
	v_med3_f32 v132, v133, v131, v89
	v_med3_f32 v129, v130, v128, v88
	v_med3_f32 v127, v128, v126, v88
	v_mul_f32_e32 v0, 0x3fb8aa3b, v0
	v_sub_f32_e32 v1, v49, v48
	v_sub_f32_e32 v2, v51, v48
	v_med3_f32 v54, v142, v140, v58
	v_med3_f32 v133, v134, v132, v90
	v_med3_f32 v130, v131, v129, v89
	v_med3_f32 v128, v129, v127, v89
	v_exp_f32_e32 v0, v0
	v_mul_f32_e32 v1, 0x3fb8aa3b, v1
	v_mul_f32_e32 v2, 0x3fb8aa3b, v2
	v_med3_f32 v134, v135, v133, v91
	v_med3_f32 v131, v132, v130, v90
	v_med3_f32 v129, v130, v128, v90
	v_exp_f32_e32 v1, v1
	v_exp_f32_e32 v4, v2
	v_sub_f32_e32 v2, v54, v48
	v_med3_f32 v135, v136, v134, v92
	v_med3_f32 v132, v133, v131, v91
	v_med3_f32 v130, v131, v129, v91
	v_med3_f32 v126, v127, v125, v89
	v_mul_f32_e32 v2, 0x3fb8aa3b, v2
	v_med3_f32 v136, v137, v135, v94
	v_med3_f32 v133, v134, v132, v92
	v_med3_f32 v131, v132, v130, v92
	v_med3_f32 v127, v128, v126, v90
	v_exp_f32_e32 v5, v2
	v_lshlrev_b32_e32 v26, 8, v26
	v_lshlrev_b32_e32 v25, 8, v25
	v_med3_f32 v137, v138, v136, v97
	v_med3_f32 v134, v135, v133, v94
	v_med3_f32 v132, v133, v131, v94
	v_med3_f32 v128, v129, v127, v91
	v_add_f32_e32 v2, 0, v0
	v_and_b32_e32 v31, 0x7f, v31
	v_and_b32_e32 v30, 0x7f, v30
	v_and_b32_e32 v26, 0x7f00, v26
	v_and_b32_e32 v25, 0x7f00, v25
	v_lshlrev_b32_e32 v29, 16, v29
	v_lshlrev_b32_e32 v27, 16, v27
	v_med3_f32 v138, v139, v137, v99
	v_med3_f32 v135, v136, v134, v97
	v_med3_f32 v133, v134, v132, v97
	v_med3_f32 v129, v130, v128, v92
	v_add_f32_e32 v2, v1, v2
	v_or_b32_e32 v26, v26, v31
	v_or_b32_e32 v25, v25, v30
	v_and_b32_e32 v29, 0x7f0000, v29
	v_and_b32_e32 v27, 0x7f0000, v27
	v_lshlrev_b32_e32 v19, 24, v19
	v_lshlrev_b32_e32 v20, 24, v20
	v_med3_f32 v55, v140, v138, v58
	v_med3_f32 v136, v137, v135, v99
	v_med3_f32 v134, v135, v133, v99
	v_med3_f32 v130, v131, v129, v94
	v_add_f32_e32 v2, v4, v2
	v_or_b32_e32 v26, v26, v29
	v_or_b32_e32 v25, v25, v27
	v_and_b32_e32 v19, 0x7f000000, v19
	v_and_b32_e32 v20, 0x7f000000, v20
	v_lshlrev_b32_e32 v18, 8, v18
	v_med3_f32 v59, v138, v136, v58
	v_med3_f32 v60, v136, v134, v58
	v_med3_f32 v131, v132, v130, v97
	v_add_f32_e32 v6, v5, v2
	v_sub_f32_e32 v2, v55, v48
	v_or_b32_e32 v27, v26, v19
	v_or_b32_e32 v26, v25, v20
	v_and_b32_e32 v20, 0x7f, v23
	v_lshlrev_b32_e32 v21, 8, v21
	v_and_b32_e32 v18, 0x7f00, v18
	v_med3_f32 v132, v133, v131, v99
	v_mul_f32_e32 v2, 0x3fb8aa3b, v2
	v_sub_f32_e32 v3, v59, v48
	v_sub_f32_e32 v7, v60, v48
	v_and_b32_e32 v19, 0x7f, v24
	v_and_b32_e32 v21, 0x7f00, v21
	v_or_b32_e32 v18, v18, v20
	v_lshlrev_b32_e32 v20, 16, v28
	v_med3_f32 v61, v134, v132, v58
	v_med3_f32 v125, v126, v124, v90
	v_exp_f32_e32 v2, v2
	v_mul_f32_e32 v3, 0x3fb8aa3b, v3
	v_mul_f32_e32 v7, 0x3fb8aa3b, v7
	v_or_b32_e32 v19, v21, v19
	v_and_b32_e32 v20, 0x7f0000, v20
	v_med3_f32 v126, v127, v125, v91
	v_exp_f32_e32 v3, v3
	v_exp_f32_e32 v8, v7
	v_sub_f32_e32 v7, v61, v48
	v_lshlrev_b32_e32 v21, 16, v22
	v_or_b32_e32 v19, v19, v20
	v_lshlrev_b32_e32 v20, 24, v50
	v_med3_f32 v127, v128, v126, v92
	v_med3_f32 v123, v125, v122, v91
	v_mul_f32_e32 v7, 0x3fb8aa3b, v7
	v_and_b32_e32 v21, 0x7f0000, v21
	v_lshlrev_b32_e32 v17, 24, v17
	v_and_b32_e32 v20, 0x7f000000, v20
	v_med3_f32 v128, v129, v127, v94
	v_med3_f32 v124, v126, v123, v92
	v_med3_f32 v121, v123, v120, v92
	v_exp_f32_e32 v9, v7
	v_or_b32_e32 v18, v18, v21
	v_and_b32_e32 v17, 0x7f000000, v17
	v_or_b32_e32 v29, v19, v20
	v_lshlrev_b32_e32 v19, 8, v37
	v_lshlrev_b32_e32 v20, 8, v33
	v_med3_f32 v129, v130, v128, v97
	v_med3_f32 v125, v127, v124, v94
	v_med3_f32 v122, v124, v121, v94
	v_add_f32_e32 v6, v2, v6
	v_or_b32_e32 v28, v18, v17
	v_and_b32_e32 v17, 0x7f, v36
	v_and_b32_e32 v18, 0x7f, v32
	v_and_b32_e32 v19, 0x7f00, v19
	v_and_b32_e32 v20, 0x7f00, v20
	v_med3_f32 v130, v131, v129, v99
	v_med3_f32 v126, v128, v125, v97
	v_med3_f32 v123, v125, v122, v97
	v_add_f32_e32 v6, v3, v6
	v_or_b32_e32 v17, v19, v17
	v_or_b32_e32 v18, v20, v18
	v_lshlrev_b32_e32 v19, 16, v38
	v_lshlrev_b32_e32 v20, 16, v34
	v_med3_f32 v62, v132, v130, v58
	v_med3_f32 v127, v129, v126, v99
	v_med3_f32 v124, v126, v123, v99
	v_med3_f32 v119, v121, v118, v94
	v_add_f32_e32 v6, v8, v6
	v_and_b32_e32 v19, 0x7f0000, v19
	v_and_b32_e32 v20, 0x7f0000, v20
	v_med3_f32 v128, v130, v127, v58
	v_med3_f32 v125, v127, v124, v58
	v_med3_f32 v120, v122, v119, v97
	v_add_f32_e32 v10, v9, v6
	v_sub_f32_e32 v6, v62, v48
	v_or_b32_e32 v17, v17, v19
	v_or_b32_e32 v18, v18, v20
	v_lshlrev_b32_e32 v19, 24, v39
	v_lshlrev_b32_e32 v20, 24, v35
	v_med3_f32 v121, v123, v120, v99
	v_mul_f32_e32 v6, 0x3fb8aa3b, v6
	v_sub_f32_e32 v7, v128, v48
	v_sub_f32_e32 v11, v125, v48
	v_and_b32_e32 v19, 0x7f000000, v19
	v_and_b32_e32 v20, 0x7f000000, v20
	v_lshlrev_b32_e32 v21, 8, v45
	v_lshlrev_b32_e32 v22, 8, v41
	v_med3_f32 v122, v124, v121, v58
	v_exp_f32_e32 v6, v6
	v_mul_f32_e32 v7, 0x3fb8aa3b, v7
	v_mul_f32_e32 v11, 0x3fb8aa3b, v11
	v_or_b32_e32 v19, v17, v19
	v_or_b32_e32 v18, v18, v20
	v_and_b32_e32 v17, 0x7f, v44
	v_and_b32_e32 v20, 0x7f, v40
	v_and_b32_e32 v21, 0x7f00, v21
	v_and_b32_e32 v22, 0x7f00, v22
	v_exp_f32_e32 v7, v7
	v_exp_f32_e32 v12, v11
	v_sub_f32_e32 v11, v122, v48
	v_or_b32_e32 v17, v21, v17
	v_or_b32_e32 v20, v22, v20
	v_lshlrev_b32_e32 v21, 16, v46
	v_lshlrev_b32_e32 v22, 16, v42
	v_mul_f32_e32 v11, 0x3fb8aa3b, v11
	v_and_b32_e32 v21, 0x7f0000, v21
	v_and_b32_e32 v22, 0x7f0000, v22
	v_exp_f32_e32 v13, v11
	v_or_b32_e32 v17, v17, v21
	v_or_b32_e32 v20, v20, v22
	v_lshlrev_b32_e32 v21, 24, v47
	v_lshlrev_b32_e32 v22, 24, v43
	v_med3_f32 v117, v119, v116, v97
	v_add_f32_e32 v10, v6, v10
	v_and_b32_e32 v21, 0x7f000000, v21
	v_and_b32_e32 v22, 0x7f000000, v22
	v_med3_f32 v118, v120, v117, v99
	v_add_f32_e32 v10, v7, v10
	v_lshl_add_u32 v57, v57, 5, v162
	v_or_b32_e32 v21, v17, v21
	v_or_b32_e32 v20, v20, v22
	v_med3_f32 v119, v121, v118, v58
	v_med3_f32 v115, v117, v114, v99
	v_add_f32_e32 v10, v12, v10
	ds_write_b128 v57, v[18:21] offset:16
	v_lshrrev_b32_e32 v17, 4, v48
	v_lshrrev_b32_e32 v19, 4, v49
	v_lshrrev_b32_e32 v21, 4, v51
	v_lshrrev_b32_e32 v23, 4, v54
	v_med3_f32 v116, v118, v115, v58
	v_add_f32_e32 v16, v13, v10
	v_sub_f32_e32 v10, v119, v48
	v_and_or_b32 v17, v17, 15, v57
	v_and_or_b32 v18, v48, 15, v57
	v_and_or_b32 v19, v19, 15, v57
	v_and_or_b32 v20, v49, 15, v57
	v_and_or_b32 v21, v21, 15, v57
	v_and_or_b32 v22, v51, 15, v57
	v_and_or_b32 v23, v23, 15, v57
	v_and_or_b32 v24, v54, 15, v57
	v_med3_f32 v113, v115, v112, v58
	v_mul_f32_e32 v10, 0x3fb8aa3b, v10
	v_sub_f32_e32 v11, v116, v48
	ds_write_b128 v57, v[26:29]
	s_waitcnt lgkmcnt(0)
	ds_read_u8 v17, v17
	ds_read_u8 v18, v18 offset:16
	ds_read_u8 v19, v19
	ds_read_u8 v20, v20 offset:16
	ds_read_u8 v21, v21
	ds_read_u8 v22, v22 offset:16
	ds_read_u8 v23, v23
	ds_read_u8 v24, v24 offset:16
	v_exp_f32_e32 v10, v10
	v_mul_f32_e32 v11, 0x3fb8aa3b, v11
	v_sub_f32_e32 v14, v113, v48
	v_exp_f32_e32 v11, v11
	v_mul_f32_e32 v14, 0x3fb8aa3b, v14
	v_sub_f32_e32 v15, v53, v48
	s_waitcnt lgkmcnt(6)
	v_lshl_or_b32 v18, v17, 7, v18
	v_lshrrev_b32_e32 v17, 4, v55
	v_lshrrev_b32_e32 v26, 4, v60
	v_lshrrev_b32_e32 v28, 4, v61
	v_exp_f32_e32 v14, v14
	v_mul_f32_e32 v15, 0x3fb8aa3b, v15
	s_waitcnt lgkmcnt(4)
	v_lshl_or_b32 v19, v19, 7, v20
	s_waitcnt lgkmcnt(2)
	v_lshl_or_b32 v20, v21, 7, v22
	v_and_or_b32 v17, v17, 15, v57
	v_lshrrev_b32_e32 v22, 4, v59
	v_and_or_b32 v25, v59, 15, v57
	v_and_or_b32 v26, v26, 15, v57
	v_and_or_b32 v27, v60, 15, v57
	v_and_or_b32 v28, v28, 15, v57
	v_and_or_b32 v29, v61, 15, v57
	v_exp_f32_e32 v15, v15
	v_and_or_b32 v21, v55, 15, v57
	v_and_or_b32 v22, v22, 15, v57
	ds_read_u8 v17, v17
	ds_read_u8 v30, v21 offset:16
	ds_read_u8 v31, v22
	ds_read_u8 v25, v25 offset:16
	ds_read_u8 v26, v26
	ds_read_u8 v27, v27 offset:16
	ds_read_u8 v28, v28
	ds_read_u8 v29, v29 offset:16
	v_add_f32_e32 v16, v10, v16
	v_add_f32_e32 v16, v11, v16
	v_add_f32_e32 v16, v14, v16
	v_add_f32_e32 v16, v15, v16
	v_div_scale_f32 v58, s[30:31], v16, v16, 1.0
	s_waitcnt lgkmcnt(8)
	v_lshl_or_b32 v21, v23, 7, v24
	s_waitcnt lgkmcnt(6)
	v_lshl_or_b32 v22, v17, 7, v30
	s_waitcnt lgkmcnt(4)
	v_lshl_or_b32 v23, v31, 7, v25
	s_waitcnt lgkmcnt(2)
	v_lshl_or_b32 v24, v26, 7, v27
	s_waitcnt lgkmcnt(0)
	v_lshl_or_b32 v25, v28, 7, v29
	v_lshrrev_b32_e32 v17, 4, v62
	v_lshrrev_b32_e32 v27, 4, v128
	v_lshrrev_b32_e32 v29, 4, v125
	v_lshrrev_b32_e32 v31, 4, v122
	v_rcp_f32_e32 v63, v58
	v_and_or_b32 v17, v17, 15, v57
	v_and_or_b32 v26, v62, 15, v57
	v_and_or_b32 v27, v27, 15, v57
	v_and_or_b32 v28, v128, 15, v57
	v_and_or_b32 v29, v29, 15, v57
	v_and_or_b32 v30, v125, 15, v57
	v_and_or_b32 v31, v31, 15, v57
	v_and_or_b32 v32, v122, 15, v57
	ds_read_u8 v17, v17
	ds_read_u8 v26, v26 offset:16
	ds_read_u8 v27, v27
	ds_read_u8 v28, v28 offset:16
	ds_read_u8 v29, v29
	ds_read_u8 v30, v30 offset:16
	ds_read_u8 v31, v31
	ds_read_u8 v32, v32 offset:16
	s_waitcnt lgkmcnt(6)
	v_lshl_or_b32 v26, v17, 7, v26
	v_lshrrev_b32_e32 v17, 4, v119
	v_lshrrev_b32_e32 v34, 4, v113
	v_lshrrev_b32_e32 v36, 4, v53
	v_add_u32_e32 v52, s18, v56
	v_fma_f32 v56, -v58, v63, 1.0
	s_waitcnt lgkmcnt(4)
	v_lshl_or_b32 v27, v27, 7, v28
	s_waitcnt lgkmcnt(2)
	v_lshl_or_b32 v28, v29, 7, v30
	v_and_or_b32 v17, v17, 15, v57
	v_lshrrev_b32_e32 v30, 4, v116
	v_and_or_b32 v33, v116, 15, v57
	v_and_or_b32 v34, v34, 15, v57
	v_and_or_b32 v35, v113, 15, v57
	v_and_or_b32 v36, v36, 15, v57
	v_and_or_b32 v37, v53, 15, v57
	v_fmac_f32_e32 v63, v56, v63
	v_div_scale_f32 v56, vcc, 1.0, v16, 1.0
	v_and_or_b32 v29, v119, 15, v57
	v_and_or_b32 v30, v30, 15, v57
	ds_read_u8 v17, v17
	ds_read_u8 v38, v29 offset:16
	ds_read_u8 v39, v30
	ds_read_u8 v33, v33 offset:16
	ds_read_u8 v34, v34
	ds_read_u8 v35, v35 offset:16
	ds_read_u8 v36, v36
	ds_read_u8 v37, v37 offset:16
	v_mul_f32_e32 v64, v56, v63
	v_or_b32_e32 v52, v52, v163
	v_fma_f32 v65, -v58, v64, v56
	v_fmac_f32_e32 v64, v65, v63
	v_ashrrev_i32_e32 v53, 31, v52
	s_lshl_b32 s18, s28, 4
	v_fma_f32 v56, -v58, v64, v56
	s_waitcnt lgkmcnt(8)
	v_lshl_or_b32 v29, v31, 7, v32
	s_waitcnt lgkmcnt(2)
	v_lshl_or_b32 v32, v34, 7, v35
	v_lshlrev_b64 v[34:35], 9, v[52:53]
	s_ashr_i32 s19, s18, 31
	v_div_fmas_f32 v56, v56, v63, v64
	v_lshl_or_b32 v31, v39, 7, v33
	s_waitcnt lgkmcnt(0)
	v_lshl_or_b32 v33, v36, 7, v37
	v_lshl_add_u64 v[36:37], s[4:5], 0, v[34:35]
	s_lshl_b64 s[18:19], s[18:19], 2
	v_div_fixup_f32 v16, v56, v16, 1.0
	v_lshl_add_u64 v[36:37], v[36:37], 0, s[18:19]
	v_lshl_add_u64 v[34:35], s[6:7], 0, v[34:35]
	v_lshl_add_u64 v[34:35], v[34:35], 0, s[18:19]
	global_store_dwordx4 v[36:37], v[18:21], off
	v_lshl_or_b32 v30, v17, 7, v38
	s_nop 0
	v_pk_mul_f32 v[18:19], v[0:1], v[16:17] op_sel_hi:[1,0]
	v_pk_mul_f32 v[20:21], v[4:5], v[16:17] op_sel_hi:[1,0]
	v_pk_mul_f32 v[0:1], v[2:3], v[16:17] op_sel_hi:[1,0]
	v_pk_mul_f32 v[2:3], v[8:9], v[16:17] op_sel_hi:[1,0]
	global_store_dwordx4 v[34:35], v[18:21], off
	global_store_dwordx4 v[36:37], v[22:25], off offset:16
	global_store_dwordx4 v[34:35], v[0:3], off offset:16
	global_store_dwordx4 v[36:37], v[26:29], off offset:32
	s_nop 0
	v_pk_mul_f32 v[0:1], v[6:7], v[16:17] op_sel_hi:[1,0]
	v_pk_mul_f32 v[2:3], v[12:13], v[16:17] op_sel_hi:[1,0]
	global_store_dwordx4 v[34:35], v[0:3], off offset:32
	global_store_dwordx4 v[36:37], v[30:33], off offset:48
	s_nop 0
	v_pk_mul_f32 v[0:1], v[10:11], v[16:17] op_sel_hi:[1,0]
	v_pk_mul_f32 v[2:3], v[14:15], v[16:17] op_sel_hi:[1,0]
	global_store_dwordx4 v[34:35], v[0:3], off offset:48
	s_branch .LBB0_467

.LBB0_1059:
	v_mov_b32_e32 v144, v152
	s_barrier
	s_lshl_b32 s18, s28, 8
	v_and_b32_e32 v163, 31, v144
	v_ashrrev_i32_e32 v164, 1, v144
	v_and_or_b32 v147, v164, s22, v163
	v_add_u32_e32 v150, s18, v147
	v_ashrrev_i32_e32 v151, 31, v150
	v_or_b32_e32 v136, 32, v150
	v_lshlrev_b64 v[128:129], 5, v[150:151]
	v_ashrrev_i32_e32 v137, 31, v136
	v_lshl_add_u64 v[128:129], s[2:3], 0, v[128:129]
	v_lshlrev_b64 v[136:137], 5, v[136:137]
	global_load_dwordx4 v[132:135], v[128:129], off
	s_nop 0
	global_load_dwordx4 v[128:131], v[128:129], off offset:16
	v_lshl_add_u64 v[136:137], s[2:3], 0, v[136:137]
	global_load_dwordx4 v[140:143], v[136:137], off
	s_nop 0
	global_load_dwordx4 v[136:139], v[136:137], off offset:16
	v_or_b32_e32 v166, 64, v150
	v_or_b32_e32 v168, 0x60, v150
	v_ashrrev_i32_e32 v167, 31, v166
	v_ashrrev_i32_e32 v169, 31, v168
	v_lshlrev_b64 v[166:167], 5, v[166:167]
	v_lshlrev_b64 v[168:169], 5, v[168:169]
	v_lshl_add_u64 v[170:171], s[2:3], 0, v[166:167]
	v_lshl_add_u64 v[180:181], s[2:3], 0, v[168:169]
	global_load_dwordx4 v[166:169], v[170:171], off offset:16
	s_nop 0
	global_load_dwordx4 v[170:173], v[170:171], off
	s_nop 0
	global_load_dwordx4 v[174:177], v[180:181], off offset:16
	s_nop 0
	global_load_dwordx4 v[180:183], v[180:181], off
	v_mov_b64_e32 v[148:149], s[14:15]
	v_bfe_u32 v151, v144, 5, 1
	v_and_b32_e32 v146, 0xc0, v144
	v_lshlrev_b32_e32 v165, 3, v151
	v_lshl_or_b32 v146, v146, 1, v165
	v_mad_u64_u32 v[146:147], s[0:1], v147, s23, v[146:147]
	s_waitcnt vmcnt(7)
	v_mov_b32_e32 v184, v132
	s_waitcnt vmcnt(6)
	v_mov_b32_e32 v185, v128
	v_mov_b32_e32 v128, v133
	v_mov_b32_e32 v132, v134
	v_mov_b32_e32 v133, v130
	v_mov_b32_e32 v130, v135
	v_pk_add_f32 v[128:129], v[184:185], v[128:129]
	v_pk_add_f32 v[130:131], v[132:133], v[130:131]
	s_waitcnt vmcnt(5)
	v_mov_b32_e32 v132, v140
	s_waitcnt vmcnt(4)
	v_mov_b32_e32 v133, v136
	v_mov_b32_e32 v136, v141
	v_mov_b32_e32 v134, v142
	v_mov_b32_e32 v135, v138
	v_mov_b32_e32 v138, v143
	v_pk_add_f32 v[128:129], v[128:129], v[130:131]
	v_pk_add_f32 v[130:131], v[132:133], v[136:137]
	v_pk_add_f32 v[132:133], v[134:135], v[138:139]
	s_nop 0
	v_pk_add_f32 v[130:131], v[130:131], v[132:133]
	v_mov_b32_e32 v133, v128
	v_mov_b32_e32 v132, v130
	v_mov_b32_e32 v128, v131
	v_pk_add_f32 v[128:129], v[132:133], v[128:129]
	s_nop 0
	v_pk_fma_f32 v[128:129], v[128:129], s[12:13], v[148:149] op_sel_hi:[1,0,0]
	s_nop 0
	v_mul_f32_e32 v130, 0x4b800000, v129
	v_cmp_gt_f32_e32 vcc, s24, v129
	v_mul_f32_e32 v131, 0x4b800000, v128
	v_cmp_gt_f32_e64 s[0:1], s24, v128
	v_cndmask_b32_e32 v129, v129, v130, vcc
	v_rsq_f32_e32 v129, v129
	v_cndmask_b32_e64 v128, v128, v131, s[0:1]
	v_rsq_f32_e32 v130, v128
	v_mul_f32_e32 v128, 0x45800000, v129
	v_cndmask_b32_e32 v128, v129, v128, vcc
	v_pk_mul_f32 v[112:113], v[112:113], v[128:129] op_sel_hi:[1,0]
	v_pk_mul_f32 v[114:115], v[114:115], v[128:129] op_sel_hi:[1,0]
	v_pk_mul_f32 v[116:117], v[116:117], v[128:129] op_sel_hi:[1,0]
	v_pk_mul_f32 v[118:119], v[118:119], v[128:129] op_sel_hi:[1,0]
	v_pk_mul_f32 v[96:97], v[96:97], v[128:129] op_sel_hi:[1,0]
	v_pk_mul_f32 v[98:99], v[98:99], v[128:129] op_sel_hi:[1,0]
	v_pk_mul_f32 v[120:121], v[120:121], v[128:129] op_sel_hi:[1,0]
	v_pk_mul_f32 v[122:123], v[122:123], v[128:129] op_sel_hi:[1,0]
	v_pk_mul_f32 v[124:125], v[124:125], v[128:129] op_sel_hi:[1,0]
	v_pk_mul_f32 v[126:127], v[126:127], v[128:129] op_sel_hi:[1,0]
	v_pk_mul_f32 v[100:101], v[100:101], v[128:129] op_sel_hi:[1,0]
	v_pk_mul_f32 v[102:103], v[102:103], v[128:129] op_sel_hi:[1,0]
	v_cvt_pk_bf16_f32 v112, v112, v113
	v_cvt_pk_bf16_f32 v113, v114, v115
	v_cvt_pk_bf16_f32 v114, v116, v117
	v_cvt_pk_bf16_f32 v115, v118, v119
	v_cvt_pk_bf16_f32 v96, v96, v97
	v_cvt_pk_bf16_f32 v97, v98, v99
	v_cvt_pk_bf16_f32 v116, v120, v121
	v_cvt_pk_bf16_f32 v117, v122, v123
	v_cvt_pk_bf16_f32 v118, v124, v125
	v_cvt_pk_bf16_f32 v119, v126, v127
	v_cvt_pk_bf16_f32 v98, v100, v101
	v_cvt_pk_bf16_f32 v99, v102, v103
	ds_write2_b64 v146, v[112:113], v[114:115] offset1:2
	ds_write2_b64 v146, v[116:117], v[118:119] offset0:4 offset1:6
	ds_write2_b64 v146, v[96:97], v[98:99] offset0:8 offset1:10
	v_pk_mul_f32 v[96:97], v[110:111], v[128:129] op_sel_hi:[1,0]
	v_pk_mul_f32 v[104:105], v[104:105], v[128:129] op_sel_hi:[1,0]
	v_cvt_pk_bf16_f32 v103, v96, v97
	v_mul_f32_e32 v96, 0x45800000, v130
	v_cndmask_b32_e64 v96, v130, v96, s[0:1]
	v_pk_mul_f32 v[64:65], v[64:65], v[96:97] op_sel_hi:[1,0]
	v_pk_mul_f32 v[66:67], v[66:67], v[96:97] op_sel_hi:[1,0]
	v_cvt_pk_bf16_f32 v64, v64, v65
	v_cvt_pk_bf16_f32 v65, v66, v67
	v_pk_mul_f32 v[66:67], v[68:69], v[96:97] op_sel_hi:[1,0]
	v_pk_mul_f32 v[68:69], v[70:71], v[96:97] op_sel_hi:[1,0]
	v_pk_mul_f32 v[80:81], v[80:81], v[96:97] op_sel_hi:[1,0]
	v_pk_mul_f32 v[82:83], v[82:83], v[96:97] op_sel_hi:[1,0]
	v_cvt_pk_bf16_f32 v66, v66, v67
	v_cvt_pk_bf16_f32 v67, v68, v69
	s_waitcnt vmcnt(2)
	v_mov_b32_e32 v68, v170
	v_mov_b32_e32 v69, v166
	v_mov_b32_e32 v166, v171
	v_mov_b32_e32 v70, v172
	v_mov_b32_e32 v71, v168
	v_mov_b32_e32 v168, v173
	v_cvt_pk_bf16_f32 v80, v80, v81
	v_cvt_pk_bf16_f32 v81, v82, v83
	v_pk_mul_f32 v[82:83], v[84:85], v[96:97] op_sel_hi:[1,0]
	v_pk_mul_f32 v[84:85], v[86:87], v[96:97] op_sel_hi:[1,0]
	v_add_u32_e32 v86, 0x4000, v146
	v_pk_add_f32 v[68:69], v[68:69], v[166:167]
	v_pk_add_f32 v[70:71], v[70:71], v[168:169]
	ds_write2_b64 v86, v[64:65], v[66:67] offset0:72 offset1:74
	v_pk_mul_f32 v[64:65], v[72:73], v[96:97] op_sel_hi:[1,0]
	v_pk_add_f32 v[68:69], v[68:69], v[70:71]
	s_waitcnt vmcnt(0)
	v_mov_b32_e32 v70, v180
	v_mov_b32_e32 v71, v174
	v_mov_b32_e32 v174, v181
	v_mov_b32_e32 v72, v182
	v_mov_b32_e32 v73, v176
	v_mov_b32_e32 v176, v183
	v_pk_add_f32 v[70:71], v[70:71], v[174:175]
	v_pk_add_f32 v[72:73], v[72:73], v[176:177]
	v_pk_mul_f32 v[66:67], v[74:75], v[96:97] op_sel_hi:[1,0]
	v_pk_add_f32 v[70:71], v[70:71], v[72:73]
	v_mov_b32_e32 v73, v68
	v_mov_b32_e32 v72, v70
	v_mov_b32_e32 v68, v71
	v_pk_add_f32 v[68:69], v[72:73], v[68:69]
	v_cvt_pk_bf16_f32 v64, v64, v65
	v_cvt_pk_bf16_f32 v65, v66, v67
	v_pk_mul_f32 v[66:67], v[76:77], v[96:97] op_sel_hi:[1,0]
	v_pk_fma_f32 v[68:69], v[68:69], s[12:13], v[148:149] op_sel_hi:[1,0,0]
	v_cvt_pk_bf16_f32 v66, v66, v67
	v_mul_f32_e32 v67, 0x4b800000, v69
	v_cmp_gt_f32_e32 vcc, s24, v69
	v_pk_mul_f32 v[70:71], v[78:79], v[96:97] op_sel_hi:[1,0]
	v_cvt_pk_bf16_f32 v82, v82, v83
	v_cndmask_b32_e32 v67, v69, v67, vcc
	v_rsq_f32_e32 v69, v67
	v_cvt_pk_bf16_f32 v67, v70, v71
	ds_write2_b64 v86, v[64:65], v[66:67] offset0:76 offset1:78
	v_cvt_pk_bf16_f32 v83, v84, v85
	v_mul_f32_e32 v64, 0x45800000, v69
	v_cndmask_b32_e32 v64, v69, v64, vcc
	v_pk_mul_f32 v[32:33], v[32:33], v[64:65] op_sel_hi:[1,0]
	v_pk_mul_f32 v[34:35], v[34:35], v[64:65] op_sel_hi:[1,0]
	v_pk_mul_f32 v[48:49], v[48:49], v[64:65] op_sel_hi:[1,0]
	v_pk_mul_f32 v[50:51], v[50:51], v[64:65] op_sel_hi:[1,0]
	v_cvt_pk_bf16_f32 v32, v32, v33
	v_cvt_pk_bf16_f32 v33, v34, v35
	v_pk_mul_f32 v[34:35], v[36:37], v[64:65] op_sel_hi:[1,0]
	v_pk_mul_f32 v[36:37], v[38:39], v[64:65] op_sel_hi:[1,0]
	v_cvt_pk_bf16_f32 v48, v48, v49
	v_cvt_pk_bf16_f32 v49, v50, v51
	v_pk_mul_f32 v[50:51], v[52:53], v[64:65] op_sel_hi:[1,0]
	v_pk_mul_f32 v[52:53], v[54:55], v[64:65] op_sel_hi:[1,0]
	v_add_u32_e32 v54, 0x8000, v146
	v_cvt_pk_bf16_f32 v34, v34, v35
	v_cvt_pk_bf16_f32 v35, v36, v37
	ds_write2_b64 v54, v[32:33], v[34:35] offset0:136 offset1:138
	v_pk_mul_f32 v[32:33], v[40:41], v[64:65] op_sel_hi:[1,0]
	v_pk_mul_f32 v[34:35], v[42:43], v[64:65] op_sel_hi:[1,0]
	v_cvt_pk_bf16_f32 v32, v32, v33
	v_cvt_pk_bf16_f32 v33, v34, v35
	v_pk_mul_f32 v[34:35], v[44:45], v[64:65] op_sel_hi:[1,0]
	v_cmp_gt_f32_e32 vcc, s24, v68
	v_cvt_pk_bf16_f32 v34, v34, v35
	v_mul_f32_e32 v35, 0x4b800000, v68
	v_cndmask_b32_e32 v35, v68, v35, vcc
	v_rsq_f32_e32 v38, v35
	v_pk_mul_f32 v[36:37], v[46:47], v[64:65] op_sel_hi:[1,0]
	v_cvt_pk_bf16_f32 v50, v50, v51
	v_cvt_pk_bf16_f32 v35, v36, v37
	ds_write2_b64 v54, v[32:33], v[34:35] offset0:140 offset1:142
	v_mul_f32_e32 v32, 0x45800000, v38
	v_cndmask_b32_e32 v32, v38, v32, vcc
	v_pk_mul_f32 v[0:1], v[0:1], v[32:33] op_sel_hi:[1,0]
	v_pk_mul_f32 v[2:3], v[2:3], v[32:33] op_sel_hi:[1,0]
	v_pk_mul_f32 v[16:17], v[16:17], v[32:33] op_sel_hi:[1,0]
	v_pk_mul_f32 v[18:19], v[18:19], v[32:33] op_sel_hi:[1,0]
	v_cvt_pk_bf16_f32 v0, v0, v1
	v_cvt_pk_bf16_f32 v1, v2, v3
	v_pk_mul_f32 v[2:3], v[4:5], v[32:33] op_sel_hi:[1,0]
	v_pk_mul_f32 v[4:5], v[6:7], v[32:33] op_sel_hi:[1,0]
	v_cvt_pk_bf16_f32 v16, v16, v17
	v_cvt_pk_bf16_f32 v17, v18, v19
	v_pk_mul_f32 v[18:19], v[20:21], v[32:33] op_sel_hi:[1,0]
	v_pk_mul_f32 v[20:21], v[22:23], v[32:33] op_sel_hi:[1,0]
	v_add_u32_e32 v22, 0xc000, v146
	v_cvt_pk_bf16_f32 v2, v2, v3
	v_cvt_pk_bf16_f32 v3, v4, v5
	ds_write2_b64 v22, v[0:1], v[2:3] offset0:200 offset1:202
	v_pk_mul_f32 v[0:1], v[8:9], v[32:33] op_sel_hi:[1,0]
	v_pk_mul_f32 v[2:3], v[10:11], v[32:33] op_sel_hi:[1,0]
	v_cvt_pk_bf16_f32 v51, v52, v53
	v_cvt_pk_bf16_f32 v18, v18, v19
	v_cvt_pk_bf16_f32 v19, v20, v21
	v_cvt_pk_bf16_f32 v0, v0, v1
	v_cvt_pk_bf16_f32 v1, v2, v3
	v_pk_mul_f32 v[2:3], v[12:13], v[32:33] op_sel_hi:[1,0]
	v_pk_mul_f32 v[4:5], v[14:15], v[32:33] op_sel_hi:[1,0]
	ds_write2_b64 v86, v[80:81], v[82:83] offset0:64 offset1:66
	v_pk_mul_f32 v[80:81], v[88:89], v[96:97] op_sel_hi:[1,0]
	v_pk_mul_f32 v[82:83], v[90:91], v[96:97] op_sel_hi:[1,0]
	ds_write2_b64 v54, v[48:49], v[50:51] offset0:128 offset1:130
	v_pk_mul_f32 v[48:49], v[56:57], v[64:65] op_sel_hi:[1,0]
	v_pk_mul_f32 v[50:51], v[58:59], v[64:65] op_sel_hi:[1,0]
	ds_write2_b64 v22, v[16:17], v[18:19] offset0:192 offset1:194
	v_pk_mul_f32 v[16:17], v[24:25], v[32:33] op_sel_hi:[1,0]
	v_pk_mul_f32 v[18:19], v[26:27], v[32:33] op_sel_hi:[1,0]
	v_cvt_pk_bf16_f32 v2, v2, v3
	v_cvt_pk_bf16_f32 v3, v4, v5
	v_pk_mul_f32 v[106:107], v[106:107], v[128:129] op_sel_hi:[1,0]
	v_pk_mul_f32 v[108:109], v[108:109], v[128:129] op_sel_hi:[1,0]
	v_cvt_pk_bf16_f32 v80, v80, v81
	v_cvt_pk_bf16_f32 v81, v82, v83
	v_pk_mul_f32 v[82:83], v[92:93], v[96:97] op_sel_hi:[1,0]
	v_pk_mul_f32 v[84:85], v[94:95], v[96:97] op_sel_hi:[1,0]
	v_cvt_pk_bf16_f32 v48, v48, v49
	v_cvt_pk_bf16_f32 v49, v50, v51
	v_pk_mul_f32 v[50:51], v[60:61], v[64:65] op_sel_hi:[1,0]
	v_pk_mul_f32 v[52:53], v[62:63], v[64:65] op_sel_hi:[1,0]
	v_cvt_pk_bf16_f32 v16, v16, v17
	v_cvt_pk_bf16_f32 v17, v18, v19
	v_pk_mul_f32 v[18:19], v[28:29], v[32:33] op_sel_hi:[1,0]
	v_pk_mul_f32 v[20:21], v[30:31], v[32:33] op_sel_hi:[1,0]
	ds_write2_b64 v22, v[0:1], v[2:3] offset0:204 offset1:206
	v_bfi_b32 v57, s25, v164, v144
	v_lshlrev_b32_e32 v0, 4, v151
	v_cvt_pk_bf16_f32 v100, v104, v105
	v_cvt_pk_bf16_f32 v101, v106, v107
	v_cvt_pk_bf16_f32 v102, v108, v109
	v_cvt_pk_bf16_f32 v82, v82, v83
	v_cvt_pk_bf16_f32 v83, v84, v85
	v_cvt_pk_bf16_f32 v50, v50, v51
	v_cvt_pk_bf16_f32 v51, v52, v53
	v_cvt_pk_bf16_f32 v18, v18, v19
	v_cvt_pk_bf16_f32 v19, v20, v21
	v_mad_u64_u32 v[52:53], s[0:1], v57, s23, v[0:1]
	ds_write2_b64 v146, v[100:101], v[102:103] offset0:12 offset1:14
	ds_write2_b64 v86, v[80:81], v[82:83] offset0:68 offset1:70
	ds_write2_b64 v54, v[48:49], v[50:51] offset0:132 offset1:134
	ds_write2_b64 v22, v[16:17], v[18:19] offset0:196 offset1:198
	s_waitcnt lgkmcnt(0)
	s_barrier
	ds_read_b128 v[16:19], v52
	ds_read_b128 v[20:23], v52 offset:32
	ds_read_b128 v[24:27], v52 offset:64
	ds_read_b128 v[28:31], v52 offset:96
	ds_read_b128 v[32:35], v52 offset:128
	ds_read_b128 v[36:39], v52 offset:160
	ds_read_b128 v[40:43], v52 offset:192
	ds_read_b128 v[44:47], v52 offset:224
	v_lshl_or_b32 v144, v163, 8, v0
	v_and_b32_e32 v56, 0xffffffe0, v164
	v_lshlrev_b32_e32 v75, 2, v151
	v_lshl_add_u64 v[54:55], s[8:9], 0, v[144:145]
	v_mov_b32_e32 v58, 0xff800000
	s_mov_b32 s0, 0
	v_mov_b32_e32 v59, 0xff800000
	v_mov_b32_e32 v74, 0xff800000
	v_mov_b32_e32 v76, 0xff800000
	v_mov_b32_e32 v77, 0xff800000
	v_mov_b32_e32 v78, 0xff800000
	v_mov_b32_e32 v79, 0xff800000
	v_mov_b32_e32 v80, 0xff800000
	v_mov_b32_e32 v81, 0xff800000
	v_mov_b32_e32 v82, 0xff800000
	v_mov_b32_e32 v83, 0xff800000
	v_mov_b32_e32 v84, 0xff800000
	v_mov_b32_e32 v85, 0xff800000
	v_mov_b32_e32 v86, 0xff800000
	v_mov_b32_e32 v87, 0xff800000
	v_mov_b32_e32 v88, 0xff800000
	global_load_dwordx4 v[196:199], v[54:55], off offset:-128
	global_load_dwordx4 v[200:203], v[54:55], off offset:-96
	global_load_dwordx4 v[204:207], v[54:55], off offset:-64
	global_load_dwordx4 v[208:211], v[54:55], off offset:-32
	global_load_dwordx4 v[212:215], v[54:55], off
	global_load_dwordx4 v[216:219], v[54:55], off offset:32
	global_load_dwordx4 v[220:223], v[54:55], off offset:64
	global_load_dwordx4 v[224:227], v[54:55], off offset:96
	v_lshl_add_u64 v[54:55], v[54:55], 0, s[16:17]

.Lnl_q1b:
	s_nop 11
	v_and_b32_e32 v0, 0xffffff80, v0
	v_and_b32_e32 v1, 0xffffff80, v1
	v_add_u32_e32 v0, v105, v0
	v_and_b32_e32 v2, 0xffffff80, v2
	v_add3_u32 v1, v105, v1, 1
	v_med3_f32 v48, v89, v90, v0
	v_med3_f32 v49, v91, v89, v0
	v_med3_f32 v50, v92, v91, v0
	v_med3_f32 v51, v93, v92, v0
	v_med3_f32 v89, v94, v93, v0
	v_med3_f32 v90, v95, v94, v0
	v_med3_f32 v91, v96, v95, v0
	v_med3_f32 v92, v97, v96, v0
	v_med3_f32 v93, v98, v97, v0
	v_med3_f32 v94, v99, v98, v0
	v_med3_f32 v95, v100, v99, v0
	v_med3_f32 v96, v101, v100, v0
	v_med3_f32 v97, v102, v101, v0
	v_med3_f32 v98, v103, v102, v0
	v_med3_f32 v99, v104, v103, v0
	v_max_f32_e32 v0, v0, v0
	v_and_b32_e32 v3, 0xffffff80, v3
	v_add3_u32 v2, v105, v2, 2
	v_max_f32_e32 v100, v1, v1
	v_max_f32_e32 v0, v106, v0
	v_and_b32_e32 v4, 0xffffff80, v4
	v_add3_u32 v3, v105, v3, 3
	v_max_f32_e32 v101, v2, v2
	v_med3_f32 v48, v49, v48, v1
	v_med3_f32 v49, v50, v49, v1
	v_med3_f32 v50, v51, v50, v1
	v_med3_f32 v51, v89, v51, v1
	v_med3_f32 v89, v90, v89, v1
	v_med3_f32 v90, v91, v90, v1
	v_med3_f32 v91, v92, v91, v1
	v_med3_f32 v92, v93, v92, v1
	v_med3_f32 v93, v94, v93, v1
	v_med3_f32 v94, v95, v94, v1
	v_med3_f32 v95, v96, v95, v1
	v_med3_f32 v96, v97, v96, v1
	v_med3_f32 v97, v98, v97, v1
	v_med3_f32 v98, v99, v98, v1
	v_med3_f32 v1, v0, v99, v1
	v_max_f32_e32 v0, v0, v100
	v_and_b32_e32 v5, 0xffffff80, v5
	v_add3_u32 v4, v105, v4, 8
	v_max_f32_e32 v102, v3, v3
	v_med3_f32 v48, v49, v48, v2
	v_med3_f32 v49, v50, v49, v2
	v_med3_f32 v50, v51, v50, v2
	v_med3_f32 v51, v89, v51, v2
	v_med3_f32 v89, v90, v89, v2
	v_med3_f32 v90, v91, v90, v2
	v_med3_f32 v91, v92, v91, v2
	v_med3_f32 v92, v93, v92, v2
	v_med3_f32 v93, v94, v93, v2
	v_med3_f32 v94, v95, v94, v2
	v_med3_f32 v95, v96, v95, v2
	v_med3_f32 v96, v97, v96, v2
	v_med3_f32 v97, v98, v97, v2
	v_med3_f32 v98, v1, v98, v2
	v_med3_f32 v1, v0, v1, v2
	v_max_f32_e32 v0, v0, v101
	v_and_b32_e32 v6, 0xffffff80, v6
	v_add3_u32 v5, v105, v5, 9
	v_max_f32_e32 v103, v4, v4
	v_med3_f32 v2, v49, v48, v3
	v_med3_f32 v48, v50, v49, v3
	v_med3_f32 v49, v51, v50, v3
	v_med3_f32 v50, v89, v51, v3
	v_med3_f32 v51, v90, v89, v3
	v_med3_f32 v89, v91, v90, v3
	v_med3_f32 v90, v92, v91, v3
	v_med3_f32 v91, v93, v92, v3
	v_med3_f32 v92, v94, v93, v3
	v_med3_f32 v93, v95, v94, v3
	v_med3_f32 v94, v96, v95, v3
	v_med3_f32 v95, v97, v96, v3
	v_med3_f32 v96, v98, v97, v3
	v_med3_f32 v97, v1, v98, v3
	v_med3_f32 v1, v0, v1, v3
	v_max_f32_e32 v0, v0, v102
	v_and_b32_e32 v7, 0xffffff80, v7
	v_and_b32_e32 v8, 0xffffff80, v8
	v_and_b32_e32 v9, 0xffffff80, v9
	v_and_b32_e32 v10, 0xffffff80, v10
	v_and_b32_e32 v11, 0xffffff80, v11
	v_and_b32_e32 v12, 0xffffff80, v12
	v_and_b32_e32 v13, 0xffffff80, v13
	v_and_b32_e32 v14, 0xffffff80, v14
	v_and_b32_e32 v15, 0xffffff80, v15
	v_add3_u32 v6, v105, v6, 10
	v_max_f32_e32 v104, v5, v5
	v_med3_f32 v2, v48, v2, v4
	v_med3_f32 v3, v49, v48, v4
	v_med3_f32 v48, v50, v49, v4
	v_med3_f32 v49, v51, v50, v4
	v_med3_f32 v50, v89, v51, v4
	v_med3_f32 v51, v90, v89, v4
	v_med3_f32 v89, v91, v90, v4
	v_med3_f32 v90, v92, v91, v4
	v_med3_f32 v91, v93, v92, v4
	v_med3_f32 v92, v94, v93, v4
	v_med3_f32 v93, v95, v94, v4
	v_med3_f32 v94, v96, v95, v4
	v_med3_f32 v95, v97, v96, v4
	v_med3_f32 v96, v1, v97, v4
	v_med3_f32 v1, v0, v1, v4
	v_max_f32_e32 v0, v0, v103
	v_add3_u32 v7, v105, v7, 11
	v_add3_u32 v8, v105, v8, 16
	v_add3_u32 v9, v105, v9, 17
	v_add3_u32 v10, v105, v10, 18
	v_add3_u32 v11, v105, v11, 19
	v_add3_u32 v12, v105, v12, 24
	v_add3_u32 v13, v105, v13, 25
	v_add3_u32 v14, v105, v14, 26
	v_add3_u32 v15, v105, v15, 27
	v_max_f32_e32 v105, v6, v6
	v_med3_f32 v2, v3, v2, v5
	v_med3_f32 v3, v48, v3, v5
	v_med3_f32 v4, v49, v48, v5
	v_med3_f32 v48, v50, v49, v5
	v_med3_f32 v49, v51, v50, v5
	v_med3_f32 v50, v89, v51, v5
	v_med3_f32 v51, v90, v89, v5
	v_med3_f32 v89, v91, v90, v5
	v_med3_f32 v90, v92, v91, v5
	v_med3_f32 v91, v93, v92, v5
	v_med3_f32 v92, v94, v93, v5
	v_med3_f32 v93, v95, v94, v5
	v_med3_f32 v94, v96, v95, v5
	v_med3_f32 v95, v1, v96, v5
	v_med3_f32 v1, v0, v1, v5
	v_max_f32_e32 v0, v0, v104
	v_max_f32_e32 v107, v7, v7
	v_med3_f32 v2, v3, v2, v6
	v_med3_f32 v3, v4, v3, v6
	v_med3_f32 v4, v48, v4, v6
	v_med3_f32 v5, v49, v48, v6
	v_med3_f32 v48, v50, v49, v6
	v_med3_f32 v49, v51, v50, v6
	v_med3_f32 v50, v89, v51, v6
	v_med3_f32 v51, v90, v89, v6
	v_med3_f32 v89, v91, v90, v6
	v_med3_f32 v90, v92, v91, v6
	v_med3_f32 v91, v93, v92, v6
	v_med3_f32 v92, v94, v93, v6
	v_med3_f32 v93, v95, v94, v6
	v_med3_f32 v94, v1, v95, v6
	v_med3_f32 v1, v0, v1, v6
	v_max_f32_e32 v0, v0, v105
	v_max_f32_e32 v108, v8, v8
	v_med3_f32 v2, v3, v2, v7
	v_med3_f32 v3, v4, v3, v7
	v_med3_f32 v4, v5, v4, v7
	v_med3_f32 v5, v48, v5, v7
	v_med3_f32 v6, v49, v48, v7
	v_med3_f32 v48, v50, v49, v7
	v_med3_f32 v49, v51, v50, v7
	v_med3_f32 v50, v89, v51, v7
	v_med3_f32 v51, v90, v89, v7
	v_med3_f32 v89, v91, v90, v7
	v_med3_f32 v90, v92, v91, v7
	v_med3_f32 v91, v93, v92, v7
	v_med3_f32 v92, v94, v93, v7
	v_med3_f32 v93, v1, v94, v7
	v_med3_f32 v1, v0, v1, v7
	v_max_f32_e32 v0, v0, v107
	v_max_f32_e32 v109, v9, v9
	v_med3_f32 v2, v3, v2, v8
	v_med3_f32 v3, v4, v3, v8
	v_med3_f32 v4, v5, v4, v8
	v_med3_f32 v5, v6, v5, v8
	v_med3_f32 v6, v48, v6, v8
	v_med3_f32 v7, v49, v48, v8
	v_med3_f32 v48, v50, v49, v8
	v_med3_f32 v49, v51, v50, v8
	v_med3_f32 v50, v89, v51, v8
	v_med3_f32 v51, v90, v89, v8
	v_med3_f32 v89, v91, v90, v8
	v_med3_f32 v90, v92, v91, v8
	v_med3_f32 v91, v93, v92, v8
	v_med3_f32 v92, v1, v93, v8
	v_med3_f32 v1, v0, v1, v8
	v_max_f32_e32 v0, v0, v108
	v_max_f32_e32 v110, v10, v10
	v_med3_f32 v2, v3, v2, v9
	v_med3_f32 v3, v4, v3, v9
	v_med3_f32 v4, v5, v4, v9
	v_med3_f32 v5, v6, v5, v9
	v_med3_f32 v6, v7, v6, v9
	v_med3_f32 v7, v48, v7, v9
	v_med3_f32 v8, v49, v48, v9
	v_med3_f32 v48, v50, v49, v9
	v_med3_f32 v49, v51, v50, v9
	v_med3_f32 v50, v89, v51, v9
	v_med3_f32 v51, v90, v89, v9
	v_med3_f32 v89, v91, v90, v9
	v_med3_f32 v90, v92, v91, v9
	v_med3_f32 v91, v1, v92, v9
	v_med3_f32 v1, v0, v1, v9
	v_max_f32_e32 v0, v0, v109
	v_max_f32_e32 v111, v11, v11
	v_med3_f32 v2, v3, v2, v10
	v_med3_f32 v3, v4, v3, v10
	v_med3_f32 v4, v5, v4, v10
	v_med3_f32 v5, v6, v5, v10
	v_med3_f32 v6, v7, v6, v10
	v_med3_f32 v7, v8, v7, v10
	v_med3_f32 v8, v48, v8, v10
	v_med3_f32 v9, v49, v48, v10
	v_med3_f32 v48, v50, v49, v10
	v_med3_f32 v49, v51, v50, v10
	v_med3_f32 v50, v89, v51, v10
	v_med3_f32 v51, v90, v89, v10
	v_med3_f32 v89, v91, v90, v10
	v_med3_f32 v90, v1, v91, v10
	v_med3_f32 v1, v0, v1, v10
	v_max_f32_e32 v0, v0, v110
	v_max_f32_e32 v112, v12, v12
	v_med3_f32 v2, v3, v2, v11
	v_med3_f32 v3, v4, v3, v11
	v_med3_f32 v4, v5, v4, v11
	v_med3_f32 v5, v6, v5, v11
	v_med3_f32 v6, v7, v6, v11
	v_med3_f32 v7, v8, v7, v11
	v_med3_f32 v8, v9, v8, v11
	v_med3_f32 v9, v48, v9, v11
	v_med3_f32 v10, v49, v48, v11
	v_med3_f32 v48, v50, v49, v11
	v_med3_f32 v49, v51, v50, v11
	v_med3_f32 v50, v89, v51, v11
	v_med3_f32 v51, v90, v89, v11
	v_med3_f32 v89, v1, v90, v11
	v_med3_f32 v1, v0, v1, v11
	v_max_f32_e32 v0, v0, v111
	v_max_f32_e32 v113, v13, v13
	v_med3_f32 v2, v3, v2, v12
	v_med3_f32 v3, v4, v3, v12
	v_med3_f32 v4, v5, v4, v12
	v_med3_f32 v5, v6, v5, v12
	v_med3_f32 v6, v7, v6, v12
	v_med3_f32 v7, v8, v7, v12
	v_med3_f32 v8, v9, v8, v12
	v_med3_f32 v9, v10, v9, v12
	v_med3_f32 v10, v48, v10, v12
	v_med3_f32 v11, v49, v48, v12
	v_med3_f32 v48, v50, v49, v12
	v_med3_f32 v49, v51, v50, v12
	v_med3_f32 v50, v89, v51, v12
	v_med3_f32 v51, v1, v89, v12
	v_med3_f32 v1, v0, v1, v12
	v_max_f32_e32 v0, v0, v112
	v_max_f32_e32 v114, v14, v14
	v_med3_f32 v2, v3, v2, v13
	v_med3_f32 v3, v4, v3, v13
	v_med3_f32 v4, v5, v4, v13
	v_med3_f32 v5, v6, v5, v13
	v_med3_f32 v6, v7, v6, v13
	v_med3_f32 v7, v8, v7, v13
	v_med3_f32 v8, v9, v8, v13
	v_med3_f32 v9, v10, v9, v13
	v_med3_f32 v10, v11, v10, v13
	v_med3_f32 v11, v48, v11, v13
	v_med3_f32 v12, v49, v48, v13
	v_med3_f32 v48, v50, v49, v13
	v_med3_f32 v49, v51, v50, v13
	v_med3_f32 v50, v1, v51, v13
	v_med3_f32 v1, v0, v1, v13
	v_max_f32_e32 v0, v0, v113
	v_max_f32_e32 v115, v15, v15
	v_med3_f32 v2, v3, v2, v14
	v_med3_f32 v3, v4, v3, v14
	v_med3_f32 v4, v5, v4, v14
	v_med3_f32 v5, v6, v5, v14
	v_med3_f32 v6, v7, v6, v14
	v_med3_f32 v7, v8, v7, v14
	v_med3_f32 v8, v9, v8, v14
	v_med3_f32 v9, v10, v9, v14
	v_med3_f32 v10, v11, v10, v14
	v_med3_f32 v11, v12, v11, v14
	v_med3_f32 v12, v48, v12, v14
	v_med3_f32 v13, v49, v48, v14
	v_med3_f32 v48, v50, v49, v14
	v_med3_f32 v49, v1, v50, v14
	v_med3_f32 v1, v0, v1, v14
	v_max_f32_e32 v0, v0, v114
	v_med3_f32 v90, v3, v2, v15
	v_med3_f32 v89, v4, v3, v15
	v_med3_f32 v91, v5, v4, v15
	v_med3_f32 v92, v6, v5, v15
	v_med3_f32 v93, v7, v6, v15
	v_med3_f32 v94, v8, v7, v15
	v_med3_f32 v95, v9, v8, v15
	v_med3_f32 v96, v10, v9, v15
	v_med3_f32 v97, v11, v10, v15
	v_med3_f32 v98, v12, v11, v15
	v_med3_f32 v99, v13, v12, v15
	v_med3_f32 v100, v48, v13, v15
	v_med3_f32 v101, v49, v48, v15
	v_med3_f32 v102, v1, v49, v15
	v_med3_f32 v103, v0, v1, v15
	v_max_f32_e32 v104, v0, v115
	s_cbranch_scc1 .LBB0_1062
	ds_bpermute_b32 v0, v161, v104
	ds_bpermute_b32 v1, v161, v103
	ds_bpermute_b32 v2, v161, v102
	ds_bpermute_b32 v3, v161, v101
	ds_bpermute_b32 v4, v161, v100
	ds_bpermute_b32 v5, v161, v99
	ds_bpermute_b32 v7, v161, v98
	ds_bpermute_b32 v8, v161, v97
	ds_bpermute_b32 v9, v161, v96
	ds_bpermute_b32 v10, v161, v95
	ds_bpermute_b32 v11, v161, v94
	ds_bpermute_b32 v12, v161, v93
	ds_bpermute_b32 v14, v161, v92
	ds_bpermute_b32 v15, v161, v91
	ds_bpermute_b32 v16, v161, v89
	ds_bpermute_b32 v47, v161, v90
	v_cmp_eq_u32_e32 vcc, 0, v151
	s_and_saveexec_b64 s[0:1], vcc
	s_cbranch_execz .LBB0_1052
	v_max_f32_e32 v28, v54, v54
	v_max_f32_e32 v29, v88, v88
	v_med3_f32 v6, v76, v74, v54
	v_med3_f32 v13, v77, v76, v54
	v_med3_f32 v17, v78, v77, v54
	v_med3_f32 v18, v79, v78, v54
	v_med3_f32 v19, v80, v79, v54
	v_med3_f32 v20, v81, v80, v54
	v_med3_f32 v21, v82, v81, v54
	v_med3_f32 v22, v83, v82, v54
	v_med3_f32 v23, v84, v83, v54
	v_med3_f32 v24, v85, v84, v54
	v_med3_f32 v25, v86, v85, v54
	v_med3_f32 v26, v87, v86, v54
	v_med3_f32 v27, v88, v87, v54
	v_max_f32_e32 v28, v29, v28
	v_max_f32_e32 v29, v55, v55
	v_med3_f32 v32, v13, v6, v55
	v_med3_f32 v13, v17, v13, v55
	v_med3_f32 v17, v18, v17, v55
	v_med3_f32 v18, v19, v18, v55
	v_med3_f32 v19, v20, v19, v55
	v_med3_f32 v20, v21, v20, v55
	v_med3_f32 v21, v22, v21, v55
	v_med3_f32 v22, v23, v22, v55
	v_med3_f32 v23, v24, v23, v55
	v_med3_f32 v24, v25, v24, v55
	v_med3_f32 v25, v26, v25, v55
	v_med3_f32 v26, v27, v26, v55
	v_med3_f32 v27, v28, v27, v55
	v_max_f32_e32 v28, v28, v29
	s_waitcnt lgkmcnt(14)
	v_max_f32_e32 v29, v60, v60
	v_med3_f32 v33, v13, v32, v60
	v_med3_f32 v13, v17, v13, v60
	v_med3_f32 v17, v18, v17, v60
	v_med3_f32 v18, v19, v18, v60
	v_med3_f32 v19, v20, v19, v60
	v_med3_f32 v20, v21, v20, v60
	v_med3_f32 v21, v22, v21, v60
	v_med3_f32 v22, v23, v22, v60
	v_med3_f32 v23, v24, v23, v60
	v_med3_f32 v24, v25, v24, v60
	v_med3_f32 v25, v26, v25, v60
	v_med3_f32 v26, v27, v26, v60
	v_med3_f32 v27, v28, v27, v60
	v_max_f32_e32 v28, v28, v29
	v_max_f32_e32 v29, v61, v61
	v_med3_f32 v34, v13, v33, v61
	v_med3_f32 v13, v17, v13, v61
	v_med3_f32 v17, v18, v17, v61
	v_med3_f32 v18, v19, v18, v61
	v_med3_f32 v19, v20, v19, v61
	v_med3_f32 v20, v21, v20, v61
	v_med3_f32 v21, v22, v21, v61
	v_med3_f32 v22, v23, v22, v61
	v_med3_f32 v23, v24, v23, v61
	v_med3_f32 v24, v25, v24, v61
	v_med3_f32 v25, v26, v25, v61
	v_med3_f32 v26, v27, v26, v61
	v_med3_f32 v27, v28, v27, v61
	v_max_f32_e32 v28, v28, v29
	v_max_f32_e32 v29, v62, v62
	v_med3_f32 v35, v13, v34, v62
	v_med3_f32 v13, v17, v13, v62
	v_med3_f32 v17, v18, v17, v62
	v_med3_f32 v18, v19, v18, v62
	v_med3_f32 v19, v20, v19, v62
	v_med3_f32 v20, v21, v20, v62
	v_med3_f32 v21, v22, v21, v62
	v_med3_f32 v22, v23, v22, v62
	v_med3_f32 v23, v24, v23, v62
	v_med3_f32 v24, v25, v24, v62
	v_med3_f32 v25, v26, v25, v62
	v_med3_f32 v26, v27, v26, v62
	v_med3_f32 v27, v28, v27, v62
	v_max_f32_e32 v28, v28, v29
	v_max_f32_e32 v29, v63, v63
	v_med3_f32 v36, v13, v35, v63
	v_med3_f32 v13, v17, v13, v63
	v_med3_f32 v17, v18, v17, v63
	v_med3_f32 v18, v19, v18, v63
	v_med3_f32 v19, v20, v19, v63
	v_med3_f32 v20, v21, v20, v63
	v_med3_f32 v21, v22, v21, v63
	v_med3_f32 v22, v23, v22, v63
	v_med3_f32 v23, v24, v23, v63
	v_med3_f32 v24, v25, v24, v63
	v_med3_f32 v25, v26, v25, v63
	v_med3_f32 v26, v27, v26, v63
	v_med3_f32 v27, v28, v27, v63
	v_max_f32_e32 v28, v28, v29
	v_max_f32_e32 v29, v64, v64
	v_med3_f32 v37, v13, v36, v64
	v_med3_f32 v13, v17, v13, v64
	v_med3_f32 v17, v18, v17, v64
	v_med3_f32 v18, v19, v18, v64
	v_med3_f32 v19, v20, v19, v64
	v_med3_f32 v20, v21, v20, v64
	v_med3_f32 v21, v22, v21, v64
	v_med3_f32 v22, v23, v22, v64
	v_med3_f32 v23, v24, v23, v64
	v_med3_f32 v24, v25, v24, v64
	v_med3_f32 v25, v26, v25, v64
	v_med3_f32 v26, v27, v26, v64
	v_med3_f32 v27, v28, v27, v64
	v_max_f32_e32 v28, v28, v29
	v_max_f32_e32 v29, v65, v65
	v_med3_f32 v38, v13, v37, v65
	v_med3_f32 v13, v17, v13, v65
	v_med3_f32 v17, v18, v17, v65
	v_med3_f32 v18, v19, v18, v65
	v_med3_f32 v19, v20, v19, v65
	v_med3_f32 v20, v21, v20, v65
	v_med3_f32 v21, v22, v21, v65
	v_med3_f32 v22, v23, v22, v65
	v_med3_f32 v23, v24, v23, v65
	v_med3_f32 v24, v25, v24, v65
	v_med3_f32 v25, v26, v25, v65
	v_med3_f32 v26, v27, v26, v65
	v_med3_f32 v27, v28, v27, v65
	v_max_f32_e32 v28, v28, v29
	v_max_f32_e32 v29, v66, v66
	v_med3_f32 v39, v13, v38, v66
	v_med3_f32 v13, v17, v13, v66
	v_med3_f32 v17, v18, v17, v66
	v_med3_f32 v18, v19, v18, v66
	v_med3_f32 v19, v20, v19, v66
	v_med3_f32 v20, v21, v20, v66
	v_med3_f32 v21, v22, v21, v66
	v_med3_f32 v22, v23, v22, v66
	v_med3_f32 v23, v24, v23, v66
	v_med3_f32 v24, v25, v24, v66
	v_med3_f32 v25, v26, v25, v66
	v_med3_f32 v26, v27, v26, v66
	v_med3_f32 v27, v28, v27, v66
	v_max_f32_e32 v28, v28, v29
	v_max_f32_e32 v29, v67, v67
	v_med3_f32 v40, v13, v39, v67
	v_med3_f32 v13, v17, v13, v67
	v_med3_f32 v17, v18, v17, v67
	v_med3_f32 v18, v19, v18, v67
	v_med3_f32 v19, v20, v19, v67
	v_med3_f32 v20, v21, v20, v67
	v_med3_f32 v21, v22, v21, v67
	v_med3_f32 v22, v23, v22, v67
	v_med3_f32 v23, v24, v23, v67
	v_med3_f32 v24, v25, v24, v67
	v_med3_f32 v25, v26, v25, v67
	v_med3_f32 v26, v27, v26, v67
	v_med3_f32 v27, v28, v27, v67
	v_max_f32_e32 v28, v28, v29
	v_max_f32_e32 v29, v68, v68
	v_med3_f32 v41, v13, v40, v68
	v_med3_f32 v13, v17, v13, v68
	v_med3_f32 v17, v18, v17, v68
	v_med3_f32 v18, v19, v18, v68
	v_med3_f32 v19, v20, v19, v68
	v_med3_f32 v20, v21, v20, v68
	v_med3_f32 v21, v22, v21, v68
	v_med3_f32 v22, v23, v22, v68
	v_med3_f32 v23, v24, v23, v68
	v_med3_f32 v24, v25, v24, v68
	v_med3_f32 v25, v26, v25, v68
	v_med3_f32 v26, v27, v26, v68
	v_med3_f32 v27, v28, v27, v68
	v_max_f32_e32 v28, v28, v29
	v_max_f32_e32 v29, v69, v69
	v_med3_f32 v42, v13, v41, v69
	v_med3_f32 v13, v17, v13, v69
	v_med3_f32 v17, v18, v17, v69
	v_med3_f32 v18, v19, v18, v69
	v_med3_f32 v19, v20, v19, v69
	v_med3_f32 v20, v21, v20, v69
	v_med3_f32 v21, v22, v21, v69
	v_med3_f32 v22, v23, v22, v69
	v_med3_f32 v23, v24, v23, v69
	v_med3_f32 v24, v25, v24, v69
	v_med3_f32 v25, v26, v25, v69
	v_med3_f32 v26, v27, v26, v69
	v_med3_f32 v27, v28, v27, v69
	v_max_f32_e32 v28, v28, v29
	v_max_f32_e32 v29, v70, v70
	v_med3_f32 v43, v13, v42, v70
	v_med3_f32 v13, v17, v13, v70
	v_med3_f32 v17, v18, v17, v70
	v_med3_f32 v18, v19, v18, v70
	v_med3_f32 v19, v20, v19, v70
	v_med3_f32 v20, v21, v20, v70
	v_med3_f32 v21, v22, v21, v70
	v_med3_f32 v22, v23, v22, v70
	v_med3_f32 v23, v24, v23, v70
	v_med3_f32 v24, v25, v24, v70
	v_med3_f32 v25, v26, v25, v70
	v_med3_f32 v26, v27, v26, v70
	v_med3_f32 v27, v28, v27, v70
	v_max_f32_e32 v28, v28, v29
	v_med3_f32 v44, v13, v43, v71
	v_med3_f32 v13, v17, v13, v71
	v_med3_f32 v29, v18, v17, v71
	v_med3_f32 v17, v19, v18, v71
	v_med3_f32 v18, v20, v19, v71
	v_med3_f32 v30, v21, v20, v71
	v_med3_f32 v21, v22, v21, v71
	v_med3_f32 v19, v23, v22, v71
	v_med3_f32 v20, v24, v23, v71
	v_med3_f32 v22, v25, v24, v71
	v_med3_f32 v23, v26, v25, v71
	v_med3_f32 v24, v27, v26, v71
	v_med3_f32 v25, v28, v27, v71
	v_max_f32_e32 v26, v71, v71
	v_max_f32_e32 v26, v28, v26
	v_med3_f32 v45, v17, v29, v72
	v_med3_f32 v46, v18, v17, v72
	v_med3_f32 v48, v30, v18, v72
	v_med3_f32 v51, v22, v20, v72
	v_med3_f32 v31, v24, v23, v72
	v_med3_f32 v24, v25, v24, v72
	v_max_f32_e32 v17, v72, v72
	v_med3_f32 v22, v23, v22, v72
	v_med3_f32 v23, v21, v30, v72
	v_med3_f32 v28, v13, v44, v72
	v_med3_f32 v49, v19, v21, v72
	v_med3_f32 v50, v20, v19, v72
	v_max_f32_e32 v27, v26, v17
	v_med3_f32 v20, v24, v31, v73
	v_med3_f32 v52, v26, v25, v72
	v_med3_f32 v26, v22, v51, v73
	v_med3_f32 v18, v23, v48, v73
	v_med3_f32 v13, v29, v13, v72
	v_max_f32_e32 v29, v73, v73
	v_med3_f32 v31, v31, v22, v73
	v_med3_f32 v22, v48, v46, v73
	v_med3_f32 v48, v74, v58, v54
	v_med3_f32 v19, v50, v49, v73
	v_med3_f32 v25, v27, v52, v73
	v_med3_f32 v21, v13, v28, v73
	v_max_f32_e32 v30, v27, v29
	v_med3_f32 v27, v52, v24, v73
	v_med3_f32 v23, v49, v23, v73
	v_med3_f32 v24, v45, v13, v73
	v_med3_f32 v49, v6, v48, v55
	v_max_f32_e32 v6, v0, v0
	v_max_f32_e32 v13, v104, v104
	v_max_f32_e32 v6, v13, v6
	v_max_f32_e32 v13, v1, v1
	v_med3_f32 v29, v51, v50, v73
	v_med3_f32 v50, v32, v49, v60
	v_max_f32_e32 v13, v6, v13
	s_waitcnt lgkmcnt(13)
	v_max_f32_e32 v32, v2, v2
	v_med3_f32 v51, v33, v50, v61
	v_max_f32_e32 v33, v13, v32
	s_waitcnt lgkmcnt(12)
	v_max_f32_e32 v32, v3, v3
	v_med3_f32 v111, v34, v51, v62
	v_max_f32_e32 v34, v33, v32
	s_waitcnt lgkmcnt(11)
	v_max_f32_e32 v32, v4, v4
	v_med3_f32 v112, v35, v111, v63
	v_max_f32_e32 v35, v34, v32
	s_waitcnt lgkmcnt(10)
	v_max_f32_e32 v32, v5, v5
	v_med3_f32 v113, v36, v112, v64
	v_max_f32_e32 v36, v35, v32
	s_waitcnt lgkmcnt(9)
	v_max_f32_e32 v32, v7, v7
	v_med3_f32 v114, v37, v113, v65
	v_max_f32_e32 v37, v36, v32
	s_waitcnt lgkmcnt(8)
	v_max_f32_e32 v32, v8, v8
	v_med3_f32 v115, v38, v114, v66
	v_max_f32_e32 v38, v37, v32
	s_waitcnt lgkmcnt(7)
	v_max_f32_e32 v32, v9, v9
	v_med3_f32 v116, v39, v115, v67
	v_max_f32_e32 v39, v38, v32
	s_waitcnt lgkmcnt(6)
	v_max_f32_e32 v32, v10, v10
	v_med3_f32 v117, v40, v116, v68
	v_max_f32_e32 v40, v39, v32
	s_waitcnt lgkmcnt(5)
	v_max_f32_e32 v32, v11, v11
	v_med3_f32 v118, v41, v117, v69
	v_max_f32_e32 v41, v40, v32
	s_waitcnt lgkmcnt(4)
	v_max_f32_e32 v32, v12, v12
	v_med3_f32 v119, v42, v118, v70
	v_max_f32_e32 v42, v41, v32
	s_waitcnt lgkmcnt(3)
	v_max_f32_e32 v32, v14, v14
	v_med3_f32 v120, v43, v119, v71
	v_max_f32_e32 v43, v42, v32
	s_waitcnt lgkmcnt(2)
	v_max_f32_e32 v32, v15, v15
	v_med3_f32 v121, v44, v120, v72
	v_max_f32_e32 v44, v43, v32
	s_waitcnt lgkmcnt(1)
	v_max_f32_e32 v32, v16, v16
	v_med3_f32 v17, v46, v45, v73
	v_max_f32_e32 v45, v44, v32
	s_waitcnt lgkmcnt(0)
	v_max_f32_e32 v32, v47, v47
	v_max_f32_e32 v32, v45, v32
	v_add_f32_e32 v46, v30, v32
	v_and_b32_e32 v46, 0xffffff00, v46
	v_max_f32_e32 v46, v46, v46
	v_max_f32_e32 v122, 0xff800000, v46
	v_med3_f32 v46, v104, v103, v0
	v_med3_f32 v6, v6, v46, v1
	v_med3_f32 v13, v13, v6, v2
	v_med3_f32 v52, v33, v13, v3
	v_med3_f32 v34, v34, v52, v4
	v_med3_f32 v35, v35, v34, v5
	v_med3_f32 v36, v36, v35, v7
	v_med3_f32 v37, v37, v36, v8
	v_med3_f32 v38, v38, v37, v9
	v_med3_f32 v39, v39, v38, v10
	v_med3_f32 v40, v40, v39, v11
	v_med3_f32 v41, v41, v40, v12
	v_med3_f32 v42, v42, v41, v14
	v_med3_f32 v43, v43, v42, v15
	v_med3_f32 v44, v44, v43, v16
	v_med3_f32 v33, v45, v44, v47
	v_add_f32_e32 v45, v30, v33
	v_and_or_b32 v45, v45, s26, 1
	v_max_f32_e32 v123, v45, v45
	v_med3_f32 v45, v103, v102, v0
	v_med3_f32 v46, v46, v45, v1
	v_med3_f32 v6, v6, v46, v2
	v_med3_f32 v13, v13, v6, v3
	v_med3_f32 v52, v52, v13, v4
	v_med3_f32 v53, v34, v52, v5
	v_med3_f32 v35, v35, v53, v7
	v_med3_f32 v36, v36, v35, v8
	v_med3_f32 v37, v37, v36, v9
	v_med3_f32 v38, v38, v37, v10
	v_med3_f32 v39, v39, v38, v11
	v_med3_f32 v40, v40, v39, v12
	v_med3_f32 v41, v41, v40, v14
	v_med3_f32 v42, v42, v41, v15
	v_med3_f32 v43, v43, v42, v16
	v_med3_f32 v34, v44, v43, v47
	v_add_f32_e32 v44, v30, v34
	v_and_or_b32 v125, v44, s26, 2
	v_med3_f32 v44, v102, v101, v0
	v_med3_f32 v45, v45, v44, v1
	v_med3_f32 v46, v46, v45, v2
	v_med3_f32 v6, v6, v46, v3
	v_med3_f32 v13, v13, v6, v4
	v_med3_f32 v52, v52, v13, v5
	v_med3_f32 v53, v53, v52, v7
	v_med3_f32 v74, v35, v53, v8
	v_med3_f32 v36, v36, v74, v9
	v_med3_f32 v37, v37, v36, v10
	v_med3_f32 v38, v38, v37, v11
	v_med3_f32 v39, v39, v38, v12
	v_med3_f32 v40, v40, v39, v14
	v_med3_f32 v41, v41, v40, v15
	v_med3_f32 v42, v42, v41, v16
	v_med3_f32 v35, v43, v42, v47
	v_add_f32_e32 v43, v30, v35
	v_and_or_b32 v128, v43, s26, 3
	v_med3_f32 v43, v101, v100, v0
	v_med3_f32 v44, v44, v43, v1
	v_med3_f32 v45, v45, v44, v2
	v_med3_f32 v46, v46, v45, v3
	v_med3_f32 v6, v6, v46, v4
	v_med3_f32 v13, v13, v6, v5
	v_med3_f32 v52, v52, v13, v7
	v_med3_f32 v53, v53, v52, v8
	v_med3_f32 v74, v74, v53, v9
	v_med3_f32 v75, v36, v74, v10
	v_med3_f32 v37, v37, v75, v11
	v_med3_f32 v38, v38, v37, v12
	v_med3_f32 v39, v39, v38, v14
	v_med3_f32 v40, v40, v39, v15
	v_med3_f32 v41, v41, v40, v16
	v_med3_f32 v36, v42, v41, v47
	v_add_f32_e32 v42, v30, v36
	v_and_or_b32 v131, v42, s26, 4
	v_med3_f32 v42, v100, v99, v0
	v_med3_f32 v43, v43, v42, v1
	v_med3_f32 v44, v44, v43, v2
	v_med3_f32 v45, v45, v44, v3
	v_med3_f32 v46, v46, v45, v4
	v_med3_f32 v6, v6, v46, v5
	v_med3_f32 v13, v13, v6, v7
	v_med3_f32 v52, v52, v13, v8
	v_med3_f32 v53, v53, v52, v9
	v_med3_f32 v74, v74, v53, v10
	v_med3_f32 v75, v75, v74, v11
	v_med3_f32 v76, v37, v75, v12
	v_med3_f32 v38, v38, v76, v14
	v_med3_f32 v39, v39, v38, v15
	v_med3_f32 v40, v40, v39, v16
	v_med3_f32 v37, v41, v40, v47
	v_add_f32_e32 v41, v30, v37
	v_and_or_b32 v110, v41, s26, 5
	v_med3_f32 v41, v99, v98, v0
	v_med3_f32 v42, v42, v41, v1
	v_med3_f32 v43, v43, v42, v2
	v_med3_f32 v44, v44, v43, v3
	v_med3_f32 v45, v45, v44, v4
	v_med3_f32 v46, v46, v45, v5
	v_med3_f32 v6, v6, v46, v7
	v_med3_f32 v13, v13, v6, v8
	v_med3_f32 v52, v52, v13, v9
	v_med3_f32 v53, v53, v52, v10
	v_med3_f32 v74, v74, v53, v11
	v_med3_f32 v75, v75, v74, v12
	v_med3_f32 v76, v76, v75, v14
	v_med3_f32 v77, v38, v76, v15
	v_med3_f32 v39, v39, v77, v16
	v_med3_f32 v38, v40, v39, v47
	v_add_f32_e32 v40, v30, v38
	v_and_or_b32 v108, v40, s26, 6
	v_med3_f32 v40, v98, v97, v0
	v_med3_f32 v41, v41, v40, v1
	v_med3_f32 v42, v42, v41, v2
	v_med3_f32 v43, v43, v42, v3
	v_med3_f32 v44, v44, v43, v4
	v_med3_f32 v45, v45, v44, v5
	v_med3_f32 v46, v46, v45, v7
	v_med3_f32 v6, v6, v46, v8
	v_med3_f32 v13, v13, v6, v9
	v_med3_f32 v52, v52, v13, v10
	v_med3_f32 v53, v53, v52, v11
	v_med3_f32 v74, v74, v53, v12
	v_med3_f32 v75, v75, v74, v14
	v_med3_f32 v76, v76, v75, v15
	v_med3_f32 v77, v77, v76, v16
	v_med3_f32 v39, v39, v77, v47
	v_add_f32_e32 v78, v30, v39
	v_and_or_b32 v106, v78, s26, 7
	v_med3_f32 v78, v97, v96, v0
	v_med3_f32 v79, v40, v78, v1
	v_med3_f32 v41, v41, v79, v2
	v_med3_f32 v42, v42, v41, v3
	v_med3_f32 v43, v43, v42, v4
	v_med3_f32 v44, v44, v43, v5
	v_med3_f32 v45, v45, v44, v7
	v_med3_f32 v46, v46, v45, v8
	v_med3_f32 v6, v6, v46, v9
	v_med3_f32 v13, v13, v6, v10
	v_med3_f32 v52, v52, v13, v11
	v_med3_f32 v53, v53, v52, v12
	v_med3_f32 v74, v74, v53, v14
	v_med3_f32 v75, v75, v74, v15
	v_med3_f32 v76, v76, v75, v16
	v_med3_f32 v40, v77, v76, v47
	v_add_f32_e32 v77, v30, v40
	v_and_or_b32 v104, v77, s26, 8
	v_med3_f32 v77, v96, v95, v0
	v_med3_f32 v78, v78, v77, v1
	v_med3_f32 v79, v79, v78, v2
	v_med3_f32 v80, v41, v79, v3
	v_med3_f32 v42, v42, v80, v4
	v_med3_f32 v43, v43, v42, v5
	v_med3_f32 v44, v44, v43, v7
	v_med3_f32 v45, v45, v44, v8
	v_med3_f32 v46, v46, v45, v9
	v_med3_f32 v6, v6, v46, v10
	v_med3_f32 v13, v13, v6, v11
	v_med3_f32 v52, v52, v13, v12
	v_med3_f32 v53, v53, v52, v14
	v_med3_f32 v74, v74, v53, v15
	v_med3_f32 v75, v75, v74, v16
	v_med3_f32 v41, v76, v75, v47
	v_add_f32_e32 v76, v30, v41
	v_and_or_b32 v102, v76, s26, 9
	v_med3_f32 v76, v95, v94, v0
	v_med3_f32 v77, v77, v76, v1
	v_med3_f32 v78, v78, v77, v2
	v_med3_f32 v79, v79, v78, v3
	v_med3_f32 v80, v80, v79, v4
	v_med3_f32 v81, v42, v80, v5
	v_med3_f32 v43, v43, v81, v7
	v_med3_f32 v44, v44, v43, v8
	v_med3_f32 v45, v45, v44, v9
	v_med3_f32 v46, v46, v45, v10
	v_med3_f32 v6, v6, v46, v11
	v_med3_f32 v13, v13, v6, v12
	v_med3_f32 v52, v52, v13, v14
	v_med3_f32 v53, v53, v52, v15
	v_med3_f32 v74, v74, v53, v16
	v_med3_f32 v42, v75, v74, v47
	v_add_f32_e32 v75, v30, v42
	v_and_or_b32 v100, v75, s26, 10
	v_med3_f32 v75, v94, v93, v0
	v_med3_f32 v76, v76, v75, v1
	v_med3_f32 v77, v77, v76, v2
	v_med3_f32 v78, v78, v77, v3
	v_med3_f32 v79, v79, v78, v4
	v_med3_f32 v80, v80, v79, v5
	v_med3_f32 v81, v81, v80, v7
	v_med3_f32 v82, v43, v81, v8
	v_med3_f32 v44, v44, v82, v9
	v_med3_f32 v45, v45, v44, v10
	v_med3_f32 v46, v46, v45, v11
	v_med3_f32 v6, v6, v46, v12
	v_med3_f32 v13, v13, v6, v14
	v_med3_f32 v52, v52, v13, v15
	v_med3_f32 v53, v53, v52, v16
	v_med3_f32 v43, v74, v53, v47
	v_add_f32_e32 v74, v30, v43
	v_and_or_b32 v96, v74, s26, 11
	v_med3_f32 v74, v93, v92, v0
	v_med3_f32 v75, v75, v74, v1
	v_med3_f32 v83, v76, v75, v2
	v_med3_f32 v77, v77, v83, v3
	v_med3_f32 v78, v78, v77, v4
	v_med3_f32 v79, v79, v78, v5
	v_med3_f32 v80, v80, v79, v7
	v_med3_f32 v81, v81, v80, v8
	v_med3_f32 v82, v82, v81, v9
	v_med3_f32 v85, v44, v82, v10
	v_med3_f32 v45, v45, v85, v11
	v_med3_f32 v46, v46, v45, v12
	v_med3_f32 v6, v6, v46, v14
	v_med3_f32 v13, v13, v6, v15
	v_med3_f32 v52, v52, v13, v16
	v_med3_f32 v44, v53, v52, v47
	v_add_f32_e32 v53, v30, v44
	v_and_or_b32 v93, v53, s26, 12
	v_med3_f32 v53, v92, v91, v0
	v_med3_f32 v74, v74, v53, v1
	v_med3_f32 v75, v75, v74, v2
	v_med3_f32 v83, v83, v75, v3
	v_med3_f32 v77, v77, v83, v4
	v_med3_f32 v78, v78, v77, v5
	v_med3_f32 v79, v79, v78, v7
	v_med3_f32 v80, v80, v79, v8
	v_med3_f32 v81, v81, v80, v9
	v_med3_f32 v86, v82, v81, v10
	v_med3_f32 v85, v85, v86, v11
	v_med3_f32 v87, v45, v85, v12
	v_med3_f32 v46, v46, v87, v14
	v_med3_f32 v6, v6, v46, v15
	v_med3_f32 v88, v13, v6, v16
	v_med3_f32 v45, v52, v88, v47
	v_med3_f32 v52, v91, v89, v0
	v_med3_f32 v53, v53, v52, v1
	v_med3_f32 v0, v89, v90, v0
	v_med3_f32 v74, v74, v53, v2
	v_med3_f32 v0, v52, v0, v1
	v_med3_f32 v75, v75, v74, v3
	v_med3_f32 v0, v53, v0, v2
	v_med3_f32 v83, v83, v75, v4
	v_med3_f32 v0, v74, v0, v3
	v_med3_f32 v91, v77, v83, v5
	v_med3_f32 v0, v75, v0, v4
	v_max_f32_e32 v124, v122, v123
	v_max_f32_e32 v126, v125, v125
	v_med3_f32 v78, v78, v91, v7
	v_med3_f32 v0, v83, v0, v5
	v_max_f32_e32 v127, v124, v126
	v_max_f32_e32 v129, v128, v128
	v_med3_f32 v79, v79, v78, v8
	v_med3_f32 v0, v91, v0, v7
	v_max_f32_e32 v130, v127, v129
	v_max_f32_e32 v109, v131, v131
	v_med3_f32 v80, v80, v79, v9
	v_med3_f32 v0, v78, v0, v8
	v_max_f32_e32 v132, v130, v109
	v_max_f32_e32 v107, v110, v110
	v_med3_f32 v81, v81, v80, v10
	v_med3_f32 v0, v79, v0, v9
	v_max_f32_e32 v133, v132, v107
	v_max_f32_e32 v105, v108, v108
	v_med3_f32 v86, v86, v81, v11
	v_med3_f32 v0, v80, v0, v10
	v_max_f32_e32 v134, v133, v105
	v_max_f32_e32 v103, v106, v106
	v_med3_f32 v85, v85, v86, v12
	v_med3_f32 v0, v81, v0, v11
	v_max_f32_e32 v135, v134, v103
	v_max_f32_e32 v101, v104, v104
	v_med3_f32 v87, v87, v85, v14
	v_med3_f32 v0, v86, v0, v12
	v_max_f32_e32 v136, v135, v101
	v_max_f32_e32 v98, v102, v102
	v_med3_f32 v92, v46, v87, v15
	v_med3_f32 v0, v85, v0, v14
	v_max_f32_e32 v137, v136, v98
	v_max_f32_e32 v95, v100, v100
	v_med3_f32 v94, v6, v92, v16
	v_med3_f32 v0, v87, v0, v15
	v_max_f32_e32 v138, v137, v95
	v_max_f32_e32 v84, v96, v96
	v_add_f32_e32 v13, v30, v45
	v_med3_f32 v46, v88, v94, v47
	v_med3_f32 v0, v92, v0, v16
	v_max_f32_e32 v139, v138, v84
	v_max_f32_e32 v76, v93, v93
	v_and_or_b32 v82, v13, s26, 13
	v_add_f32_e32 v6, v30, v46
	v_med3_f32 v47, v94, v0, v47
	v_max_f32_e32 v140, v139, v76
	v_max_f32_e32 v13, v82, v82
	v_and_or_b32 v77, v6, s26, 14
	v_add_f32_e32 v0, v30, v47
	v_max_f32_e32 v141, v140, v13
	v_max_f32_e32 v6, v77, v77
	v_and_or_b32 v14, v0, s26, 15
	v_add_f32_e32 v1, v25, v32
	v_max_f32_e32 v142, v141, v6
	v_max_f32_e32 v0, v14, v14
	v_and_or_b32 v1, v1, s26, 16
	v_max_f32_e32 v143, v142, v0
	v_max_f32_e32 v2, v1, v1
	v_max_f32_e32 v144, v143, v2
	v_add_f32_e32 v2, v25, v33
	v_and_or_b32 v2, v2, s26, 17
	v_max_f32_e32 v3, v2, v2
	v_max_f32_e32 v146, v144, v3
	v_add_f32_e32 v3, v25, v34
	v_and_or_b32 v3, v3, s26, 18
	v_max_f32_e32 v4, v3, v3
	v_max_f32_e32 v147, v146, v4
	v_add_f32_e32 v4, v25, v35
	v_and_or_b32 v4, v4, s26, 19
	v_max_f32_e32 v5, v4, v4
	v_max_f32_e32 v148, v147, v5
	v_add_f32_e32 v5, v25, v36
	v_and_or_b32 v5, v5, s26, 20
	v_max_f32_e32 v7, v5, v5
	v_max_f32_e32 v149, v148, v7
	v_add_f32_e32 v7, v25, v37
	v_and_or_b32 v7, v7, s26, 21
	v_max_f32_e32 v8, v7, v7
	v_max_f32_e32 v150, v149, v8
	v_add_f32_e32 v8, v25, v38
	v_and_or_b32 v8, v8, s26, 22
	v_max_f32_e32 v9, v8, v8
	v_max_f32_e32 v151, v150, v9
	v_add_f32_e32 v9, v25, v39
	v_and_or_b32 v9, v9, s26, 23
	v_max_f32_e32 v10, v9, v9
	v_max_f32_e32 v164, v151, v10
	v_add_f32_e32 v10, v27, v32
	v_and_or_b32 v10, v10, s26, 32
	v_max_f32_e32 v11, v10, v10
	v_max_f32_e32 v165, v164, v11
	v_add_f32_e32 v11, v27, v33
	v_and_or_b32 v11, v11, s26, 33
	v_max_f32_e32 v12, v11, v11
	v_max_f32_e32 v166, v165, v12
	v_add_f32_e32 v12, v27, v34
	v_and_or_b32 v12, v12, s26, 34
	v_max_f32_e32 v15, v12, v12
	v_max_f32_e32 v167, v166, v15
	v_add_f32_e32 v15, v27, v35
	v_and_or_b32 v15, v15, s26, 35
	v_max_f32_e32 v16, v15, v15
	v_max_f32_e32 v168, v167, v16
	v_add_f32_e32 v16, v27, v36
	v_and_or_b32 v16, v16, s26, 36
	v_max_f32_e32 v52, v16, v16
	v_max_f32_e32 v169, v168, v52
	v_add_f32_e32 v52, v20, v32
	v_and_or_b32 v52, v52, s26, 48
	v_max_f32_e32 v53, v52, v52
	v_max_f32_e32 v170, v169, v53
	v_add_f32_e32 v53, v20, v33
	v_and_or_b32 v53, v53, s26, 49
	v_max_f32_e32 v74, v53, v53
	v_max_f32_e32 v171, v170, v74
	v_add_f32_e32 v74, v20, v34
	v_and_or_b32 v74, v74, s26, 50
	v_max_f32_e32 v75, v74, v74
	v_max_f32_e32 v172, v171, v75
	v_add_f32_e32 v75, v20, v35
	v_and_or_b32 v75, v75, s26, 51
	v_max_f32_e32 v78, v75, v75
	v_max_f32_e32 v173, v172, v78
	v_add_f32_e32 v78, v31, v32
	v_and_or_b32 v78, v78, s26, 64
	v_max_f32_e32 v79, v78, v78
	v_max_f32_e32 v174, v173, v79
	v_add_f32_e32 v79, v31, v33
	v_and_b32_e32 v79, 0xffffff00, v79
	v_or_b32_e32 v79, 0x41, v79
	v_max_f32_e32 v80, v79, v79
	v_max_f32_e32 v175, v174, v80
	v_add_f32_e32 v80, v31, v34
	v_and_b32_e32 v80, 0xffffff00, v80
	v_or_b32_e32 v80, 0x42, v80
	v_max_f32_e32 v81, v80, v80
	v_max_f32_e32 v176, v175, v81
	v_add_f32_e32 v81, v26, v32
	v_and_b32_e32 v81, 0xffffff00, v81
	v_or_b32_e32 v81, 0x50, v81
	v_med3_f32 v54, v58, v59, v54
	v_max_f32_e32 v83, v81, v81
	v_med3_f32 v48, v48, v54, v55
	v_max_f32_e32 v177, v176, v83
	v_add_f32_e32 v83, v26, v33
	v_med3_f32 v48, v49, v48, v60
	v_and_b32_e32 v83, 0xffffff00, v83
	v_med3_f32 v48, v50, v48, v61
	v_or_b32_e32 v83, 0x51, v83
	v_med3_f32 v48, v51, v48, v62
	v_min_f32_e32 v51, v122, v123
	v_max_f32_e32 v85, v83, v83
	v_med3_f32 v54, v124, v51, v125
	v_min_f32_e32 v126, v51, v126
	v_max_f32_e32 v180, v177, v85
	v_add_f32_e32 v85, v29, v32
	v_med3_f32 v55, v127, v54, v128
	v_med3_f32 v54, v54, v126, v128
	v_min_f32_e32 v126, v126, v129
	v_and_b32_e32 v85, 0xffffff00, v85
	v_med3_f32 v59, v130, v55, v131
	v_med3_f32 v55, v55, v54, v131
	v_med3_f32 v129, v54, v126, v131
	v_min_f32_e32 v109, v126, v109
	v_or_b32_e32 v85, 0x60, v85
	v_med3_f32 v60, v132, v59, v110
	v_med3_f32 v59, v59, v55, v110
	v_med3_f32 v55, v55, v129, v110
	v_med3_f32 v110, v129, v109, v110
	v_min_f32_e32 v107, v109, v107
	v_max_f32_e32 v86, v85, v85
	v_med3_f32 v61, v133, v60, v108
	v_med3_f32 v60, v60, v59, v108
	v_med3_f32 v59, v59, v55, v108
	v_med3_f32 v126, v55, v110, v108
	v_med3_f32 v108, v110, v107, v108
	v_min_f32_e32 v105, v107, v105
	v_max_f32_e32 v181, v180, v86
	v_add_f32_e32 v86, v29, v33
	v_med3_f32 v62, v134, v61, v106
	v_med3_f32 v61, v61, v60, v106
	v_med3_f32 v60, v60, v59, v106
	v_med3_f32 v59, v59, v126, v106
	v_med3_f32 v109, v126, v108, v106
	v_med3_f32 v106, v108, v105, v106
	v_min_f32_e32 v103, v105, v103
	v_and_b32_e32 v86, 0xffffff00, v86
	v_med3_f32 v48, v111, v48, v63
	v_med3_f32 v63, v135, v62, v104
	v_med3_f32 v62, v62, v61, v104
	v_med3_f32 v61, v61, v60, v104
	v_med3_f32 v60, v60, v59, v104
	v_med3_f32 v110, v59, v109, v104
	v_med3_f32 v107, v109, v106, v104
	v_med3_f32 v104, v106, v103, v104
	v_min_f32_e32 v101, v103, v101
	v_or_b32_e32 v86, 0x61, v86
	v_med3_f32 v48, v112, v48, v64
	v_med3_f32 v64, v136, v63, v102
	v_med3_f32 v63, v63, v62, v102
	v_med3_f32 v62, v62, v61, v102
	v_med3_f32 v61, v61, v60, v102
	v_med3_f32 v60, v60, v110, v102
	v_med3_f32 v108, v110, v107, v102
	v_med3_f32 v105, v107, v104, v102
	v_med3_f32 v102, v104, v101, v102
	v_min_f32_e32 v98, v101, v98
	v_max_f32_e32 v87, v86, v86
	v_med3_f32 v48, v113, v48, v65
	v_med3_f32 v65, v137, v64, v100
	v_med3_f32 v64, v64, v63, v100
	v_med3_f32 v63, v63, v62, v100
	v_med3_f32 v62, v62, v61, v100
	v_med3_f32 v61, v61, v60, v100
	v_med3_f32 v109, v60, v108, v100
	v_med3_f32 v106, v108, v105, v100
	v_med3_f32 v103, v105, v102, v100
	v_med3_f32 v100, v102, v98, v100
	v_min_f32_e32 v95, v98, v95
	v_max_f32_e32 v182, v181, v87
	v_add_f32_e32 v87, v19, v32
	v_med3_f32 v48, v114, v48, v66
	v_med3_f32 v66, v138, v65, v96
	v_med3_f32 v65, v65, v64, v96
	v_med3_f32 v64, v64, v63, v96
	v_med3_f32 v63, v63, v62, v96
	v_med3_f32 v62, v62, v61, v96
	v_med3_f32 v61, v61, v109, v96
	v_med3_f32 v107, v109, v106, v96
	v_med3_f32 v104, v106, v103, v96
	v_med3_f32 v101, v103, v100, v96
	v_med3_f32 v96, v100, v95, v96
	v_min_f32_e32 v84, v95, v84
	v_and_b32_e32 v87, 0xffffff00, v87
	v_med3_f32 v48, v115, v48, v67
	v_med3_f32 v67, v139, v66, v93
	v_med3_f32 v66, v66, v65, v93
	v_med3_f32 v65, v65, v64, v93
	v_med3_f32 v64, v64, v63, v93
	v_med3_f32 v63, v63, v62, v93
	v_med3_f32 v62, v62, v61, v93
	v_med3_f32 v108, v61, v107, v93
	v_med3_f32 v105, v107, v104, v93
	v_med3_f32 v102, v104, v101, v93
	v_med3_f32 v98, v101, v96, v93
	v_med3_f32 v93, v96, v84, v93
	v_min_f32_e32 v76, v84, v76
	v_or_b32_e32 v87, 0x70, v87
	v_med3_f32 v48, v116, v48, v68
	v_med3_f32 v68, v140, v67, v82
	v_med3_f32 v67, v67, v66, v82
	v_med3_f32 v66, v66, v65, v82
	v_med3_f32 v65, v65, v64, v82
	v_med3_f32 v64, v64, v63, v82
	v_med3_f32 v63, v63, v62, v82
	v_med3_f32 v62, v62, v108, v82
	v_med3_f32 v106, v108, v105, v82
	v_med3_f32 v103, v105, v102, v82
	v_med3_f32 v100, v102, v98, v82
	v_med3_f32 v95, v98, v93, v82
	v_med3_f32 v82, v93, v76, v82
	v_min_f32_e32 v13, v76, v13
	v_max_f32_e32 v88, v87, v87
	v_med3_f32 v48, v117, v48, v69
	v_med3_f32 v69, v141, v68, v77
	v_med3_f32 v68, v68, v67, v77
	v_med3_f32 v67, v67, v66, v77
	v_med3_f32 v66, v66, v65, v77
	v_med3_f32 v65, v65, v64, v77
	v_med3_f32 v64, v64, v63, v77
	v_med3_f32 v63, v63, v62, v77
	v_med3_f32 v107, v62, v106, v77
	v_med3_f32 v104, v106, v103, v77
	v_med3_f32 v101, v103, v100, v77
	v_med3_f32 v96, v100, v95, v77
	v_med3_f32 v84, v95, v82, v77
	v_med3_f32 v76, v82, v13, v77
	v_min_f32_e32 v6, v13, v6
	v_max_f32_e32 v183, v182, v88
	v_add_f32_e32 v88, v19, v33
	v_med3_f32 v48, v118, v48, v70
	v_med3_f32 v70, v142, v69, v14
	v_med3_f32 v69, v69, v68, v14
	v_med3_f32 v68, v68, v67, v14
	v_med3_f32 v67, v67, v66, v14
	v_med3_f32 v66, v66, v65, v14
	v_med3_f32 v65, v65, v64, v14
	v_med3_f32 v64, v64, v63, v14
	v_med3_f32 v63, v63, v107, v14
	v_med3_f32 v105, v107, v104, v14
	v_med3_f32 v102, v104, v101, v14
	v_med3_f32 v98, v101, v96, v14
	v_med3_f32 v93, v96, v84, v14
	v_med3_f32 v77, v84, v76, v14
	v_med3_f32 v13, v76, v6, v14
	v_min_f32_e32 v0, v6, v0
	v_and_b32_e32 v88, 0xffffff00, v88
	v_med3_f32 v48, v119, v48, v71
	v_med3_f32 v71, v143, v70, v1
	v_med3_f32 v70, v70, v69, v1
	v_med3_f32 v69, v69, v68, v1
	v_med3_f32 v68, v68, v67, v1
	v_med3_f32 v67, v67, v66, v1
	v_med3_f32 v66, v66, v65, v1
	v_med3_f32 v65, v65, v64, v1
	v_med3_f32 v64, v64, v63, v1
	v_med3_f32 v63, v63, v105, v1
	v_med3_f32 v103, v105, v102, v1
	v_med3_f32 v100, v102, v98, v1
	v_med3_f32 v95, v98, v93, v1
	v_med3_f32 v82, v93, v77, v1
	v_med3_f32 v14, v77, v13, v1
	v_med3_f32 v0, v13, v0, v1
	v_or_b32_e32 v88, 0x71, v88
	v_med3_f32 v48, v120, v48, v72
	v_med3_f32 v72, v144, v71, v2
	v_med3_f32 v71, v71, v70, v2
	v_med3_f32 v70, v70, v69, v2
	v_med3_f32 v69, v69, v68, v2
	v_med3_f32 v68, v68, v67, v2
	v_med3_f32 v67, v67, v66, v2
	v_med3_f32 v66, v66, v65, v2
	v_med3_f32 v65, v65, v64, v2
	v_med3_f32 v64, v64, v63, v2
	v_med3_f32 v63, v63, v103, v2
	v_med3_f32 v101, v103, v100, v2
	v_med3_f32 v96, v100, v95, v2
	v_med3_f32 v84, v95, v82, v2
	v_med3_f32 v76, v82, v14, v2
	v_med3_f32 v0, v14, v0, v2
	v_med3_f32 v28, v28, v121, v73
	v_max_f32_e32 v89, v88, v88
	v_med3_f32 v50, v121, v48, v73
	v_med3_f32 v73, v146, v72, v3
	v_med3_f32 v72, v72, v71, v3
	v_med3_f32 v71, v71, v70, v3
	v_med3_f32 v70, v70, v69, v3
	v_med3_f32 v69, v69, v68, v3
	v_med3_f32 v68, v68, v67, v3
	v_med3_f32 v67, v67, v66, v3
	v_med3_f32 v66, v66, v65, v3
	v_med3_f32 v65, v65, v64, v3
	v_med3_f32 v64, v64, v63, v3
	v_med3_f32 v63, v63, v101, v3
	v_med3_f32 v98, v101, v96, v3
	v_med3_f32 v93, v96, v84, v3
	v_med3_f32 v77, v84, v76, v3
	v_med3_f32 v0, v76, v0, v3
	v_max_f32_e32 v184, v183, v89
	v_add_f32_e32 v89, v23, v32
	v_med3_f32 v111, v147, v73, v4
	v_med3_f32 v73, v73, v72, v4
	v_med3_f32 v72, v72, v71, v4
	v_med3_f32 v71, v71, v70, v4
	v_med3_f32 v70, v70, v69, v4
	v_med3_f32 v69, v69, v68, v4
	v_med3_f32 v68, v68, v67, v4
	v_med3_f32 v67, v67, v66, v4
	v_med3_f32 v66, v66, v65, v4
	v_med3_f32 v65, v65, v64, v4
	v_med3_f32 v64, v64, v63, v4
	v_med3_f32 v63, v63, v98, v4
	v_med3_f32 v95, v98, v93, v4
	v_med3_f32 v82, v93, v77, v4
	v_med3_f32 v0, v77, v0, v4
	v_and_b32_e32 v89, 0xffffff00, v89
	v_med3_f32 v112, v148, v111, v5
	v_med3_f32 v111, v111, v73, v5
	v_med3_f32 v73, v73, v72, v5
	v_med3_f32 v72, v72, v71, v5
	v_med3_f32 v71, v71, v70, v5
	v_med3_f32 v70, v70, v69, v5
	v_med3_f32 v69, v69, v68, v5
	v_med3_f32 v68, v68, v67, v5
	v_med3_f32 v67, v67, v66, v5
	v_med3_f32 v66, v66, v65, v5
	v_med3_f32 v65, v65, v64, v5
	v_med3_f32 v64, v64, v63, v5
	v_med3_f32 v63, v63, v95, v5
	v_med3_f32 v84, v95, v82, v5
	v_med3_f32 v0, v82, v0, v5
	v_or_b32_e32 v89, 0x80, v89
	v_med3_f32 v113, v149, v112, v7
	v_med3_f32 v112, v112, v111, v7
	v_med3_f32 v111, v111, v73, v7
	v_med3_f32 v73, v73, v72, v7
	v_med3_f32 v72, v72, v71, v7
	v_med3_f32 v71, v71, v70, v7
	v_med3_f32 v70, v70, v69, v7
	v_med3_f32 v69, v69, v68, v7
	v_med3_f32 v68, v68, v67, v7
	v_med3_f32 v67, v67, v66, v7
	v_med3_f32 v66, v66, v65, v7
	v_med3_f32 v65, v65, v64, v7
	v_med3_f32 v64, v64, v63, v7
	v_med3_f32 v63, v63, v84, v7
	v_med3_f32 v0, v84, v0, v7
	v_max_f32_e32 v90, v89, v89
	v_med3_f32 v114, v150, v113, v8
	v_med3_f32 v113, v113, v112, v8
	v_med3_f32 v112, v112, v111, v8
	v_med3_f32 v111, v111, v73, v8
	v_med3_f32 v73, v73, v72, v8
	v_med3_f32 v72, v72, v71, v8
	v_med3_f32 v71, v71, v70, v8
	v_med3_f32 v70, v70, v69, v8
	v_med3_f32 v69, v69, v68, v8
	v_med3_f32 v68, v68, v67, v8
	v_med3_f32 v67, v67, v66, v8
	v_med3_f32 v66, v66, v65, v8
	v_med3_f32 v65, v65, v64, v8
	v_med3_f32 v64, v64, v63, v8
	v_med3_f32 v0, v63, v0, v8
	v_max_f32_e32 v185, v184, v90
	v_add_f32_e32 v90, v18, v32
	v_med3_f32 v115, v151, v114, v9
	v_med3_f32 v114, v114, v113, v9
	v_med3_f32 v113, v113, v112, v9
	v_med3_f32 v112, v112, v111, v9
	v_med3_f32 v111, v111, v73, v9
	v_med3_f32 v73, v73, v72, v9
	v_med3_f32 v72, v72, v71, v9
	v_med3_f32 v71, v71, v70, v9
	v_med3_f32 v70, v70, v69, v9
	v_med3_f32 v69, v69, v68, v9
	v_med3_f32 v68, v68, v67, v9
	v_med3_f32 v67, v67, v66, v9
	v_med3_f32 v66, v66, v65, v9
	v_med3_f32 v65, v65, v64, v9
	v_med3_f32 v0, v64, v0, v9
	v_and_b32_e32 v90, 0xffffff00, v90
	v_med3_f32 v116, v164, v115, v10
	v_med3_f32 v115, v115, v114, v10
	v_med3_f32 v114, v114, v113, v10
	v_med3_f32 v113, v113, v112, v10
	v_med3_f32 v112, v112, v111, v10
	v_med3_f32 v110, v111, v73, v10
	v_med3_f32 v73, v73, v72, v10
	v_med3_f32 v72, v72, v71, v10
	v_med3_f32 v71, v71, v70, v10
	v_med3_f32 v70, v70, v69, v10
	v_med3_f32 v69, v69, v68, v10
	v_med3_f32 v68, v68, v67, v10
	v_med3_f32 v67, v67, v66, v10
	v_med3_f32 v66, v66, v65, v10
	v_med3_f32 v0, v65, v0, v10
	v_or_b32_e32 v90, 0x90, v90
	v_med3_f32 v117, v165, v116, v11
	v_med3_f32 v116, v116, v115, v11
	v_med3_f32 v115, v115, v114, v11
	v_med3_f32 v114, v114, v113, v11
	v_med3_f32 v113, v113, v112, v11
	v_med3_f32 v111, v112, v110, v11
	v_med3_f32 v109, v110, v73, v11
	v_med3_f32 v73, v73, v72, v11
	v_med3_f32 v72, v72, v71, v11
	v_med3_f32 v71, v71, v70, v11
	v_med3_f32 v70, v70, v69, v11
	v_med3_f32 v69, v69, v68, v11
	v_med3_f32 v68, v68, v67, v11
	v_med3_f32 v67, v67, v66, v11
	v_med3_f32 v0, v66, v0, v11
	v_max_f32_e32 v91, v90, v90
	v_med3_f32 v118, v166, v117, v12
	v_med3_f32 v117, v117, v116, v12
	v_med3_f32 v116, v116, v115, v12
	v_med3_f32 v115, v115, v114, v12
	v_med3_f32 v114, v114, v113, v12
	v_med3_f32 v112, v113, v111, v12
	v_med3_f32 v110, v111, v109, v12
	v_med3_f32 v108, v109, v73, v12
	v_med3_f32 v73, v73, v72, v12
	v_med3_f32 v72, v72, v71, v12
	v_med3_f32 v71, v71, v70, v12
	v_med3_f32 v70, v70, v69, v12
	v_med3_f32 v69, v69, v68, v12
	v_med3_f32 v68, v68, v67, v12
	v_med3_f32 v0, v67, v0, v12
	v_max_f32_e32 v186, v185, v91
	v_add_f32_e32 v91, v22, v32
	v_med3_f32 v119, v167, v118, v15
	v_med3_f32 v118, v118, v117, v15
	v_med3_f32 v117, v117, v116, v15
	v_med3_f32 v116, v116, v115, v15
	v_med3_f32 v115, v115, v114, v15
	v_med3_f32 v113, v114, v112, v15
	v_med3_f32 v111, v112, v110, v15
	v_med3_f32 v109, v110, v108, v15
	v_med3_f32 v106, v108, v73, v15
	v_med3_f32 v73, v73, v72, v15
	v_med3_f32 v72, v72, v71, v15
	v_med3_f32 v71, v71, v70, v15
	v_med3_f32 v70, v70, v69, v15
	v_med3_f32 v69, v69, v68, v15
	v_med3_f32 v0, v68, v0, v15
	v_and_b32_e32 v91, 0xffffff00, v91
	v_med3_f32 v120, v168, v119, v16
	v_med3_f32 v119, v119, v118, v16
	v_med3_f32 v118, v118, v117, v16
	v_med3_f32 v117, v117, v116, v16
	v_med3_f32 v116, v116, v115, v16
	v_med3_f32 v114, v115, v113, v16
	v_med3_f32 v112, v113, v111, v16
	v_med3_f32 v110, v111, v109, v16
	v_med3_f32 v107, v109, v106, v16
	v_med3_f32 v104, v106, v73, v16
	v_med3_f32 v73, v73, v72, v16
	v_med3_f32 v72, v72, v71, v16
	v_med3_f32 v71, v71, v70, v16
	v_med3_f32 v70, v70, v69, v16
	v_med3_f32 v0, v69, v0, v16
	v_or_b32_e32 v91, 0xa0, v91
	v_med3_f32 v121, v169, v120, v52
	v_med3_f32 v120, v120, v119, v52
	v_med3_f32 v119, v119, v118, v52
	v_med3_f32 v118, v118, v117, v52
	v_med3_f32 v117, v117, v116, v52
	v_med3_f32 v115, v116, v114, v52
	v_med3_f32 v113, v114, v112, v52
	v_med3_f32 v111, v112, v110, v52
	v_med3_f32 v108, v110, v107, v52
	v_med3_f32 v105, v107, v104, v52
	v_med3_f32 v102, v104, v73, v52
	v_med3_f32 v73, v73, v72, v52
	v_med3_f32 v72, v72, v71, v52
	v_med3_f32 v71, v71, v70, v52
	v_med3_f32 v0, v70, v0, v52
	v_max_f32_e32 v92, v91, v91
	v_med3_f32 v122, v170, v121, v53
	v_med3_f32 v121, v121, v120, v53
	v_med3_f32 v120, v120, v119, v53
	v_med3_f32 v119, v119, v118, v53
	v_med3_f32 v118, v118, v117, v53
	v_med3_f32 v116, v117, v115, v53
	v_med3_f32 v114, v115, v113, v53
	v_med3_f32 v112, v113, v111, v53
	v_med3_f32 v109, v111, v108, v53
	v_med3_f32 v106, v108, v105, v53
	v_med3_f32 v103, v105, v102, v53
	v_med3_f32 v100, v102, v73, v53
	v_med3_f32 v73, v73, v72, v53
	v_med3_f32 v72, v72, v71, v53
	v_med3_f32 v0, v71, v0, v53
	v_max_f32_e32 v187, v186, v92
	v_add_f32_e32 v92, v17, v32
	v_med3_f32 v123, v171, v122, v74
	v_med3_f32 v122, v122, v121, v74
	v_med3_f32 v121, v121, v120, v74
	v_med3_f32 v120, v120, v119, v74
	v_med3_f32 v119, v119, v118, v74
	v_med3_f32 v117, v118, v116, v74
	v_med3_f32 v115, v116, v114, v74
	v_med3_f32 v113, v114, v112, v74
	v_med3_f32 v110, v112, v109, v74
	v_med3_f32 v107, v109, v106, v74
	v_med3_f32 v104, v106, v103, v74
	v_med3_f32 v101, v103, v100, v74
	v_med3_f32 v96, v100, v73, v74
	v_med3_f32 v73, v73, v72, v74
	v_med3_f32 v0, v72, v0, v74
	v_and_b32_e32 v92, 0xffffff00, v92
	v_med3_f32 v124, v172, v123, v75
	v_med3_f32 v123, v123, v122, v75
	v_med3_f32 v122, v122, v121, v75
	v_med3_f32 v121, v121, v120, v75
	v_med3_f32 v120, v120, v119, v75
	v_med3_f32 v118, v119, v117, v75
	v_med3_f32 v116, v117, v115, v75
	v_med3_f32 v114, v115, v113, v75
	v_med3_f32 v111, v113, v110, v75
	v_med3_f32 v108, v110, v107, v75
	v_med3_f32 v105, v107, v104, v75
	v_med3_f32 v102, v104, v101, v75
	v_med3_f32 v98, v101, v96, v75
	v_med3_f32 v93, v96, v73, v75
	v_med3_f32 v0, v73, v0, v75
	v_or_b32_e32 v92, 0xb0, v92
	v_med3_f32 v125, v173, v124, v78
	v_med3_f32 v124, v124, v123, v78
	v_med3_f32 v123, v123, v122, v78
	v_med3_f32 v122, v122, v121, v78
	v_med3_f32 v121, v121, v120, v78
	v_med3_f32 v119, v120, v118, v78
	v_med3_f32 v117, v118, v116, v78
	v_med3_f32 v115, v116, v114, v78
	v_med3_f32 v112, v114, v111, v78
	v_med3_f32 v109, v111, v108, v78
	v_med3_f32 v106, v108, v105, v78
	v_med3_f32 v103, v105, v102, v78
	v_med3_f32 v100, v102, v98, v78
	v_med3_f32 v95, v98, v93, v78
	v_med3_f32 v0, v93, v0, v78
	v_max_f32_e32 v94, v92, v92
	v_med3_f32 v127, v174, v125, v79
	v_med3_f32 v125, v125, v124, v79
	v_med3_f32 v124, v124, v123, v79
	v_med3_f32 v123, v123, v122, v79
	v_med3_f32 v122, v122, v121, v79
	v_med3_f32 v120, v121, v119, v79
	v_med3_f32 v118, v119, v117, v79
	v_med3_f32 v116, v117, v115, v79
	v_med3_f32 v113, v115, v112, v79
	v_med3_f32 v110, v112, v109, v79
	v_med3_f32 v107, v109, v106, v79
	v_med3_f32 v104, v106, v103, v79
	v_med3_f32 v101, v103, v100, v79
	v_med3_f32 v96, v100, v95, v79
	v_med3_f32 v0, v95, v0, v79
	v_max_f32_e32 v188, v187, v94
	v_add_f32_e32 v94, v24, v32
	v_med3_f32 v130, v175, v127, v80
	v_med3_f32 v127, v127, v125, v80
	v_med3_f32 v125, v125, v124, v80
	v_med3_f32 v124, v124, v123, v80
	v_med3_f32 v123, v123, v122, v80
	v_med3_f32 v121, v122, v120, v80
	v_med3_f32 v119, v120, v118, v80
	v_med3_f32 v117, v118, v116, v80
	v_med3_f32 v114, v116, v113, v80
	v_med3_f32 v111, v113, v110, v80
	v_med3_f32 v108, v110, v107, v80
	v_med3_f32 v105, v107, v104, v80
	v_med3_f32 v102, v104, v101, v80
	v_med3_f32 v98, v101, v96, v80
	v_med3_f32 v0, v96, v0, v80
	v_and_b32_e32 v94, 0xffffff00, v94
	v_med3_f32 v132, v176, v130, v81
	v_med3_f32 v128, v130, v127, v81
	v_med3_f32 v127, v127, v125, v81
	v_med3_f32 v125, v125, v124, v81
	v_med3_f32 v124, v124, v123, v81
	v_med3_f32 v122, v123, v121, v81
	v_med3_f32 v120, v121, v119, v81
	v_med3_f32 v118, v119, v117, v81
	v_med3_f32 v115, v117, v114, v81
	v_med3_f32 v112, v114, v111, v81
	v_med3_f32 v109, v111, v108, v81
	v_med3_f32 v106, v108, v105, v81
	v_med3_f32 v103, v105, v102, v81
	v_med3_f32 v100, v102, v98, v81
	v_med3_f32 v0, v98, v0, v81
	v_or_b32_e32 v94, 0xc0, v94
	v_med3_f32 v133, v177, v132, v83
	v_med3_f32 v130, v132, v128, v83
	v_med3_f32 v128, v128, v127, v83
	v_med3_f32 v127, v127, v125, v83
	v_med3_f32 v125, v125, v124, v83
	v_med3_f32 v123, v124, v122, v83
	v_med3_f32 v121, v122, v120, v83
	v_med3_f32 v119, v120, v118, v83
	v_med3_f32 v116, v118, v115, v83
	v_med3_f32 v113, v115, v112, v83
	v_med3_f32 v110, v112, v109, v83
	v_med3_f32 v107, v109, v106, v83
	v_med3_f32 v104, v106, v103, v83
	v_med3_f32 v101, v103, v100, v83
	v_med3_f32 v0, v100, v0, v83
	v_max_f32_e32 v97, v94, v94
	v_med3_f32 v134, v180, v133, v85
	v_med3_f32 v132, v133, v130, v85
	v_med3_f32 v130, v130, v128, v85
	v_med3_f32 v128, v128, v127, v85
	v_med3_f32 v126, v127, v125, v85
	v_med3_f32 v124, v125, v123, v85
	v_med3_f32 v122, v123, v121, v85
	v_med3_f32 v120, v121, v119, v85
	v_med3_f32 v117, v119, v116, v85
	v_med3_f32 v114, v116, v113, v85
	v_med3_f32 v111, v113, v110, v85
	v_med3_f32 v108, v110, v107, v85
	v_med3_f32 v105, v107, v104, v85
	v_med3_f32 v102, v104, v101, v85
	v_med3_f32 v0, v101, v0, v85
	v_max_f32_e32 v189, v188, v97
	v_add_f32_e32 v97, v21, v32
	v_med3_f32 v135, v181, v134, v86
	v_med3_f32 v133, v134, v132, v86
	v_med3_f32 v127, v128, v126, v86
	v_med3_f32 v125, v126, v124, v86
	v_med3_f32 v123, v124, v122, v86
	v_med3_f32 v121, v122, v120, v86
	v_med3_f32 v118, v120, v117, v86
	v_med3_f32 v115, v117, v114, v86
	v_med3_f32 v112, v114, v111, v86
	v_med3_f32 v109, v111, v108, v86
	v_med3_f32 v106, v108, v105, v86
	v_med3_f32 v103, v105, v102, v86
	v_med3_f32 v0, v102, v0, v86
	v_and_b32_e32 v97, 0xffffff00, v97
	v_med3_f32 v136, v182, v135, v87
	v_med3_f32 v134, v135, v133, v87
	v_med3_f32 v126, v127, v125, v87
	v_med3_f32 v124, v125, v123, v87
	v_med3_f32 v122, v123, v121, v87
	v_med3_f32 v119, v121, v118, v87
	v_med3_f32 v116, v118, v115, v87
	v_med3_f32 v113, v115, v112, v87
	v_med3_f32 v110, v112, v109, v87
	v_med3_f32 v107, v109, v106, v87
	v_med3_f32 v104, v106, v103, v87
	v_med3_f32 v0, v103, v0, v87
	v_or_b32_e32 v97, 0xd0, v97
	v_med3_f32 v137, v183, v136, v88
	v_med3_f32 v135, v136, v134, v88
	v_med3_f32 v131, v132, v130, v86
	v_med3_f32 v125, v126, v124, v88
	v_med3_f32 v123, v124, v122, v88
	v_med3_f32 v120, v122, v119, v88
	v_med3_f32 v117, v119, v116, v88
	v_med3_f32 v114, v116, v113, v88
	v_med3_f32 v111, v113, v110, v88
	v_med3_f32 v108, v110, v107, v88
	v_med3_f32 v105, v107, v104, v88
	v_med3_f32 v0, v104, v0, v88
	v_max_f32_e32 v99, v97, v97
	v_med3_f32 v138, v184, v137, v89
	v_med3_f32 v136, v137, v135, v89
	v_med3_f32 v132, v133, v131, v87
	v_med3_f32 v124, v125, v123, v89
	v_med3_f32 v121, v123, v120, v89
	v_med3_f32 v118, v120, v117, v89
	v_med3_f32 v115, v117, v114, v89
	v_med3_f32 v112, v114, v111, v89
	v_med3_f32 v109, v111, v108, v89
	v_med3_f32 v106, v108, v105, v89
	v_med3_f32 v0, v105, v0, v89
	v_max_f32_e32 v190, v189, v99
	v_add_f32_e32 v99, v28, v32
	v_med3_f32 v139, v185, v138, v90
	v_med3_f32 v137, v138, v136, v90
	v_med3_f32 v133, v134, v132, v88
	v_med3_f32 v122, v124, v121, v90
	v_med3_f32 v119, v121, v118, v90
	v_med3_f32 v116, v118, v115, v90
	v_med3_f32 v113, v115, v112, v90
	v_med3_f32 v110, v112, v109, v90
	v_med3_f32 v107, v109, v106, v90
	v_med3_f32 v0, v106, v0, v90
	v_and_b32_e32 v99, 0xffffff00, v99
	v_add_f32_e32 v48, v50, v32
	v_med3_f32 v140, v186, v139, v91
	v_med3_f32 v138, v139, v137, v91
	v_med3_f32 v134, v135, v133, v89
	v_med3_f32 v120, v122, v119, v91
	v_med3_f32 v117, v119, v116, v91
	v_med3_f32 v114, v116, v113, v91
	v_med3_f32 v111, v113, v110, v91
	v_med3_f32 v108, v110, v107, v91
	v_med3_f32 v0, v107, v0, v91
	v_or_b32_e32 v99, 0xe0, v99
	v_and_b32_e32 v48, 0xffffff00, v48
	v_med3_f32 v141, v187, v140, v92
	v_med3_f32 v139, v140, v138, v92
	v_med3_f32 v135, v136, v134, v90
	v_med3_f32 v118, v120, v117, v92
	v_med3_f32 v115, v117, v114, v92
	v_med3_f32 v112, v114, v111, v92
	v_med3_f32 v109, v111, v108, v92
	v_med3_f32 v0, v108, v0, v92
	v_max_f32_e32 v191, v99, v99
	v_or_b32_e32 v58, 0xf0, v48
	v_med3_f32 v142, v188, v141, v94
	v_med3_f32 v140, v141, v139, v94
	v_med3_f32 v136, v137, v135, v91
	v_med3_f32 v116, v118, v115, v94
	v_med3_f32 v113, v115, v112, v94
	v_med3_f32 v110, v112, v109, v94
	v_med3_f32 v0, v109, v0, v94
	v_max_f32_e32 v191, v190, v191
	v_max_f32_e32 v48, v58, v58
	v_med3_f32 v143, v189, v142, v97
	v_med3_f32 v141, v142, v140, v97
	v_med3_f32 v137, v138, v136, v92
	v_med3_f32 v129, v130, v128, v86
	v_med3_f32 v114, v116, v113, v97
	v_med3_f32 v111, v113, v110, v97
	v_med3_f32 v0, v110, v0, v97
	v_max_f32_e32 v48, v191, v48
	v_med3_f32 v144, v190, v143, v99
	v_med3_f32 v142, v143, v141, v99
	v_med3_f32 v138, v139, v137, v94
	v_med3_f32 v130, v131, v129, v87
	v_med3_f32 v112, v114, v111, v99
	v_med3_f32 v0, v111, v0, v99
	v_med3_f32 v49, v191, v144, v58
	v_med3_f32 v51, v144, v142, v58
	v_med3_f32 v139, v140, v138, v97
	v_med3_f32 v131, v132, v130, v88
	v_med3_f32 v128, v129, v127, v87
	v_med3_f32 v53, v112, v0, v58
	v_sub_f32_e32 v0, v48, v48
	v_med3_f32 v140, v141, v139, v99
	v_med3_f32 v132, v133, v131, v89
	v_med3_f32 v129, v130, v128, v88
	v_med3_f32 v127, v128, v126, v88
	v_mul_f32_e32 v0, 0x3fb8aa3b, v0
	v_sub_f32_e32 v1, v49, v48
	v_sub_f32_e32 v2, v51, v48
	v_med3_f32 v54, v142, v140, v58
	v_med3_f32 v133, v134, v132, v90
	v_med3_f32 v130, v131, v129, v89
	v_med3_f32 v128, v129, v127, v89
	v_exp_f32_e32 v0, v0
	v_mul_f32_e32 v1, 0x3fb8aa3b, v1
	v_mul_f32_e32 v2, 0x3fb8aa3b, v2
	v_med3_f32 v134, v135, v133, v91
	v_med3_f32 v131, v132, v130, v90
	v_med3_f32 v129, v130, v128, v90
	v_exp_f32_e32 v1, v1
	v_exp_f32_e32 v4, v2
	v_sub_f32_e32 v2, v54, v48
	v_med3_f32 v135, v136, v134, v92
	v_med3_f32 v132, v133, v131, v91
	v_med3_f32 v130, v131, v129, v91
	v_med3_f32 v126, v127, v125, v89
	v_mul_f32_e32 v2, 0x3fb8aa3b, v2
	v_med3_f32 v136, v137, v135, v94
	v_med3_f32 v133, v134, v132, v92
	v_med3_f32 v131, v132, v130, v92
	v_med3_f32 v127, v128, v126, v90
	v_exp_f32_e32 v5, v2
	v_lshlrev_b32_e32 v26, 8, v26
	v_lshlrev_b32_e32 v25, 8, v25
	v_med3_f32 v137, v138, v136, v97
	v_med3_f32 v134, v135, v133, v94
	v_med3_f32 v132, v133, v131, v94
	v_med3_f32 v128, v129, v127, v91
	v_add_f32_e32 v2, 0, v0
	v_and_b32_e32 v31, 0x7f, v31
	v_and_b32_e32 v30, 0x7f, v30
	v_and_b32_e32 v26, 0x7f00, v26
	v_and_b32_e32 v25, 0x7f00, v25
	v_lshlrev_b32_e32 v29, 16, v29
	v_lshlrev_b32_e32 v27, 16, v27
	v_med3_f32 v138, v139, v137, v99
	v_med3_f32 v135, v136, v134, v97
	v_med3_f32 v133, v134, v132, v97
	v_med3_f32 v129, v130, v128, v92
	v_add_f32_e32 v2, v1, v2
	v_or_b32_e32 v26, v26, v31
	v_or_b32_e32 v25, v25, v30
	v_and_b32_e32 v29, 0x7f0000, v29
	v_and_b32_e32 v27, 0x7f0000, v27
	v_lshlrev_b32_e32 v19, 24, v19
	v_lshlrev_b32_e32 v20, 24, v20
	v_med3_f32 v55, v140, v138, v58
	v_med3_f32 v136, v137, v135, v99
	v_med3_f32 v134, v135, v133, v99
	v_med3_f32 v130, v131, v129, v94
	v_add_f32_e32 v2, v4, v2
	v_or_b32_e32 v26, v26, v29
	v_or_b32_e32 v25, v25, v27
	v_and_b32_e32 v19, 0x7f000000, v19
	v_and_b32_e32 v20, 0x7f000000, v20
	v_lshlrev_b32_e32 v18, 8, v18
	v_med3_f32 v59, v138, v136, v58
	v_med3_f32 v60, v136, v134, v58
	v_med3_f32 v131, v132, v130, v97
	v_add_f32_e32 v6, v5, v2
	v_sub_f32_e32 v2, v55, v48
	v_or_b32_e32 v27, v26, v19
	v_or_b32_e32 v26, v25, v20
	v_and_b32_e32 v20, 0x7f, v23
	v_lshlrev_b32_e32 v21, 8, v21
	v_and_b32_e32 v18, 0x7f00, v18
	v_med3_f32 v132, v133, v131, v99
	v_mul_f32_e32 v2, 0x3fb8aa3b, v2
	v_sub_f32_e32 v3, v59, v48
	v_sub_f32_e32 v7, v60, v48
	v_and_b32_e32 v19, 0x7f, v24
	v_and_b32_e32 v21, 0x7f00, v21
	v_or_b32_e32 v18, v18, v20
	v_lshlrev_b32_e32 v20, 16, v28
	v_med3_f32 v61, v134, v132, v58
	v_med3_f32 v125, v126, v124, v90
	v_exp_f32_e32 v2, v2
	v_mul_f32_e32 v3, 0x3fb8aa3b, v3
	v_mul_f32_e32 v7, 0x3fb8aa3b, v7
	v_or_b32_e32 v19, v21, v19
	v_and_b32_e32 v20, 0x7f0000, v20
	v_med3_f32 v126, v127, v125, v91
	v_exp_f32_e32 v3, v3
	v_exp_f32_e32 v8, v7
	v_sub_f32_e32 v7, v61, v48
	v_lshlrev_b32_e32 v21, 16, v22
	v_or_b32_e32 v19, v19, v20
	v_lshlrev_b32_e32 v20, 24, v50
	v_med3_f32 v127, v128, v126, v92
	v_med3_f32 v123, v125, v122, v91
	v_mul_f32_e32 v7, 0x3fb8aa3b, v7
	v_and_b32_e32 v21, 0x7f0000, v21
	v_lshlrev_b32_e32 v17, 24, v17
	v_and_b32_e32 v20, 0x7f000000, v20
	v_med3_f32 v128, v129, v127, v94
	v_med3_f32 v124, v126, v123, v92
	v_med3_f32 v121, v123, v120, v92
	v_exp_f32_e32 v9, v7
	v_or_b32_e32 v18, v18, v21
	v_and_b32_e32 v17, 0x7f000000, v17
	v_or_b32_e32 v29, v19, v20
	v_lshlrev_b32_e32 v19, 8, v37
	v_lshlrev_b32_e32 v20, 8, v33
	v_med3_f32 v129, v130, v128, v97
	v_med3_f32 v125, v127, v124, v94
	v_med3_f32 v122, v124, v121, v94
	v_add_f32_e32 v6, v2, v6
	v_or_b32_e32 v28, v18, v17
	v_and_b32_e32 v17, 0x7f, v36
	v_and_b32_e32 v18, 0x7f, v32
	v_and_b32_e32 v19, 0x7f00, v19
	v_and_b32_e32 v20, 0x7f00, v20
	v_med3_f32 v130, v131, v129, v99
	v_med3_f32 v126, v128, v125, v97
	v_med3_f32 v123, v125, v122, v97
	v_add_f32_e32 v6, v3, v6
	v_or_b32_e32 v17, v19, v17
	v_or_b32_e32 v18, v20, v18
	v_lshlrev_b32_e32 v19, 16, v38
	v_lshlrev_b32_e32 v20, 16, v34
	v_med3_f32 v62, v132, v130, v58
	v_med3_f32 v127, v129, v126, v99
	v_med3_f32 v124, v126, v123, v99
	v_med3_f32 v119, v121, v118, v94
	v_add_f32_e32 v6, v8, v6
	v_and_b32_e32 v19, 0x7f0000, v19
	v_and_b32_e32 v20, 0x7f0000, v20
	v_med3_f32 v128, v130, v127, v58
	v_med3_f32 v125, v127, v124, v58
	v_med3_f32 v120, v122, v119, v97
	v_add_f32_e32 v10, v9, v6
	v_sub_f32_e32 v6, v62, v48
	v_or_b32_e32 v17, v17, v19
	v_or_b32_e32 v18, v18, v20
	v_lshlrev_b32_e32 v19, 24, v39
	v_lshlrev_b32_e32 v20, 24, v35
	v_med3_f32 v121, v123, v120, v99
	v_mul_f32_e32 v6, 0x3fb8aa3b, v6
	v_sub_f32_e32 v7, v128, v48
	v_sub_f32_e32 v11, v125, v48
	v_and_b32_e32 v19, 0x7f000000, v19
	v_and_b32_e32 v20, 0x7f000000, v20
	v_lshlrev_b32_e32 v21, 8, v45
	v_lshlrev_b32_e32 v22, 8, v41
	v_med3_f32 v122, v124, v121, v58
	v_exp_f32_e32 v6, v6
	v_mul_f32_e32 v7, 0x3fb8aa3b, v7
	v_mul_f32_e32 v11, 0x3fb8aa3b, v11
	v_or_b32_e32 v19, v17, v19
	v_or_b32_e32 v18, v18, v20
	v_and_b32_e32 v17, 0x7f, v44
	v_and_b32_e32 v20, 0x7f, v40
	v_and_b32_e32 v21, 0x7f00, v21
	v_and_b32_e32 v22, 0x7f00, v22
	v_exp_f32_e32 v7, v7
	v_exp_f32_e32 v12, v11
	v_sub_f32_e32 v11, v122, v48
	v_or_b32_e32 v17, v21, v17
	v_or_b32_e32 v20, v22, v20
	v_lshlrev_b32_e32 v21, 16, v46
	v_lshlrev_b32_e32 v22, 16, v42
	v_mul_f32_e32 v11, 0x3fb8aa3b, v11
	v_and_b32_e32 v21, 0x7f0000, v21
	v_and_b32_e32 v22, 0x7f0000, v22
	v_exp_f32_e32 v13, v11
	v_or_b32_e32 v17, v17, v21
	v_or_b32_e32 v20, v20, v22
	v_lshlrev_b32_e32 v21, 24, v47
	v_lshlrev_b32_e32 v22, 24, v43
	v_med3_f32 v117, v119, v116, v97
	v_add_f32_e32 v10, v6, v10
	v_and_b32_e32 v21, 0x7f000000, v21
	v_and_b32_e32 v22, 0x7f000000, v22
	v_med3_f32 v118, v120, v117, v99
	v_add_f32_e32 v10, v7, v10
	v_lshl_add_u32 v57, v57, 5, v162
	v_or_b32_e32 v21, v17, v21
	v_or_b32_e32 v20, v20, v22
	v_med3_f32 v119, v121, v118, v58
	v_med3_f32 v115, v117, v114, v99
	v_add_f32_e32 v10, v12, v10
	ds_write_b128 v57, v[18:21] offset:16
	v_lshrrev_b32_e32 v17, 4, v48
	v_lshrrev_b32_e32 v19, 4, v49
	v_lshrrev_b32_e32 v21, 4, v51
	v_lshrrev_b32_e32 v23, 4, v54
	v_med3_f32 v116, v118, v115, v58
	v_add_f32_e32 v16, v13, v10
	v_sub_f32_e32 v10, v119, v48
	v_and_or_b32 v17, v17, 15, v57
	v_and_or_b32 v18, v48, 15, v57
	v_and_or_b32 v19, v19, 15, v57
	v_and_or_b32 v20, v49, 15, v57
	v_and_or_b32 v21, v21, 15, v57
	v_and_or_b32 v22, v51, 15, v57
	v_and_or_b32 v23, v23, 15, v57
	v_and_or_b32 v24, v54, 15, v57
	v_med3_f32 v113, v115, v112, v58
	v_mul_f32_e32 v10, 0x3fb8aa3b, v10
	v_sub_f32_e32 v11, v116, v48
	ds_write_b128 v57, v[26:29]
	s_waitcnt lgkmcnt(0)
	ds_read_u8 v17, v17
	ds_read_u8 v18, v18 offset:16
	ds_read_u8 v19, v19
	ds_read_u8 v20, v20 offset:16
	ds_read_u8 v21, v21
	ds_read_u8 v22, v22 offset:16
	ds_read_u8 v23, v23
	ds_read_u8 v24, v24 offset:16
	v_exp_f32_e32 v10, v10
	v_mul_f32_e32 v11, 0x3fb8aa3b, v11
	v_sub_f32_e32 v14, v113, v48
	v_exp_f32_e32 v11, v11
	v_mul_f32_e32 v14, 0x3fb8aa3b, v14
	v_sub_f32_e32 v15, v53, v48
	s_waitcnt lgkmcnt(6)
	v_lshl_or_b32 v18, v17, 7, v18
	v_lshrrev_b32_e32 v17, 4, v55
	v_lshrrev_b32_e32 v26, 4, v60
	v_lshrrev_b32_e32 v28, 4, v61
	v_exp_f32_e32 v14, v14
	v_mul_f32_e32 v15, 0x3fb8aa3b, v15
	s_waitcnt lgkmcnt(4)
	v_lshl_or_b32 v19, v19, 7, v20
	s_waitcnt lgkmcnt(2)
	v_lshl_or_b32 v20, v21, 7, v22
	v_and_or_b32 v17, v17, 15, v57
	v_lshrrev_b32_e32 v22, 4, v59
	v_and_or_b32 v25, v59, 15, v57
	v_and_or_b32 v26, v26, 15, v57
	v_and_or_b32 v27, v60, 15, v57
	v_and_or_b32 v28, v28, 15, v57
	v_and_or_b32 v29, v61, 15, v57
	v_exp_f32_e32 v15, v15
	v_and_or_b32 v21, v55, 15, v57
	v_and_or_b32 v22, v22, 15, v57
	ds_read_u8 v17, v17
	ds_read_u8 v30, v21 offset:16
	ds_read_u8 v31, v22
	ds_read_u8 v25, v25 offset:16
	ds_read_u8 v26, v26
	ds_read_u8 v27, v27 offset:16
	ds_read_u8 v28, v28
	ds_read_u8 v29, v29 offset:16
	v_add_f32_e32 v16, v10, v16
	v_add_f32_e32 v16, v11, v16
	v_add_f32_e32 v16, v14, v16
	v_add_f32_e32 v16, v15, v16
	v_div_scale_f32 v58, s[28:29], v16, v16, 1.0
	s_waitcnt lgkmcnt(8)
	v_lshl_or_b32 v21, v23, 7, v24
	s_waitcnt lgkmcnt(6)
	v_lshl_or_b32 v22, v17, 7, v30
	s_waitcnt lgkmcnt(4)
	v_lshl_or_b32 v23, v31, 7, v25
	s_waitcnt lgkmcnt(2)
	v_lshl_or_b32 v24, v26, 7, v27
	s_waitcnt lgkmcnt(0)
	v_lshl_or_b32 v25, v28, 7, v29
	v_lshrrev_b32_e32 v17, 4, v62
	v_lshrrev_b32_e32 v27, 4, v128
	v_lshrrev_b32_e32 v29, 4, v125
	v_lshrrev_b32_e32 v31, 4, v122
	v_rcp_f32_e32 v63, v58
	v_and_or_b32 v17, v17, 15, v57
	v_and_or_b32 v26, v62, 15, v57
	v_and_or_b32 v27, v27, 15, v57
	v_and_or_b32 v28, v128, 15, v57
	v_and_or_b32 v29, v29, 15, v57
	v_and_or_b32 v30, v125, 15, v57
	v_and_or_b32 v31, v31, 15, v57
	v_and_or_b32 v32, v122, 15, v57
	ds_read_u8 v17, v17
	ds_read_u8 v26, v26 offset:16
	ds_read_u8 v27, v27
	ds_read_u8 v28, v28 offset:16
	ds_read_u8 v29, v29
	ds_read_u8 v30, v30 offset:16
	ds_read_u8 v31, v31
	ds_read_u8 v32, v32 offset:16
	s_waitcnt lgkmcnt(6)
	v_lshl_or_b32 v26, v17, 7, v26
	v_lshrrev_b32_e32 v17, 4, v119
	v_lshrrev_b32_e32 v34, 4, v113
	v_lshrrev_b32_e32 v36, 4, v53
	v_add_u32_e32 v52, s18, v56
	v_fma_f32 v56, -v58, v63, 1.0
	s_waitcnt lgkmcnt(4)
	v_lshl_or_b32 v27, v27, 7, v28
	s_waitcnt lgkmcnt(2)
	v_lshl_or_b32 v28, v29, 7, v30
	v_and_or_b32 v17, v17, 15, v57
	v_lshrrev_b32_e32 v30, 4, v116
	v_and_or_b32 v33, v116, 15, v57
	v_and_or_b32 v34, v34, 15, v57
	v_and_or_b32 v35, v113, 15, v57
	v_and_or_b32 v36, v36, 15, v57
	v_and_or_b32 v37, v53, 15, v57
	v_fmac_f32_e32 v63, v56, v63
	v_div_scale_f32 v56, vcc, 1.0, v16, 1.0
	v_and_or_b32 v29, v119, 15, v57
	v_and_or_b32 v30, v30, 15, v57
	ds_read_u8 v17, v17
	ds_read_u8 v38, v29 offset:16
	ds_read_u8 v39, v30
	ds_read_u8 v33, v33 offset:16
	ds_read_u8 v34, v34
	ds_read_u8 v35, v35 offset:16
	ds_read_u8 v36, v36
	ds_read_u8 v37, v37 offset:16
	v_mul_f32_e32 v64, v56, v63
	v_or_b32_e32 v52, v52, v163
	v_fma_f32 v65, -v58, v64, v56
	v_fmac_f32_e32 v64, v65, v63
	v_ashrrev_i32_e32 v53, 31, v52
	s_lshl_b32 s18, s27, 4
	v_fma_f32 v56, -v58, v64, v56
	s_waitcnt lgkmcnt(8)
	v_lshl_or_b32 v29, v31, 7, v32
	s_waitcnt lgkmcnt(2)
	v_lshl_or_b32 v32, v34, 7, v35
	v_lshlrev_b64 v[34:35], 9, v[52:53]
	s_ashr_i32 s19, s18, 31
	v_div_fmas_f32 v56, v56, v63, v64
	v_lshl_or_b32 v31, v39, 7, v33
	s_waitcnt lgkmcnt(0)
	v_lshl_or_b32 v33, v36, 7, v37
	v_lshl_add_u64 v[36:37], s[4:5], 0, v[34:35]
	s_lshl_b64 s[18:19], s[18:19], 2
	v_div_fixup_f32 v16, v56, v16, 1.0
	v_lshl_add_u64 v[36:37], v[36:37], 0, s[18:19]
	v_lshl_add_u64 v[34:35], s[6:7], 0, v[34:35]
	v_lshl_add_u64 v[34:35], v[34:35], 0, s[18:19]
	global_store_dwordx4 v[36:37], v[18:21], off
	v_lshl_or_b32 v30, v17, 7, v38
	s_nop 0
	v_pk_mul_f32 v[18:19], v[0:1], v[16:17] op_sel_hi:[1,0]
	v_pk_mul_f32 v[20:21], v[4:5], v[16:17] op_sel_hi:[1,0]
	v_pk_mul_f32 v[0:1], v[2:3], v[16:17] op_sel_hi:[1,0]
	v_pk_mul_f32 v[2:3], v[8:9], v[16:17] op_sel_hi:[1,0]
	global_store_dwordx4 v[34:35], v[18:21], off
	global_store_dwordx4 v[36:37], v[22:25], off offset:16
	global_store_dwordx4 v[34:35], v[0:3], off offset:16
	global_store_dwordx4 v[36:37], v[26:29], off offset:32
	s_nop 0
	v_pk_mul_f32 v[0:1], v[6:7], v[16:17] op_sel_hi:[1,0]
	v_pk_mul_f32 v[2:3], v[12:13], v[16:17] op_sel_hi:[1,0]
	global_store_dwordx4 v[34:35], v[0:3], off offset:32
	global_store_dwordx4 v[36:37], v[30:33], off offset:48
	s_nop 0
	v_pk_mul_f32 v[0:1], v[10:11], v[16:17] op_sel_hi:[1,0]
	v_pk_mul_f32 v[2:3], v[14:15], v[16:17] op_sel_hi:[1,0]
	global_store_dwordx4 v[34:35], v[0:3], off offset:48
	s_branch .LBB0_1052
